# v21 + EpiResid<false> GEMMs (FFN-down x2, w_out): first row group's 4 residual loads issued from the K loop into GEMM-dead VGPRs; epilogue keeps row groups 1-3 in flight from its first instruction
# baseline (speedup 1.0000x reference)
;     __device__ __forceinline__ void operator()(const f32x4 (&acc)[2][2][4][2], const Unit& u, int wr, int wc, int fr, int fq) const {
;     ...
;                     const size_t off = (size_t)row * DM + col0 + bj * HALF;
;                     const u32x4 hh = *(const u32x4*)(HI + off), ll = *(const u32x4*)(LO + off);
.LBB0_241:
	s_cmp_eq_u32 s34, 36
	s_cbranch_scc0 .Lpre_f1d_skip
	s_mov_b64 s[100:101], s[38:39]
	v_readlane_b32 s98, v250, 49
	v_readlane_b32 s99, v250, 50
	v_lshl_add_u32 v243, s31, 8, v160
	v_lshl_or_b32 v246, s4, 8, v162
	v_lshl_add_u32 v243, v243, 10, v246
	v_lshlrev_b32_e32 v243, 1, v243
	s_nop 1
	global_load_dwordx4 v[226:229], v243, s[100:101]
	global_load_dwordx4 v[230:233], v243, s[98:99]
	global_load_dwordx4 v[234:237], v243, s[100:101] offset:256
	global_load_dwordx4 v[242:245], v243, s[98:99] offset:256

; __device__ __forceinline__ float bflo(unsigned u) { return __uint_as_float(u << 16); }
;     __device__ __forceinline__ void operator()(const f32x4 (&acc)[2][2][4][2], const Unit& u, int wr, int wc, int fr, int fq) const {
;     ...
;                 const int row = row0 + ai * HALF + m * 16;
;                 float rs = 0.f; if (GATED) rs = rsqrtf(row_ssq(ssq_in, 16, 4, row, fq) * (1.f / 1024.f) + EPS);
;                 float sq = 0.f;
; #pragma unroll
;                 for (int bj = 0; bj < 2; ++bj) {
;                     const size_t off = (size_t)row * DM + col0 + bj * HALF;
;                     const u32x4 hh = *(const u32x4*)(HI + off), ll = *(const u32x4*)(LO + off);
;                     float hv[8] = {bflo(hh.x) + bflo(ll.x), bfhi(hh.x) + bfhi(ll.x), bflo(hh.y) + bflo(ll.y), bfhi(hh.y) + bfhi(ll.y),
;                                    bflo(hh.z) + bflo(ll.z), bfhi(hh.z) + bfhi(ll.z), bflo(hh.w) + bflo(ll.w), bfhi(hh.w) + bfhi(ll.w)};
;                     float av[8] = {acc[ai][bj][m][0][0], acc[ai][bj][m][0][1], acc[ai][bj][m][0][2], acc[ai][bj][m][0][3], acc[ai][bj][m][1][0], acc[ai][bj][m][1][1], acc[ai][bj][m][1][2], acc[ai][bj][m][1][3]};
;                     if (GATED) { const u32x4 pp = *(const u32x4*)(PP + off);
;                         const float pv[8] = {bflo(pp.x), bfhi(pp.x), bflo(pp.y), bfhi(pp.y), bflo(pp.z), bfhi(pp.z), bflo(pp.w), bfhi(pp.w)};
; #pragma unroll
;                         for (int e = 0; e < 8; ++e) av[e] = fast_sigmoid(av[e] * rs) * pv[e]; }
;                     else {
; #pragma unroll
;                         for (int e = 0; e < 8; ++e) av[e] *= alpha; }
;                     float lo[8];
; #pragma unroll
;                     for (int e = 0; e < 8; ++e) { hv[e] += av[e]; sq += hv[e] * hv[e]; }
;                     u32x4 wh; wh.x = pk2(hv[0], hv[1]); wh.y = pk2(hv[2], hv[3]); wh.z = pk2(hv[4], hv[5]); wh.w = pk2(hv[6], hv[7]);
;                     lo[0] = hv[0] - bflo(wh.x); lo[1] = hv[1] - bfhi(wh.x); lo[2] = hv[2] - bflo(wh.y); lo[3] = hv[3] - bfhi(wh.y);
;                     lo[4] = hv[4] - bflo(wh.z); lo[5] = hv[5] - bfhi(wh.z); lo[6] = hv[6] - bflo(wh.w); lo[7] = hv[7] - bfhi(wh.w);
;                     u32x4 wl; wl.x = pk2(lo[0], lo[1]); wl.y = pk2(lo[2], lo[3]); wl.z = pk2(lo[4], lo[5]); wl.w = pk2(lo[6], lo[7]);
;                     *(u32x4*)(HO + off) = wh; *(u32x4*)(LO + off) = wl;
.LBB0_244:
	v_and_b32_e32 v158, 64, v241
	v_xor_b32_e32 v214, 16, v241
	v_add_u32_e32 v158, 64, v158
	v_cmp_lt_i32_e32 vcc, v214, v158
	v_lshl_add_u32 v156, s31, 8, v160
	v_lshl_or_b32 v157, s4, 8, v162
	v_cndmask_b32_e32 v214, v241, v214, vcc
	v_lshlrev_b32_e32 v214, 2, v214
	v_xor_b32_e32 v215, 32, v241
	v_cmp_lt_i32_e32 vcc, v215, v158
	v_readlane_b32 s6, v250, 49
	v_readlane_b32 s7, v250, 50
	v_readlane_b32 s10, v253, 35
	v_readlane_b32 s11, v253, 36
	s_nop 1
	v_cndmask_b32_e32 v215, v241, v215, vcc
	v_lshlrev_b32_e32 v215, 2, v215
	v_lshl_add_u32 v213, v156, 10, v157
	v_lshlrev_b32_e32 v213, 1, v213
	s_lshl_b32 s40, s4, 4
	s_lshl_b32 s52, s25, 2
	s_add_i32 s40, s40, s52
	v_lshlrev_b32_e32 v216, 6, v156
	v_add_u32_e32 v216, s40, v216
	v_add_u32_e32 v217, 0x2000, v216
	s_nop 1
	v_add_u32_e32 v211, 0x8000, v213
	global_load_dwordx4 v[164:167], v211, s[38:39]
	global_load_dwordx4 v[168:171], v211, s[6:7]
	global_load_dwordx4 v[172:175], v211, s[38:39] offset:256
	global_load_dwordx4 v[176:179], v211, s[6:7] offset:256
	v_add_u32_e32 v212, 0x10000, v213
	global_load_dwordx4 v[180:183], v212, s[38:39]
	global_load_dwordx4 v[184:187], v212, s[6:7]
	global_load_dwordx4 v[188:191], v212, s[38:39] offset:256
	global_load_dwordx4 v[192:195], v212, s[6:7] offset:256
	v_add_u32_e32 v210, 0x18000, v213
	global_load_dwordx4 v[140:143], v210, s[38:39]
	global_load_dwordx4 v[144:147], v210, s[6:7]
	global_load_dwordx4 v[148:151], v210, s[38:39] offset:256
	global_load_dwordx4 v[152:155], v210, s[6:7] offset:256
	s_waitcnt vmcnt(12)
	v_lshlrev_b32_e32 v156, 16, v226
	v_and_b32_e32 v157, 0xffff0000, v226
	v_lshlrev_b32_e32 v158, 16, v230
	v_and_b32_e32 v159, 0xffff0000, v230
	v_pk_add_f32 v[156:157], v[156:157], v[158:159]
	v_pk_fma_f32 v[156:157], v[126:127], 0.5, v[156:157] op_sel_hi:[1,0,1]
	v_cvt_pk_bf16_f32 v226, v156, v157
	v_pk_mul_f32 v[198:199], v[156:157], v[156:157]
	v_lshlrev_b32_e32 v158, 16, v226
	v_and_b32_e32 v159, 0xffff0000, v226
	v_pk_add_f32 v[196:197], v[156:157], v[158:159] neg_lo:[0,1] neg_hi:[0,1]
	v_cvt_pk_bf16_f32 v230, v196, v197
	v_lshlrev_b32_e32 v156, 16, v227
	v_and_b32_e32 v157, 0xffff0000, v227
	v_lshlrev_b32_e32 v158, 16, v231
	v_and_b32_e32 v159, 0xffff0000, v231
	v_pk_add_f32 v[156:157], v[156:157], v[158:159]
	v_pk_fma_f32 v[156:157], v[128:129], 0.5, v[156:157] op_sel_hi:[1,0,1]
	v_cvt_pk_bf16_f32 v227, v156, v157
	v_pk_fma_f32 v[198:199], v[156:157], v[156:157], v[198:199]
	v_lshlrev_b32_e32 v158, 16, v227
	v_and_b32_e32 v159, 0xffff0000, v227
	v_pk_add_f32 v[196:197], v[156:157], v[158:159] neg_lo:[0,1] neg_hi:[0,1]
	v_cvt_pk_bf16_f32 v231, v196, v197
	v_lshlrev_b32_e32 v156, 16, v228
	v_and_b32_e32 v157, 0xffff0000, v228
	v_lshlrev_b32_e32 v158, 16, v232
	v_and_b32_e32 v159, 0xffff0000, v232
	v_pk_add_f32 v[156:157], v[156:157], v[158:159]
	v_pk_fma_f32 v[156:157], v[122:123], 0.5, v[156:157] op_sel_hi:[1,0,1]
	v_cvt_pk_bf16_f32 v228, v156, v157
	v_pk_fma_f32 v[198:199], v[156:157], v[156:157], v[198:199]
	v_lshlrev_b32_e32 v158, 16, v228
	v_and_b32_e32 v159, 0xffff0000, v228
	v_pk_add_f32 v[196:197], v[156:157], v[158:159] neg_lo:[0,1] neg_hi:[0,1]
	v_cvt_pk_bf16_f32 v232, v196, v197
	v_lshlrev_b32_e32 v156, 16, v229
	v_and_b32_e32 v157, 0xffff0000, v229
	v_lshlrev_b32_e32 v158, 16, v233
	v_and_b32_e32 v159, 0xffff0000, v233
	v_pk_add_f32 v[156:157], v[156:157], v[158:159]
	v_pk_fma_f32 v[156:157], v[124:125], 0.5, v[156:157] op_sel_hi:[1,0,1]
	v_cvt_pk_bf16_f32 v229, v156, v157
	v_pk_fma_f32 v[198:199], v[156:157], v[156:157], v[198:199]
	v_lshlrev_b32_e32 v158, 16, v229
	v_and_b32_e32 v159, 0xffff0000, v229
	v_pk_add_f32 v[196:197], v[156:157], v[158:159] neg_lo:[0,1] neg_hi:[0,1]
	v_cvt_pk_bf16_f32 v233, v196, v197
	global_store_dwordx4 v213, v[226:229], s[10:11]
	global_store_dwordx4 v213, v[230:233], s[6:7]
	v_lshlrev_b32_e32 v156, 16, v234
	v_and_b32_e32 v157, 0xffff0000, v234
	v_lshlrev_b32_e32 v158, 16, v242
	v_and_b32_e32 v159, 0xffff0000, v242
	v_pk_add_f32 v[156:157], v[156:157], v[158:159]
	v_pk_fma_f32 v[156:157], v[118:119], 0.5, v[156:157] op_sel_hi:[1,0,1]
	v_cvt_pk_bf16_f32 v234, v156, v157
	v_pk_fma_f32 v[198:199], v[156:157], v[156:157], v[198:199]
	v_lshlrev_b32_e32 v158, 16, v234
	v_and_b32_e32 v159, 0xffff0000, v234
	v_pk_add_f32 v[196:197], v[156:157], v[158:159] neg_lo:[0,1] neg_hi:[0,1]
	v_cvt_pk_bf16_f32 v242, v196, v197
	v_lshlrev_b32_e32 v156, 16, v235
	v_and_b32_e32 v157, 0xffff0000, v235
	v_lshlrev_b32_e32 v158, 16, v243
	v_and_b32_e32 v159, 0xffff0000, v243
	v_pk_add_f32 v[156:157], v[156:157], v[158:159]
	v_pk_fma_f32 v[156:157], v[120:121], 0.5, v[156:157] op_sel_hi:[1,0,1]
	v_cvt_pk_bf16_f32 v235, v156, v157
	v_pk_fma_f32 v[198:199], v[156:157], v[156:157], v[198:199]
	v_lshlrev_b32_e32 v158, 16, v235
	v_and_b32_e32 v159, 0xffff0000, v235
	v_pk_add_f32 v[196:197], v[156:157], v[158:159] neg_lo:[0,1] neg_hi:[0,1]
	v_cvt_pk_bf16_f32 v243, v196, v197
	v_lshlrev_b32_e32 v156, 16, v236
	v_and_b32_e32 v157, 0xffff0000, v236
	v_lshlrev_b32_e32 v158, 16, v244
	v_and_b32_e32 v159, 0xffff0000, v244
	v_pk_add_f32 v[156:157], v[156:157], v[158:159]
	v_pk_fma_f32 v[156:157], v[114:115], 0.5, v[156:157] op_sel_hi:[1,0,1]
	v_cvt_pk_bf16_f32 v236, v156, v157
	v_pk_fma_f32 v[198:199], v[156:157], v[156:157], v[198:199]
	v_lshlrev_b32_e32 v158, 16, v236
	v_and_b32_e32 v159, 0xffff0000, v236
	v_pk_add_f32 v[196:197], v[156:157], v[158:159] neg_lo:[0,1] neg_hi:[0,1]
	v_cvt_pk_bf16_f32 v244, v196, v197
	v_lshlrev_b32_e32 v156, 16, v237
	v_and_b32_e32 v157, 0xffff0000, v237
	v_lshlrev_b32_e32 v158, 16, v245
	v_and_b32_e32 v159, 0xffff0000, v245
	v_pk_add_f32 v[156:157], v[156:157], v[158:159]
	v_pk_fma_f32 v[156:157], v[116:117], 0.5, v[156:157] op_sel_hi:[1,0,1]
	v_cvt_pk_bf16_f32 v237, v156, v157
	v_pk_fma_f32 v[198:199], v[156:157], v[156:157], v[198:199]
	v_lshlrev_b32_e32 v158, 16, v237
	v_and_b32_e32 v159, 0xffff0000, v237
	v_pk_add_f32 v[196:197], v[156:157], v[158:159] neg_lo:[0,1] neg_hi:[0,1]
	v_cvt_pk_bf16_f32 v245, v196, v197
	global_store_dwordx4 v213, v[234:237], s[10:11] offset:256
	global_store_dwordx4 v213, v[242:245], s[6:7] offset:256
	v_add_f32_e32 v200, v198, v199
	s_waitcnt vmcnt(14)
; __device__ __forceinline__ unsigned pk2(float lo, float hi) { f32x2_t v = {lo, hi}; bf16x2_t b = __builtin_convertvector(v, bf16x2_t); return __builtin_bit_cast(unsigned, b); }
; __device__ __forceinline__ float bflo(unsigned u) { return __uint_as_float(u << 16); }
;     __device__ __forceinline__ void operator()(const f32x4 (&acc)[2][2][4][2], const Unit& u, int wr, int wc, int fr, int fq) const {
;     ...
;                 for (int bj = 0; bj < 2; ++bj) {
;                     const size_t off = (size_t)row * DM + col0 + bj * HALF;
;                     const u32x4 hh = *(const u32x4*)(HI + off), ll = *(const u32x4*)(LO + off);
;                     float hv[8] = {bflo(hh.x) + bflo(ll.x), bfhi(hh.x) + bfhi(ll.x), bflo(hh.y) + bflo(ll.y), bfhi(hh.y) + bfhi(ll.y),
;                                    bflo(hh.z) + bflo(ll.z), bfhi(hh.z) + bfhi(ll.z), bflo(hh.w) + bflo(ll.w), bfhi(hh.w) + bfhi(ll.w)};
;                     float av[8] = {acc[ai][bj][m][0][0], acc[ai][bj][m][0][1], acc[ai][bj][m][0][2], acc[ai][bj][m][0][3], acc[ai][bj][m][1][0], acc[ai][bj][m][1][1], acc[ai][bj][m][1][2], acc[ai][bj][m][1][3]};
;                     if (GATED) { const u32x4 pp = *(const u32x4*)(PP + off);
;                         const float pv[8] = {bflo(pp.x), bfhi(pp.x), bflo(pp.y), bfhi(pp.y), bflo(pp.z), bfhi(pp.z), bflo(pp.w), bfhi(pp.w)};
; #pragma unroll
;                         for (int e = 0; e < 8; ++e) av[e] = fast_sigmoid(av[e] * rs) * pv[e]; }
;                     else {
; #pragma unroll
;                         for (int e = 0; e < 8; ++e) av[e] *= alpha; }
;                     float lo[8];
; #pragma unroll
;                     for (int e = 0; e < 8; ++e) { hv[e] += av[e]; sq += hv[e] * hv[e]; }
;                     u32x4 wh; wh.x = pk2(hv[0], hv[1]); wh.y = pk2(hv[2], hv[3]); wh.z = pk2(hv[4], hv[5]); wh.w = pk2(hv[6], hv[7]);
;                     lo[0] = hv[0] - bflo(wh.x); lo[1] = hv[1] - bfhi(wh.x); lo[2] = hv[2] - bflo(wh.y); lo[3] = hv[3] - bfhi(wh.y);
;                     lo[4] = hv[4] - bflo(wh.z); lo[5] = hv[5] - bfhi(wh.z); lo[6] = hv[6] - bflo(wh.w); lo[7] = hv[7] - bfhi(wh.w);
;                     u32x4 wl; wl.x = pk2(lo[0], lo[1]); wl.y = pk2(lo[2], lo[3]); wl.z = pk2(lo[4], lo[5]); wl.w = pk2(lo[6], lo[7]);
;                     *(u32x4*)(HO + off) = wh; *(u32x4*)(LO + off) = wl;
	v_lshlrev_b32_e32 v156, 16, v164
	v_and_b32_e32 v157, 0xffff0000, v164
	v_lshlrev_b32_e32 v158, 16, v168
	v_and_b32_e32 v159, 0xffff0000, v168
	v_pk_add_f32 v[156:157], v[156:157], v[158:159]
	v_pk_fma_f32 v[156:157], v[110:111], 0.5, v[156:157] op_sel_hi:[1,0,1]
	v_cvt_pk_bf16_f32 v164, v156, v157
	v_pk_mul_f32 v[198:199], v[156:157], v[156:157]
	v_lshlrev_b32_e32 v158, 16, v164
	v_and_b32_e32 v159, 0xffff0000, v164
	v_pk_add_f32 v[196:197], v[156:157], v[158:159] neg_lo:[0,1] neg_hi:[0,1]
	v_cvt_pk_bf16_f32 v168, v196, v197
	v_lshlrev_b32_e32 v156, 16, v165
	v_and_b32_e32 v157, 0xffff0000, v165
	v_lshlrev_b32_e32 v158, 16, v169
	v_and_b32_e32 v159, 0xffff0000, v169
	v_pk_add_f32 v[156:157], v[156:157], v[158:159]
	v_pk_fma_f32 v[156:157], v[112:113], 0.5, v[156:157] op_sel_hi:[1,0,1]
	v_cvt_pk_bf16_f32 v165, v156, v157
	v_pk_fma_f32 v[198:199], v[156:157], v[156:157], v[198:199]
	v_lshlrev_b32_e32 v158, 16, v165
	v_and_b32_e32 v159, 0xffff0000, v165
	v_pk_add_f32 v[196:197], v[156:157], v[158:159] neg_lo:[0,1] neg_hi:[0,1]
	v_cvt_pk_bf16_f32 v169, v196, v197
	v_lshlrev_b32_e32 v156, 16, v166
	v_and_b32_e32 v157, 0xffff0000, v166
	v_lshlrev_b32_e32 v158, 16, v170
	v_and_b32_e32 v159, 0xffff0000, v170
	v_pk_add_f32 v[156:157], v[156:157], v[158:159]
	v_pk_fma_f32 v[156:157], v[106:107], 0.5, v[156:157] op_sel_hi:[1,0,1]
	v_cvt_pk_bf16_f32 v166, v156, v157
	v_pk_fma_f32 v[198:199], v[156:157], v[156:157], v[198:199]
	v_lshlrev_b32_e32 v158, 16, v166
	v_and_b32_e32 v159, 0xffff0000, v166
	v_pk_add_f32 v[196:197], v[156:157], v[158:159] neg_lo:[0,1] neg_hi:[0,1]
	v_cvt_pk_bf16_f32 v170, v196, v197
	v_lshlrev_b32_e32 v156, 16, v167
	v_and_b32_e32 v157, 0xffff0000, v167
	v_lshlrev_b32_e32 v158, 16, v171
	v_and_b32_e32 v159, 0xffff0000, v171
	v_pk_add_f32 v[156:157], v[156:157], v[158:159]
	v_pk_fma_f32 v[156:157], v[108:109], 0.5, v[156:157] op_sel_hi:[1,0,1]
	v_cvt_pk_bf16_f32 v167, v156, v157
	v_pk_fma_f32 v[198:199], v[156:157], v[156:157], v[198:199]
	v_lshlrev_b32_e32 v158, 16, v167
	v_and_b32_e32 v159, 0xffff0000, v167
	v_pk_add_f32 v[196:197], v[156:157], v[158:159] neg_lo:[0,1] neg_hi:[0,1]
	v_cvt_pk_bf16_f32 v171, v196, v197
	global_store_dwordx4 v211, v[164:167], s[10:11]
	global_store_dwordx4 v211, v[168:171], s[6:7]
	s_waitcnt vmcnt(14)
	v_lshlrev_b32_e32 v156, 16, v172
	v_and_b32_e32 v157, 0xffff0000, v172
	v_lshlrev_b32_e32 v158, 16, v176
	v_and_b32_e32 v159, 0xffff0000, v176
	v_pk_add_f32 v[156:157], v[156:157], v[158:159]
	v_pk_fma_f32 v[156:157], v[102:103], 0.5, v[156:157] op_sel_hi:[1,0,1]
	v_cvt_pk_bf16_f32 v172, v156, v157
	v_pk_fma_f32 v[198:199], v[156:157], v[156:157], v[198:199]
	v_lshlrev_b32_e32 v158, 16, v172
	v_and_b32_e32 v159, 0xffff0000, v172
	v_pk_add_f32 v[196:197], v[156:157], v[158:159] neg_lo:[0,1] neg_hi:[0,1]
	v_cvt_pk_bf16_f32 v176, v196, v197
	v_lshlrev_b32_e32 v156, 16, v173
	v_and_b32_e32 v157, 0xffff0000, v173
	v_lshlrev_b32_e32 v158, 16, v177
	v_and_b32_e32 v159, 0xffff0000, v177
	v_pk_add_f32 v[156:157], v[156:157], v[158:159]
	v_pk_fma_f32 v[156:157], v[104:105], 0.5, v[156:157] op_sel_hi:[1,0,1]
	v_cvt_pk_bf16_f32 v173, v156, v157
	v_pk_fma_f32 v[198:199], v[156:157], v[156:157], v[198:199]
	v_lshlrev_b32_e32 v158, 16, v173
	v_and_b32_e32 v159, 0xffff0000, v173
	v_pk_add_f32 v[196:197], v[156:157], v[158:159] neg_lo:[0,1] neg_hi:[0,1]
	v_cvt_pk_bf16_f32 v177, v196, v197
	v_lshlrev_b32_e32 v156, 16, v174
	v_and_b32_e32 v157, 0xffff0000, v174
	v_lshlrev_b32_e32 v158, 16, v178
	v_and_b32_e32 v159, 0xffff0000, v178
	v_pk_add_f32 v[156:157], v[156:157], v[158:159]
	v_pk_fma_f32 v[156:157], v[98:99], 0.5, v[156:157] op_sel_hi:[1,0,1]
	v_cvt_pk_bf16_f32 v174, v156, v157
	v_pk_fma_f32 v[198:199], v[156:157], v[156:157], v[198:199]
	v_lshlrev_b32_e32 v158, 16, v174
	v_and_b32_e32 v159, 0xffff0000, v174
	v_pk_add_f32 v[196:197], v[156:157], v[158:159] neg_lo:[0,1] neg_hi:[0,1]
	v_cvt_pk_bf16_f32 v178, v196, v197
	v_lshlrev_b32_e32 v156, 16, v175
	v_and_b32_e32 v157, 0xffff0000, v175
	v_lshlrev_b32_e32 v158, 16, v179
	v_and_b32_e32 v159, 0xffff0000, v179
	v_pk_add_f32 v[156:157], v[156:157], v[158:159]
	v_pk_fma_f32 v[156:157], v[100:101], 0.5, v[156:157] op_sel_hi:[1,0,1]
	v_cvt_pk_bf16_f32 v175, v156, v157
	v_pk_fma_f32 v[198:199], v[156:157], v[156:157], v[198:199]
	v_lshlrev_b32_e32 v158, 16, v175
	v_and_b32_e32 v159, 0xffff0000, v175
	v_pk_add_f32 v[196:197], v[156:157], v[158:159] neg_lo:[0,1] neg_hi:[0,1]
	v_cvt_pk_bf16_f32 v179, v196, v197
	global_store_dwordx4 v211, v[172:175], s[10:11] offset:256
	global_store_dwordx4 v211, v[176:179], s[6:7] offset:256
	v_add_f32_e32 v201, v198, v199
	s_nop 0
	v_add_u32_e32 v211, 0x40000, v213
	global_load_dwordx4 v[164:167], v211, s[38:39]
	global_load_dwordx4 v[168:171], v211, s[6:7]
	global_load_dwordx4 v[172:175], v211, s[38:39] offset:256
	global_load_dwordx4 v[176:179], v211, s[6:7] offset:256
	s_waitcnt vmcnt(18)
; __device__ __forceinline__ unsigned pk2(float lo, float hi) { f32x2_t v = {lo, hi}; bf16x2_t b = __builtin_convertvector(v, bf16x2_t); return __builtin_bit_cast(unsigned, b); }
; __device__ __forceinline__ float bflo(unsigned u) { return __uint_as_float(u << 16); }
;     __device__ __forceinline__ void operator()(const f32x4 (&acc)[2][2][4][2], const Unit& u, int wr, int wc, int fr, int fq) const {
;     ...
;                 for (int bj = 0; bj < 2; ++bj) {
;                     const size_t off = (size_t)row * DM + col0 + bj * HALF;
;                     const u32x4 hh = *(const u32x4*)(HI + off), ll = *(const u32x4*)(LO + off);
;                     float hv[8] = {bflo(hh.x) + bflo(ll.x), bfhi(hh.x) + bfhi(ll.x), bflo(hh.y) + bflo(ll.y), bfhi(hh.y) + bfhi(ll.y),
;                                    bflo(hh.z) + bflo(ll.z), bfhi(hh.z) + bfhi(ll.z), bflo(hh.w) + bflo(ll.w), bfhi(hh.w) + bfhi(ll.w)};
;                     float av[8] = {acc[ai][bj][m][0][0], acc[ai][bj][m][0][1], acc[ai][bj][m][0][2], acc[ai][bj][m][0][3], acc[ai][bj][m][1][0], acc[ai][bj][m][1][1], acc[ai][bj][m][1][2], acc[ai][bj][m][1][3]};
;                     if (GATED) { const u32x4 pp = *(const u32x4*)(PP + off);
;                         const float pv[8] = {bflo(pp.x), bfhi(pp.x), bflo(pp.y), bfhi(pp.y), bflo(pp.z), bfhi(pp.z), bflo(pp.w), bfhi(pp.w)};
; #pragma unroll
;                         for (int e = 0; e < 8; ++e) av[e] = fast_sigmoid(av[e] * rs) * pv[e]; }
;                     else {
; #pragma unroll
;                         for (int e = 0; e < 8; ++e) av[e] *= alpha; }
;                     float lo[8];
; #pragma unroll
;                     for (int e = 0; e < 8; ++e) { hv[e] += av[e]; sq += hv[e] * hv[e]; }
;                     u32x4 wh; wh.x = pk2(hv[0], hv[1]); wh.y = pk2(hv[2], hv[3]); wh.z = pk2(hv[4], hv[5]); wh.w = pk2(hv[6], hv[7]);
;                     lo[0] = hv[0] - bflo(wh.x); lo[1] = hv[1] - bfhi(wh.x); lo[2] = hv[2] - bflo(wh.y); lo[3] = hv[3] - bfhi(wh.y);
;                     lo[4] = hv[4] - bflo(wh.z); lo[5] = hv[5] - bfhi(wh.z); lo[6] = hv[6] - bflo(wh.w); lo[7] = hv[7] - bfhi(wh.w);
;                     u32x4 wl; wl.x = pk2(lo[0], lo[1]); wl.y = pk2(lo[2], lo[3]); wl.z = pk2(lo[4], lo[5]); wl.w = pk2(lo[6], lo[7]);
;                     *(u32x4*)(HO + off) = wh; *(u32x4*)(LO + off) = wl;
	v_lshlrev_b32_e32 v156, 16, v180
	v_and_b32_e32 v157, 0xffff0000, v180
	v_lshlrev_b32_e32 v158, 16, v184
	v_and_b32_e32 v159, 0xffff0000, v184
	v_pk_add_f32 v[156:157], v[156:157], v[158:159]
	v_pk_fma_f32 v[156:157], v[94:95], 0.5, v[156:157] op_sel_hi:[1,0,1]
	v_cvt_pk_bf16_f32 v180, v156, v157
	v_pk_mul_f32 v[198:199], v[156:157], v[156:157]
	v_lshlrev_b32_e32 v158, 16, v180
	v_and_b32_e32 v159, 0xffff0000, v180
	v_pk_add_f32 v[196:197], v[156:157], v[158:159] neg_lo:[0,1] neg_hi:[0,1]
	v_cvt_pk_bf16_f32 v184, v196, v197
	v_lshlrev_b32_e32 v156, 16, v181
	v_and_b32_e32 v157, 0xffff0000, v181
	v_lshlrev_b32_e32 v158, 16, v185
	v_and_b32_e32 v159, 0xffff0000, v185
	v_pk_add_f32 v[156:157], v[156:157], v[158:159]
	v_pk_fma_f32 v[156:157], v[96:97], 0.5, v[156:157] op_sel_hi:[1,0,1]
	v_cvt_pk_bf16_f32 v181, v156, v157
	v_pk_fma_f32 v[198:199], v[156:157], v[156:157], v[198:199]
	v_lshlrev_b32_e32 v158, 16, v181
	v_and_b32_e32 v159, 0xffff0000, v181
	v_pk_add_f32 v[196:197], v[156:157], v[158:159] neg_lo:[0,1] neg_hi:[0,1]
	v_cvt_pk_bf16_f32 v185, v196, v197
	v_lshlrev_b32_e32 v156, 16, v182
	v_and_b32_e32 v157, 0xffff0000, v182
	v_lshlrev_b32_e32 v158, 16, v186
	v_and_b32_e32 v159, 0xffff0000, v186
	v_pk_add_f32 v[156:157], v[156:157], v[158:159]
	v_pk_fma_f32 v[156:157], v[90:91], 0.5, v[156:157] op_sel_hi:[1,0,1]
	v_cvt_pk_bf16_f32 v182, v156, v157
	v_pk_fma_f32 v[198:199], v[156:157], v[156:157], v[198:199]
	v_lshlrev_b32_e32 v158, 16, v182
	v_and_b32_e32 v159, 0xffff0000, v182
	v_pk_add_f32 v[196:197], v[156:157], v[158:159] neg_lo:[0,1] neg_hi:[0,1]
	v_cvt_pk_bf16_f32 v186, v196, v197
	v_lshlrev_b32_e32 v156, 16, v183
	v_and_b32_e32 v157, 0xffff0000, v183
	v_lshlrev_b32_e32 v158, 16, v187
	v_and_b32_e32 v159, 0xffff0000, v187
	v_pk_add_f32 v[156:157], v[156:157], v[158:159]
	v_pk_fma_f32 v[156:157], v[92:93], 0.5, v[156:157] op_sel_hi:[1,0,1]
	v_cvt_pk_bf16_f32 v183, v156, v157
	v_pk_fma_f32 v[198:199], v[156:157], v[156:157], v[198:199]
	v_lshlrev_b32_e32 v158, 16, v183
	v_and_b32_e32 v159, 0xffff0000, v183
	v_pk_add_f32 v[196:197], v[156:157], v[158:159] neg_lo:[0,1] neg_hi:[0,1]
	v_cvt_pk_bf16_f32 v187, v196, v197
	global_store_dwordx4 v212, v[180:183], s[10:11]
	global_store_dwordx4 v212, v[184:187], s[6:7]
	s_waitcnt vmcnt(18)
	v_lshlrev_b32_e32 v156, 16, v188
	v_and_b32_e32 v157, 0xffff0000, v188
	v_lshlrev_b32_e32 v158, 16, v192
	v_and_b32_e32 v159, 0xffff0000, v192
	v_pk_add_f32 v[156:157], v[156:157], v[158:159]
	v_pk_fma_f32 v[156:157], v[86:87], 0.5, v[156:157] op_sel_hi:[1,0,1]
	v_cvt_pk_bf16_f32 v188, v156, v157
	v_pk_fma_f32 v[198:199], v[156:157], v[156:157], v[198:199]
	v_lshlrev_b32_e32 v158, 16, v188
	v_and_b32_e32 v159, 0xffff0000, v188
	v_pk_add_f32 v[196:197], v[156:157], v[158:159] neg_lo:[0,1] neg_hi:[0,1]
	v_cvt_pk_bf16_f32 v192, v196, v197
	v_lshlrev_b32_e32 v156, 16, v189
	v_and_b32_e32 v157, 0xffff0000, v189
	v_lshlrev_b32_e32 v158, 16, v193
	v_and_b32_e32 v159, 0xffff0000, v193
	v_pk_add_f32 v[156:157], v[156:157], v[158:159]
	v_pk_fma_f32 v[156:157], v[88:89], 0.5, v[156:157] op_sel_hi:[1,0,1]
	v_cvt_pk_bf16_f32 v189, v156, v157
	v_pk_fma_f32 v[198:199], v[156:157], v[156:157], v[198:199]
	v_lshlrev_b32_e32 v158, 16, v189
	v_and_b32_e32 v159, 0xffff0000, v189
	v_pk_add_f32 v[196:197], v[156:157], v[158:159] neg_lo:[0,1] neg_hi:[0,1]
	v_cvt_pk_bf16_f32 v193, v196, v197
	v_lshlrev_b32_e32 v156, 16, v190
	v_and_b32_e32 v157, 0xffff0000, v190
	v_lshlrev_b32_e32 v158, 16, v194
	v_and_b32_e32 v159, 0xffff0000, v194
	v_pk_add_f32 v[156:157], v[156:157], v[158:159]
	v_pk_fma_f32 v[156:157], v[82:83], 0.5, v[156:157] op_sel_hi:[1,0,1]
	v_cvt_pk_bf16_f32 v190, v156, v157
	v_pk_fma_f32 v[198:199], v[156:157], v[156:157], v[198:199]
	v_lshlrev_b32_e32 v158, 16, v190
	v_and_b32_e32 v159, 0xffff0000, v190
	v_pk_add_f32 v[196:197], v[156:157], v[158:159] neg_lo:[0,1] neg_hi:[0,1]
	v_cvt_pk_bf16_f32 v194, v196, v197
	v_lshlrev_b32_e32 v156, 16, v191
	v_and_b32_e32 v157, 0xffff0000, v191
	v_lshlrev_b32_e32 v158, 16, v195
	v_and_b32_e32 v159, 0xffff0000, v195
	v_pk_add_f32 v[156:157], v[156:157], v[158:159]
	v_pk_fma_f32 v[156:157], v[84:85], 0.5, v[156:157] op_sel_hi:[1,0,1]
	v_cvt_pk_bf16_f32 v191, v156, v157
	v_pk_fma_f32 v[198:199], v[156:157], v[156:157], v[198:199]
	v_lshlrev_b32_e32 v158, 16, v191
	v_and_b32_e32 v159, 0xffff0000, v191
	v_pk_add_f32 v[196:197], v[156:157], v[158:159] neg_lo:[0,1] neg_hi:[0,1]
	v_cvt_pk_bf16_f32 v195, v196, v197
	global_store_dwordx4 v212, v[188:191], s[10:11] offset:256
	global_store_dwordx4 v212, v[192:195], s[6:7] offset:256
	v_add_f32_e32 v202, v198, v199
	s_nop 0
	v_add_u32_e32 v212, 0x48000, v213
	global_load_dwordx4 v[180:183], v212, s[38:39]
	global_load_dwordx4 v[184:187], v212, s[6:7]
	global_load_dwordx4 v[188:191], v212, s[38:39] offset:256
	global_load_dwordx4 v[192:195], v212, s[6:7] offset:256
	s_waitcnt vmcnt(22)
; __device__ __forceinline__ unsigned pk2(float lo, float hi) { f32x2_t v = {lo, hi}; bf16x2_t b = __builtin_convertvector(v, bf16x2_t); return __builtin_bit_cast(unsigned, b); }
; __device__ __forceinline__ float bflo(unsigned u) { return __uint_as_float(u << 16); }
;     __device__ __forceinline__ void operator()(const f32x4 (&acc)[2][2][4][2], const Unit& u, int wr, int wc, int fr, int fq) const {
;     ...
;                 for (int bj = 0; bj < 2; ++bj) {
;                     const size_t off = (size_t)row * DM + col0 + bj * HALF;
;                     const u32x4 hh = *(const u32x4*)(HI + off), ll = *(const u32x4*)(LO + off);
;                     float hv[8] = {bflo(hh.x) + bflo(ll.x), bfhi(hh.x) + bfhi(ll.x), bflo(hh.y) + bflo(ll.y), bfhi(hh.y) + bfhi(ll.y),
;                                    bflo(hh.z) + bflo(ll.z), bfhi(hh.z) + bfhi(ll.z), bflo(hh.w) + bflo(ll.w), bfhi(hh.w) + bfhi(ll.w)};
;                     float av[8] = {acc[ai][bj][m][0][0], acc[ai][bj][m][0][1], acc[ai][bj][m][0][2], acc[ai][bj][m][0][3], acc[ai][bj][m][1][0], acc[ai][bj][m][1][1], acc[ai][bj][m][1][2], acc[ai][bj][m][1][3]};
;                     if (GATED) { const u32x4 pp = *(const u32x4*)(PP + off);
;                         const float pv[8] = {bflo(pp.x), bfhi(pp.x), bflo(pp.y), bfhi(pp.y), bflo(pp.z), bfhi(pp.z), bflo(pp.w), bfhi(pp.w)};
; #pragma unroll
;                         for (int e = 0; e < 8; ++e) av[e] = fast_sigmoid(av[e] * rs) * pv[e]; }
;                     else {
; #pragma unroll
;                         for (int e = 0; e < 8; ++e) av[e] *= alpha; }
;                     float lo[8];
; #pragma unroll
;                     for (int e = 0; e < 8; ++e) { hv[e] += av[e]; sq += hv[e] * hv[e]; }
;                     u32x4 wh; wh.x = pk2(hv[0], hv[1]); wh.y = pk2(hv[2], hv[3]); wh.z = pk2(hv[4], hv[5]); wh.w = pk2(hv[6], hv[7]);
;                     lo[0] = hv[0] - bflo(wh.x); lo[1] = hv[1] - bfhi(wh.x); lo[2] = hv[2] - bflo(wh.y); lo[3] = hv[3] - bfhi(wh.y);
;                     lo[4] = hv[4] - bflo(wh.z); lo[5] = hv[5] - bfhi(wh.z); lo[6] = hv[6] - bflo(wh.w); lo[7] = hv[7] - bfhi(wh.w);
;                     u32x4 wl; wl.x = pk2(lo[0], lo[1]); wl.y = pk2(lo[2], lo[3]); wl.z = pk2(lo[4], lo[5]); wl.w = pk2(lo[6], lo[7]);
;                     *(u32x4*)(HO + off) = wh; *(u32x4*)(LO + off) = wl;
	v_lshlrev_b32_e32 v156, 16, v140
	v_and_b32_e32 v157, 0xffff0000, v140
	v_lshlrev_b32_e32 v158, 16, v144
	v_and_b32_e32 v159, 0xffff0000, v144
	v_pk_add_f32 v[156:157], v[156:157], v[158:159]
	v_pk_fma_f32 v[156:157], v[78:79], 0.5, v[156:157] op_sel_hi:[1,0,1]
	v_cvt_pk_bf16_f32 v140, v156, v157
	v_pk_mul_f32 v[198:199], v[156:157], v[156:157]
	v_lshlrev_b32_e32 v158, 16, v140
	v_and_b32_e32 v159, 0xffff0000, v140
	v_pk_add_f32 v[196:197], v[156:157], v[158:159] neg_lo:[0,1] neg_hi:[0,1]
	v_cvt_pk_bf16_f32 v144, v196, v197
	v_lshlrev_b32_e32 v156, 16, v141
	v_and_b32_e32 v157, 0xffff0000, v141
	v_lshlrev_b32_e32 v158, 16, v145
	v_and_b32_e32 v159, 0xffff0000, v145
	v_pk_add_f32 v[156:157], v[156:157], v[158:159]
	v_pk_fma_f32 v[156:157], v[80:81], 0.5, v[156:157] op_sel_hi:[1,0,1]
	v_cvt_pk_bf16_f32 v141, v156, v157
	v_pk_fma_f32 v[198:199], v[156:157], v[156:157], v[198:199]
	v_lshlrev_b32_e32 v158, 16, v141
	v_and_b32_e32 v159, 0xffff0000, v141
	v_pk_add_f32 v[196:197], v[156:157], v[158:159] neg_lo:[0,1] neg_hi:[0,1]
	v_cvt_pk_bf16_f32 v145, v196, v197
	v_lshlrev_b32_e32 v156, 16, v142
	v_and_b32_e32 v157, 0xffff0000, v142
	v_lshlrev_b32_e32 v158, 16, v146
	v_and_b32_e32 v159, 0xffff0000, v146
	v_pk_add_f32 v[156:157], v[156:157], v[158:159]
	v_pk_fma_f32 v[156:157], v[74:75], 0.5, v[156:157] op_sel_hi:[1,0,1]
	v_cvt_pk_bf16_f32 v142, v156, v157
	v_pk_fma_f32 v[198:199], v[156:157], v[156:157], v[198:199]
	v_lshlrev_b32_e32 v158, 16, v142
	v_and_b32_e32 v159, 0xffff0000, v142
	v_pk_add_f32 v[196:197], v[156:157], v[158:159] neg_lo:[0,1] neg_hi:[0,1]
	v_cvt_pk_bf16_f32 v146, v196, v197
	v_lshlrev_b32_e32 v156, 16, v143
	v_and_b32_e32 v157, 0xffff0000, v143
	v_lshlrev_b32_e32 v158, 16, v147
	v_and_b32_e32 v159, 0xffff0000, v147
	v_pk_add_f32 v[156:157], v[156:157], v[158:159]
	v_pk_fma_f32 v[156:157], v[76:77], 0.5, v[156:157] op_sel_hi:[1,0,1]
	v_cvt_pk_bf16_f32 v143, v156, v157
	v_pk_fma_f32 v[198:199], v[156:157], v[156:157], v[198:199]
	v_lshlrev_b32_e32 v158, 16, v143
	v_and_b32_e32 v159, 0xffff0000, v143
	v_pk_add_f32 v[196:197], v[156:157], v[158:159] neg_lo:[0,1] neg_hi:[0,1]
	v_cvt_pk_bf16_f32 v147, v196, v197
	global_store_dwordx4 v210, v[140:143], s[10:11]
	global_store_dwordx4 v210, v[144:147], s[6:7]
	s_waitcnt vmcnt(22)
	v_lshlrev_b32_e32 v156, 16, v148
	v_and_b32_e32 v157, 0xffff0000, v148
	v_lshlrev_b32_e32 v158, 16, v152
	v_and_b32_e32 v159, 0xffff0000, v152
	v_pk_add_f32 v[156:157], v[156:157], v[158:159]
	v_pk_fma_f32 v[156:157], v[70:71], 0.5, v[156:157] op_sel_hi:[1,0,1]
	v_cvt_pk_bf16_f32 v148, v156, v157
	v_pk_fma_f32 v[198:199], v[156:157], v[156:157], v[198:199]
	v_lshlrev_b32_e32 v158, 16, v148
	v_and_b32_e32 v159, 0xffff0000, v148
	v_pk_add_f32 v[196:197], v[156:157], v[158:159] neg_lo:[0,1] neg_hi:[0,1]
	v_cvt_pk_bf16_f32 v152, v196, v197
	v_lshlrev_b32_e32 v156, 16, v149
	v_and_b32_e32 v157, 0xffff0000, v149
	v_lshlrev_b32_e32 v158, 16, v153
	v_and_b32_e32 v159, 0xffff0000, v153
	v_pk_add_f32 v[156:157], v[156:157], v[158:159]
	v_pk_fma_f32 v[156:157], v[72:73], 0.5, v[156:157] op_sel_hi:[1,0,1]
	v_cvt_pk_bf16_f32 v149, v156, v157
	v_pk_fma_f32 v[198:199], v[156:157], v[156:157], v[198:199]
	v_lshlrev_b32_e32 v158, 16, v149
	v_and_b32_e32 v159, 0xffff0000, v149
	v_pk_add_f32 v[196:197], v[156:157], v[158:159] neg_lo:[0,1] neg_hi:[0,1]
	v_cvt_pk_bf16_f32 v153, v196, v197
	v_lshlrev_b32_e32 v156, 16, v150
	v_and_b32_e32 v157, 0xffff0000, v150
	v_lshlrev_b32_e32 v158, 16, v154
	v_and_b32_e32 v159, 0xffff0000, v154
	v_pk_add_f32 v[156:157], v[156:157], v[158:159]
	v_pk_fma_f32 v[156:157], v[66:67], 0.5, v[156:157] op_sel_hi:[1,0,1]
	v_cvt_pk_bf16_f32 v150, v156, v157
	v_pk_fma_f32 v[198:199], v[156:157], v[156:157], v[198:199]
	v_lshlrev_b32_e32 v158, 16, v150
	v_and_b32_e32 v159, 0xffff0000, v150
	v_pk_add_f32 v[196:197], v[156:157], v[158:159] neg_lo:[0,1] neg_hi:[0,1]
	v_cvt_pk_bf16_f32 v154, v196, v197
	v_lshlrev_b32_e32 v156, 16, v151
	v_and_b32_e32 v157, 0xffff0000, v151
	v_lshlrev_b32_e32 v158, 16, v155
	v_and_b32_e32 v159, 0xffff0000, v155
	v_pk_add_f32 v[156:157], v[156:157], v[158:159]
	v_pk_fma_f32 v[156:157], v[68:69], 0.5, v[156:157] op_sel_hi:[1,0,1]
	v_cvt_pk_bf16_f32 v151, v156, v157
	v_pk_fma_f32 v[198:199], v[156:157], v[156:157], v[198:199]
	v_lshlrev_b32_e32 v158, 16, v151
	v_and_b32_e32 v159, 0xffff0000, v151
	v_pk_add_f32 v[196:197], v[156:157], v[158:159] neg_lo:[0,1] neg_hi:[0,1]
	v_cvt_pk_bf16_f32 v155, v196, v197
	global_store_dwordx4 v210, v[148:151], s[10:11] offset:256
	global_store_dwordx4 v210, v[152:155], s[6:7] offset:256
	v_add_f32_e32 v203, v198, v199
	s_nop 0
	v_add_u32_e32 v210, 0x50000, v213
	global_load_dwordx4 v[140:143], v210, s[38:39]
	global_load_dwordx4 v[144:147], v210, s[6:7]
	global_load_dwordx4 v[148:151], v210, s[38:39] offset:256
	global_load_dwordx4 v[152:155], v210, s[6:7] offset:256
	s_waitcnt vmcnt(18)
; __device__ __forceinline__ unsigned pk2(float lo, float hi) { f32x2_t v = {lo, hi}; bf16x2_t b = __builtin_convertvector(v, bf16x2_t); return __builtin_bit_cast(unsigned, b); }
; __device__ __forceinline__ float bflo(unsigned u) { return __uint_as_float(u << 16); }
;     __device__ __forceinline__ void operator()(const f32x4 (&acc)[2][2][4][2], const Unit& u, int wr, int wc, int fr, int fq) const {
;     ...
;                 for (int bj = 0; bj < 2; ++bj) {
;                     const size_t off = (size_t)row * DM + col0 + bj * HALF;
;                     const u32x4 hh = *(const u32x4*)(HI + off), ll = *(const u32x4*)(LO + off);
;                     float hv[8] = {bflo(hh.x) + bflo(ll.x), bfhi(hh.x) + bfhi(ll.x), bflo(hh.y) + bflo(ll.y), bfhi(hh.y) + bfhi(ll.y),
;                                    bflo(hh.z) + bflo(ll.z), bfhi(hh.z) + bfhi(ll.z), bflo(hh.w) + bflo(ll.w), bfhi(hh.w) + bfhi(ll.w)};
;                     float av[8] = {acc[ai][bj][m][0][0], acc[ai][bj][m][0][1], acc[ai][bj][m][0][2], acc[ai][bj][m][0][3], acc[ai][bj][m][1][0], acc[ai][bj][m][1][1], acc[ai][bj][m][1][2], acc[ai][bj][m][1][3]};
;                     if (GATED) { const u32x4 pp = *(const u32x4*)(PP + off);
;                         const float pv[8] = {bflo(pp.x), bfhi(pp.x), bflo(pp.y), bfhi(pp.y), bflo(pp.z), bfhi(pp.z), bflo(pp.w), bfhi(pp.w)};
; #pragma unroll
;                         for (int e = 0; e < 8; ++e) av[e] = fast_sigmoid(av[e] * rs) * pv[e]; }
;                     else {
; #pragma unroll
;                         for (int e = 0; e < 8; ++e) av[e] *= alpha; }
;                     float lo[8];
; #pragma unroll
;                     for (int e = 0; e < 8; ++e) { hv[e] += av[e]; sq += hv[e] * hv[e]; }
;                     u32x4 wh; wh.x = pk2(hv[0], hv[1]); wh.y = pk2(hv[2], hv[3]); wh.z = pk2(hv[4], hv[5]); wh.w = pk2(hv[6], hv[7]);
;                     lo[0] = hv[0] - bflo(wh.x); lo[1] = hv[1] - bfhi(wh.x); lo[2] = hv[2] - bflo(wh.y); lo[3] = hv[3] - bfhi(wh.y);
;                     lo[4] = hv[4] - bflo(wh.z); lo[5] = hv[5] - bfhi(wh.z); lo[6] = hv[6] - bflo(wh.w); lo[7] = hv[7] - bfhi(wh.w);
;                     u32x4 wl; wl.x = pk2(lo[0], lo[1]); wl.y = pk2(lo[2], lo[3]); wl.z = pk2(lo[4], lo[5]); wl.w = pk2(lo[6], lo[7]);
;                     *(u32x4*)(HO + off) = wh; *(u32x4*)(LO + off) = wl;
	v_lshlrev_b32_e32 v156, 16, v164
	v_and_b32_e32 v157, 0xffff0000, v164
	v_lshlrev_b32_e32 v158, 16, v168
	v_and_b32_e32 v159, 0xffff0000, v168
	v_pk_add_f32 v[156:157], v[156:157], v[158:159]
	v_pk_fma_f32 v[156:157], v[62:63], 0.5, v[156:157] op_sel_hi:[1,0,1]
	v_cvt_pk_bf16_f32 v164, v156, v157
	v_pk_mul_f32 v[198:199], v[156:157], v[156:157]
	v_lshlrev_b32_e32 v158, 16, v164
	v_and_b32_e32 v159, 0xffff0000, v164
	v_pk_add_f32 v[196:197], v[156:157], v[158:159] neg_lo:[0,1] neg_hi:[0,1]
	v_cvt_pk_bf16_f32 v168, v196, v197
	v_lshlrev_b32_e32 v156, 16, v165
	v_and_b32_e32 v157, 0xffff0000, v165
	v_lshlrev_b32_e32 v158, 16, v169
	v_and_b32_e32 v159, 0xffff0000, v169
	v_pk_add_f32 v[156:157], v[156:157], v[158:159]
	v_pk_fma_f32 v[156:157], v[64:65], 0.5, v[156:157] op_sel_hi:[1,0,1]
	v_cvt_pk_bf16_f32 v165, v156, v157
	v_pk_fma_f32 v[198:199], v[156:157], v[156:157], v[198:199]
	v_lshlrev_b32_e32 v158, 16, v165
	v_and_b32_e32 v159, 0xffff0000, v165
	v_pk_add_f32 v[196:197], v[156:157], v[158:159] neg_lo:[0,1] neg_hi:[0,1]
	v_cvt_pk_bf16_f32 v169, v196, v197
	v_lshlrev_b32_e32 v156, 16, v166
	v_and_b32_e32 v157, 0xffff0000, v166
	v_lshlrev_b32_e32 v158, 16, v170
	v_and_b32_e32 v159, 0xffff0000, v170
	v_pk_add_f32 v[156:157], v[156:157], v[158:159]
	v_pk_fma_f32 v[156:157], v[58:59], 0.5, v[156:157] op_sel_hi:[1,0,1]
	v_cvt_pk_bf16_f32 v166, v156, v157
	v_pk_fma_f32 v[198:199], v[156:157], v[156:157], v[198:199]
	v_lshlrev_b32_e32 v158, 16, v166
	v_and_b32_e32 v159, 0xffff0000, v166
	v_pk_add_f32 v[196:197], v[156:157], v[158:159] neg_lo:[0,1] neg_hi:[0,1]
	v_cvt_pk_bf16_f32 v170, v196, v197
	v_lshlrev_b32_e32 v156, 16, v167
	v_and_b32_e32 v157, 0xffff0000, v167
	v_lshlrev_b32_e32 v158, 16, v171
	v_and_b32_e32 v159, 0xffff0000, v171
	v_pk_add_f32 v[156:157], v[156:157], v[158:159]
	v_pk_fma_f32 v[156:157], v[60:61], 0.5, v[156:157] op_sel_hi:[1,0,1]
	v_cvt_pk_bf16_f32 v167, v156, v157
	v_pk_fma_f32 v[198:199], v[156:157], v[156:157], v[198:199]
	v_lshlrev_b32_e32 v158, 16, v167
	v_and_b32_e32 v159, 0xffff0000, v167
	v_pk_add_f32 v[196:197], v[156:157], v[158:159] neg_lo:[0,1] neg_hi:[0,1]
	v_cvt_pk_bf16_f32 v171, v196, v197
	global_store_dwordx4 v211, v[164:167], s[10:11]
	global_store_dwordx4 v211, v[168:171], s[6:7]
	s_waitcnt vmcnt(18)
	v_lshlrev_b32_e32 v156, 16, v172
	v_and_b32_e32 v157, 0xffff0000, v172
	v_lshlrev_b32_e32 v158, 16, v176
	v_and_b32_e32 v159, 0xffff0000, v176
	v_pk_add_f32 v[156:157], v[156:157], v[158:159]
	v_pk_fma_f32 v[156:157], v[54:55], 0.5, v[156:157] op_sel_hi:[1,0,1]
	v_cvt_pk_bf16_f32 v172, v156, v157
	v_pk_fma_f32 v[198:199], v[156:157], v[156:157], v[198:199]
	v_lshlrev_b32_e32 v158, 16, v172
	v_and_b32_e32 v159, 0xffff0000, v172
	v_pk_add_f32 v[196:197], v[156:157], v[158:159] neg_lo:[0,1] neg_hi:[0,1]
	v_cvt_pk_bf16_f32 v176, v196, v197
	v_lshlrev_b32_e32 v156, 16, v173
	v_and_b32_e32 v157, 0xffff0000, v173
	v_lshlrev_b32_e32 v158, 16, v177
	v_and_b32_e32 v159, 0xffff0000, v177
	v_pk_add_f32 v[156:157], v[156:157], v[158:159]
	v_pk_fma_f32 v[156:157], v[56:57], 0.5, v[156:157] op_sel_hi:[1,0,1]
	v_cvt_pk_bf16_f32 v173, v156, v157
	v_pk_fma_f32 v[198:199], v[156:157], v[156:157], v[198:199]
	v_lshlrev_b32_e32 v158, 16, v173
	v_and_b32_e32 v159, 0xffff0000, v173
	v_pk_add_f32 v[196:197], v[156:157], v[158:159] neg_lo:[0,1] neg_hi:[0,1]
	v_cvt_pk_bf16_f32 v177, v196, v197
	v_lshlrev_b32_e32 v156, 16, v174
	v_and_b32_e32 v157, 0xffff0000, v174
	v_lshlrev_b32_e32 v158, 16, v178
	v_and_b32_e32 v159, 0xffff0000, v178
	v_pk_add_f32 v[156:157], v[156:157], v[158:159]
	v_pk_fma_f32 v[156:157], v[50:51], 0.5, v[156:157] op_sel_hi:[1,0,1]
	v_cvt_pk_bf16_f32 v174, v156, v157
	v_pk_fma_f32 v[198:199], v[156:157], v[156:157], v[198:199]
	v_lshlrev_b32_e32 v158, 16, v174
	v_and_b32_e32 v159, 0xffff0000, v174
	v_pk_add_f32 v[196:197], v[156:157], v[158:159] neg_lo:[0,1] neg_hi:[0,1]
	v_cvt_pk_bf16_f32 v178, v196, v197
	v_lshlrev_b32_e32 v156, 16, v175
	v_and_b32_e32 v157, 0xffff0000, v175
	v_lshlrev_b32_e32 v158, 16, v179
	v_and_b32_e32 v159, 0xffff0000, v179
	v_pk_add_f32 v[156:157], v[156:157], v[158:159]
	v_pk_fma_f32 v[156:157], v[52:53], 0.5, v[156:157] op_sel_hi:[1,0,1]
	v_cvt_pk_bf16_f32 v175, v156, v157
	v_pk_fma_f32 v[198:199], v[156:157], v[156:157], v[198:199]
	v_lshlrev_b32_e32 v158, 16, v175
	v_and_b32_e32 v159, 0xffff0000, v175
	v_pk_add_f32 v[196:197], v[156:157], v[158:159] neg_lo:[0,1] neg_hi:[0,1]
	v_cvt_pk_bf16_f32 v179, v196, v197
	global_store_dwordx4 v211, v[172:175], s[10:11] offset:256
	global_store_dwordx4 v211, v[176:179], s[6:7] offset:256
	v_add_f32_e32 v206, v198, v199
	s_nop 0
	v_add_u32_e32 v211, 0x58000, v213
	global_load_dwordx4 v[164:167], v211, s[38:39]
	global_load_dwordx4 v[168:171], v211, s[6:7]
	global_load_dwordx4 v[172:175], v211, s[38:39] offset:256
	global_load_dwordx4 v[176:179], v211, s[6:7] offset:256
	s_waitcnt vmcnt(18)
; __device__ __forceinline__ unsigned pk2(float lo, float hi) { f32x2_t v = {lo, hi}; bf16x2_t b = __builtin_convertvector(v, bf16x2_t); return __builtin_bit_cast(unsigned, b); }
; __device__ __forceinline__ float bflo(unsigned u) { return __uint_as_float(u << 16); }
;     __device__ __forceinline__ void operator()(const f32x4 (&acc)[2][2][4][2], const Unit& u, int wr, int wc, int fr, int fq) const {
;     ...
;                 for (int bj = 0; bj < 2; ++bj) {
;                     const size_t off = (size_t)row * DM + col0 + bj * HALF;
;                     const u32x4 hh = *(const u32x4*)(HI + off), ll = *(const u32x4*)(LO + off);
;                     float hv[8] = {bflo(hh.x) + bflo(ll.x), bfhi(hh.x) + bfhi(ll.x), bflo(hh.y) + bflo(ll.y), bfhi(hh.y) + bfhi(ll.y),
;                                    bflo(hh.z) + bflo(ll.z), bfhi(hh.z) + bfhi(ll.z), bflo(hh.w) + bflo(ll.w), bfhi(hh.w) + bfhi(ll.w)};
;                     float av[8] = {acc[ai][bj][m][0][0], acc[ai][bj][m][0][1], acc[ai][bj][m][0][2], acc[ai][bj][m][0][3], acc[ai][bj][m][1][0], acc[ai][bj][m][1][1], acc[ai][bj][m][1][2], acc[ai][bj][m][1][3]};
;                     if (GATED) { const u32x4 pp = *(const u32x4*)(PP + off);
;                         const float pv[8] = {bflo(pp.x), bfhi(pp.x), bflo(pp.y), bfhi(pp.y), bflo(pp.z), bfhi(pp.z), bflo(pp.w), bfhi(pp.w)};
; #pragma unroll
;                         for (int e = 0; e < 8; ++e) av[e] = fast_sigmoid(av[e] * rs) * pv[e]; }
;                     else {
; #pragma unroll
;                         for (int e = 0; e < 8; ++e) av[e] *= alpha; }
;                     float lo[8];
; #pragma unroll
;                     for (int e = 0; e < 8; ++e) { hv[e] += av[e]; sq += hv[e] * hv[e]; }
;                     u32x4 wh; wh.x = pk2(hv[0], hv[1]); wh.y = pk2(hv[2], hv[3]); wh.z = pk2(hv[4], hv[5]); wh.w = pk2(hv[6], hv[7]);
;                     lo[0] = hv[0] - bflo(wh.x); lo[1] = hv[1] - bfhi(wh.x); lo[2] = hv[2] - bflo(wh.y); lo[3] = hv[3] - bfhi(wh.y);
;                     lo[4] = hv[4] - bflo(wh.z); lo[5] = hv[5] - bfhi(wh.z); lo[6] = hv[6] - bflo(wh.w); lo[7] = hv[7] - bfhi(wh.w);
;                     u32x4 wl; wl.x = pk2(lo[0], lo[1]); wl.y = pk2(lo[2], lo[3]); wl.z = pk2(lo[4], lo[5]); wl.w = pk2(lo[6], lo[7]);
;                     *(u32x4*)(HO + off) = wh; *(u32x4*)(LO + off) = wl;
	v_lshlrev_b32_e32 v156, 16, v180
	v_and_b32_e32 v157, 0xffff0000, v180
	v_lshlrev_b32_e32 v158, 16, v184
	v_and_b32_e32 v159, 0xffff0000, v184
	v_pk_add_f32 v[156:157], v[156:157], v[158:159]
	v_pk_fma_f32 v[156:157], v[46:47], 0.5, v[156:157] op_sel_hi:[1,0,1]
	v_cvt_pk_bf16_f32 v180, v156, v157
	v_pk_mul_f32 v[198:199], v[156:157], v[156:157]
	v_lshlrev_b32_e32 v158, 16, v180
	v_and_b32_e32 v159, 0xffff0000, v180
	v_pk_add_f32 v[196:197], v[156:157], v[158:159] neg_lo:[0,1] neg_hi:[0,1]
	v_cvt_pk_bf16_f32 v184, v196, v197
	v_lshlrev_b32_e32 v156, 16, v181
	v_and_b32_e32 v157, 0xffff0000, v181
	v_lshlrev_b32_e32 v158, 16, v185
	v_and_b32_e32 v159, 0xffff0000, v185
	v_pk_add_f32 v[156:157], v[156:157], v[158:159]
	v_pk_fma_f32 v[156:157], v[48:49], 0.5, v[156:157] op_sel_hi:[1,0,1]
	v_cvt_pk_bf16_f32 v181, v156, v157
	v_pk_fma_f32 v[198:199], v[156:157], v[156:157], v[198:199]
	v_lshlrev_b32_e32 v158, 16, v181
	v_and_b32_e32 v159, 0xffff0000, v181
	v_pk_add_f32 v[196:197], v[156:157], v[158:159] neg_lo:[0,1] neg_hi:[0,1]
	v_cvt_pk_bf16_f32 v185, v196, v197
	v_lshlrev_b32_e32 v156, 16, v182
	v_and_b32_e32 v157, 0xffff0000, v182
	v_lshlrev_b32_e32 v158, 16, v186
	v_and_b32_e32 v159, 0xffff0000, v186
	v_pk_add_f32 v[156:157], v[156:157], v[158:159]
	v_pk_fma_f32 v[156:157], v[42:43], 0.5, v[156:157] op_sel_hi:[1,0,1]
	v_cvt_pk_bf16_f32 v182, v156, v157
	v_pk_fma_f32 v[198:199], v[156:157], v[156:157], v[198:199]
	v_lshlrev_b32_e32 v158, 16, v182
	v_and_b32_e32 v159, 0xffff0000, v182
	v_pk_add_f32 v[196:197], v[156:157], v[158:159] neg_lo:[0,1] neg_hi:[0,1]
	v_cvt_pk_bf16_f32 v186, v196, v197
	v_lshlrev_b32_e32 v156, 16, v183
	v_and_b32_e32 v157, 0xffff0000, v183
	v_lshlrev_b32_e32 v158, 16, v187
	v_and_b32_e32 v159, 0xffff0000, v187
	v_pk_add_f32 v[156:157], v[156:157], v[158:159]
	v_pk_fma_f32 v[156:157], v[44:45], 0.5, v[156:157] op_sel_hi:[1,0,1]
	v_cvt_pk_bf16_f32 v183, v156, v157
	v_pk_fma_f32 v[198:199], v[156:157], v[156:157], v[198:199]
	v_lshlrev_b32_e32 v158, 16, v183
	v_and_b32_e32 v159, 0xffff0000, v183
	v_pk_add_f32 v[196:197], v[156:157], v[158:159] neg_lo:[0,1] neg_hi:[0,1]
	v_cvt_pk_bf16_f32 v187, v196, v197
	global_store_dwordx4 v212, v[180:183], s[10:11]
	global_store_dwordx4 v212, v[184:187], s[6:7]
	s_waitcnt vmcnt(18)
	v_lshlrev_b32_e32 v156, 16, v188
	v_and_b32_e32 v157, 0xffff0000, v188
	v_lshlrev_b32_e32 v158, 16, v192
	v_and_b32_e32 v159, 0xffff0000, v192
	v_pk_add_f32 v[156:157], v[156:157], v[158:159]
	v_pk_fma_f32 v[156:157], v[38:39], 0.5, v[156:157] op_sel_hi:[1,0,1]
	v_cvt_pk_bf16_f32 v188, v156, v157
	v_pk_fma_f32 v[198:199], v[156:157], v[156:157], v[198:199]
	v_lshlrev_b32_e32 v158, 16, v188
	v_and_b32_e32 v159, 0xffff0000, v188
	v_pk_add_f32 v[196:197], v[156:157], v[158:159] neg_lo:[0,1] neg_hi:[0,1]
	v_cvt_pk_bf16_f32 v192, v196, v197
	v_lshlrev_b32_e32 v156, 16, v189
	v_and_b32_e32 v157, 0xffff0000, v189
	v_lshlrev_b32_e32 v158, 16, v193
	v_and_b32_e32 v159, 0xffff0000, v193
	v_pk_add_f32 v[156:157], v[156:157], v[158:159]
	v_pk_fma_f32 v[156:157], v[40:41], 0.5, v[156:157] op_sel_hi:[1,0,1]
	v_cvt_pk_bf16_f32 v189, v156, v157
	v_pk_fma_f32 v[198:199], v[156:157], v[156:157], v[198:199]
	v_lshlrev_b32_e32 v158, 16, v189
	v_and_b32_e32 v159, 0xffff0000, v189
	v_pk_add_f32 v[196:197], v[156:157], v[158:159] neg_lo:[0,1] neg_hi:[0,1]
	v_cvt_pk_bf16_f32 v193, v196, v197
	v_lshlrev_b32_e32 v156, 16, v190
	v_and_b32_e32 v157, 0xffff0000, v190
	v_lshlrev_b32_e32 v158, 16, v194
	v_and_b32_e32 v159, 0xffff0000, v194
	v_pk_add_f32 v[156:157], v[156:157], v[158:159]
	v_pk_fma_f32 v[156:157], v[34:35], 0.5, v[156:157] op_sel_hi:[1,0,1]
	v_cvt_pk_bf16_f32 v190, v156, v157
	v_pk_fma_f32 v[198:199], v[156:157], v[156:157], v[198:199]
	v_lshlrev_b32_e32 v158, 16, v190
	v_and_b32_e32 v159, 0xffff0000, v190
	v_pk_add_f32 v[196:197], v[156:157], v[158:159] neg_lo:[0,1] neg_hi:[0,1]
	v_cvt_pk_bf16_f32 v194, v196, v197
	v_lshlrev_b32_e32 v156, 16, v191
	v_and_b32_e32 v157, 0xffff0000, v191
	v_lshlrev_b32_e32 v158, 16, v195
	v_and_b32_e32 v159, 0xffff0000, v195
	v_pk_add_f32 v[156:157], v[156:157], v[158:159]
	v_pk_fma_f32 v[156:157], v[36:37], 0.5, v[156:157] op_sel_hi:[1,0,1]
	v_cvt_pk_bf16_f32 v191, v156, v157
	v_pk_fma_f32 v[198:199], v[156:157], v[156:157], v[198:199]
	v_lshlrev_b32_e32 v158, 16, v191
	v_and_b32_e32 v159, 0xffff0000, v191
	v_pk_add_f32 v[196:197], v[156:157], v[158:159] neg_lo:[0,1] neg_hi:[0,1]
	v_cvt_pk_bf16_f32 v195, v196, v197
	global_store_dwordx4 v212, v[188:191], s[10:11] offset:256
	global_store_dwordx4 v212, v[192:195], s[6:7] offset:256
	v_add_f32_e32 v207, v198, v199
	s_waitcnt vmcnt(14)
; __device__ __forceinline__ unsigned pk2(float lo, float hi) { f32x2_t v = {lo, hi}; bf16x2_t b = __builtin_convertvector(v, bf16x2_t); return __builtin_bit_cast(unsigned, b); }
; __device__ __forceinline__ float bflo(unsigned u) { return __uint_as_float(u << 16); }
;     __device__ __forceinline__ void operator()(const f32x4 (&acc)[2][2][4][2], const Unit& u, int wr, int wc, int fr, int fq) const {
;     ...
;                 for (int bj = 0; bj < 2; ++bj) {
;                     const size_t off = (size_t)row * DM + col0 + bj * HALF;
;                     const u32x4 hh = *(const u32x4*)(HI + off), ll = *(const u32x4*)(LO + off);
;                     float hv[8] = {bflo(hh.x) + bflo(ll.x), bfhi(hh.x) + bfhi(ll.x), bflo(hh.y) + bflo(ll.y), bfhi(hh.y) + bfhi(ll.y),
;                                    bflo(hh.z) + bflo(ll.z), bfhi(hh.z) + bfhi(ll.z), bflo(hh.w) + bflo(ll.w), bfhi(hh.w) + bfhi(ll.w)};
;                     float av[8] = {acc[ai][bj][m][0][0], acc[ai][bj][m][0][1], acc[ai][bj][m][0][2], acc[ai][bj][m][0][3], acc[ai][bj][m][1][0], acc[ai][bj][m][1][1], acc[ai][bj][m][1][2], acc[ai][bj][m][1][3]};
;                     if (GATED) { const u32x4 pp = *(const u32x4*)(PP + off);
;                         const float pv[8] = {bflo(pp.x), bfhi(pp.x), bflo(pp.y), bfhi(pp.y), bflo(pp.z), bfhi(pp.z), bflo(pp.w), bfhi(pp.w)};
; #pragma unroll
;                         for (int e = 0; e < 8; ++e) av[e] = fast_sigmoid(av[e] * rs) * pv[e]; }
;                     else {
; #pragma unroll
;                         for (int e = 0; e < 8; ++e) av[e] *= alpha; }
;                     float lo[8];
; #pragma unroll
;                     for (int e = 0; e < 8; ++e) { hv[e] += av[e]; sq += hv[e] * hv[e]; }
;                     u32x4 wh; wh.x = pk2(hv[0], hv[1]); wh.y = pk2(hv[2], hv[3]); wh.z = pk2(hv[4], hv[5]); wh.w = pk2(hv[6], hv[7]);
;                     lo[0] = hv[0] - bflo(wh.x); lo[1] = hv[1] - bfhi(wh.x); lo[2] = hv[2] - bflo(wh.y); lo[3] = hv[3] - bfhi(wh.y);
;                     lo[4] = hv[4] - bflo(wh.z); lo[5] = hv[5] - bfhi(wh.z); lo[6] = hv[6] - bflo(wh.w); lo[7] = hv[7] - bfhi(wh.w);
;                     u32x4 wl; wl.x = pk2(lo[0], lo[1]); wl.y = pk2(lo[2], lo[3]); wl.z = pk2(lo[4], lo[5]); wl.w = pk2(lo[6], lo[7]);
;                     *(u32x4*)(HO + off) = wh; *(u32x4*)(LO + off) = wl;
	v_lshlrev_b32_e32 v156, 16, v140
	v_and_b32_e32 v157, 0xffff0000, v140
	v_lshlrev_b32_e32 v158, 16, v144
	v_and_b32_e32 v159, 0xffff0000, v144
	v_pk_add_f32 v[156:157], v[156:157], v[158:159]
	v_pk_fma_f32 v[156:157], v[30:31], 0.5, v[156:157] op_sel_hi:[1,0,1]
	v_cvt_pk_bf16_f32 v140, v156, v157
	v_pk_mul_f32 v[198:199], v[156:157], v[156:157]
	v_lshlrev_b32_e32 v158, 16, v140
	v_and_b32_e32 v159, 0xffff0000, v140
	v_pk_add_f32 v[196:197], v[156:157], v[158:159] neg_lo:[0,1] neg_hi:[0,1]
	v_cvt_pk_bf16_f32 v144, v196, v197
	v_lshlrev_b32_e32 v156, 16, v141
	v_and_b32_e32 v157, 0xffff0000, v141
	v_lshlrev_b32_e32 v158, 16, v145
	v_and_b32_e32 v159, 0xffff0000, v145
	v_pk_add_f32 v[156:157], v[156:157], v[158:159]
	v_pk_fma_f32 v[156:157], v[32:33], 0.5, v[156:157] op_sel_hi:[1,0,1]
	v_cvt_pk_bf16_f32 v141, v156, v157
	v_pk_fma_f32 v[198:199], v[156:157], v[156:157], v[198:199]
	v_lshlrev_b32_e32 v158, 16, v141
	v_and_b32_e32 v159, 0xffff0000, v141
	v_pk_add_f32 v[196:197], v[156:157], v[158:159] neg_lo:[0,1] neg_hi:[0,1]
	v_cvt_pk_bf16_f32 v145, v196, v197
	v_lshlrev_b32_e32 v156, 16, v142
	v_and_b32_e32 v157, 0xffff0000, v142
	v_lshlrev_b32_e32 v158, 16, v146
	v_and_b32_e32 v159, 0xffff0000, v146
	v_pk_add_f32 v[156:157], v[156:157], v[158:159]
	v_pk_fma_f32 v[156:157], v[26:27], 0.5, v[156:157] op_sel_hi:[1,0,1]
	v_cvt_pk_bf16_f32 v142, v156, v157
	v_pk_fma_f32 v[198:199], v[156:157], v[156:157], v[198:199]
	v_lshlrev_b32_e32 v158, 16, v142
	v_and_b32_e32 v159, 0xffff0000, v142
	v_pk_add_f32 v[196:197], v[156:157], v[158:159] neg_lo:[0,1] neg_hi:[0,1]
	v_cvt_pk_bf16_f32 v146, v196, v197
	v_lshlrev_b32_e32 v156, 16, v143
	v_and_b32_e32 v157, 0xffff0000, v143
	v_lshlrev_b32_e32 v158, 16, v147
	v_and_b32_e32 v159, 0xffff0000, v147
	v_pk_add_f32 v[156:157], v[156:157], v[158:159]
	v_pk_fma_f32 v[156:157], v[28:29], 0.5, v[156:157] op_sel_hi:[1,0,1]
	v_cvt_pk_bf16_f32 v143, v156, v157
	v_pk_fma_f32 v[198:199], v[156:157], v[156:157], v[198:199]
	v_lshlrev_b32_e32 v158, 16, v143
	v_and_b32_e32 v159, 0xffff0000, v143
	v_pk_add_f32 v[196:197], v[156:157], v[158:159] neg_lo:[0,1] neg_hi:[0,1]
	v_cvt_pk_bf16_f32 v147, v196, v197
	global_store_dwordx4 v210, v[140:143], s[10:11]
	global_store_dwordx4 v210, v[144:147], s[6:7]
	s_waitcnt vmcnt(14)
	v_lshlrev_b32_e32 v156, 16, v148
	v_and_b32_e32 v157, 0xffff0000, v148
	v_lshlrev_b32_e32 v158, 16, v152
	v_and_b32_e32 v159, 0xffff0000, v152
	v_pk_add_f32 v[156:157], v[156:157], v[158:159]
	v_pk_fma_f32 v[156:157], v[22:23], 0.5, v[156:157] op_sel_hi:[1,0,1]
	v_cvt_pk_bf16_f32 v148, v156, v157
	v_pk_fma_f32 v[198:199], v[156:157], v[156:157], v[198:199]
	v_lshlrev_b32_e32 v158, 16, v148
	v_and_b32_e32 v159, 0xffff0000, v148
	v_pk_add_f32 v[196:197], v[156:157], v[158:159] neg_lo:[0,1] neg_hi:[0,1]
	v_cvt_pk_bf16_f32 v152, v196, v197
	v_lshlrev_b32_e32 v156, 16, v149
	v_and_b32_e32 v157, 0xffff0000, v149
	v_lshlrev_b32_e32 v158, 16, v153
	v_and_b32_e32 v159, 0xffff0000, v153
	v_pk_add_f32 v[156:157], v[156:157], v[158:159]
	v_pk_fma_f32 v[156:157], v[24:25], 0.5, v[156:157] op_sel_hi:[1,0,1]
	v_cvt_pk_bf16_f32 v149, v156, v157
	v_pk_fma_f32 v[198:199], v[156:157], v[156:157], v[198:199]
	v_lshlrev_b32_e32 v158, 16, v149
	v_and_b32_e32 v159, 0xffff0000, v149
	v_pk_add_f32 v[196:197], v[156:157], v[158:159] neg_lo:[0,1] neg_hi:[0,1]
	v_cvt_pk_bf16_f32 v153, v196, v197
	v_lshlrev_b32_e32 v156, 16, v150
	v_and_b32_e32 v157, 0xffff0000, v150
	v_lshlrev_b32_e32 v158, 16, v154
	v_and_b32_e32 v159, 0xffff0000, v154
	v_pk_add_f32 v[156:157], v[156:157], v[158:159]
	v_pk_fma_f32 v[156:157], v[18:19], 0.5, v[156:157] op_sel_hi:[1,0,1]
	v_cvt_pk_bf16_f32 v150, v156, v157
	v_pk_fma_f32 v[198:199], v[156:157], v[156:157], v[198:199]
	v_lshlrev_b32_e32 v158, 16, v150
	v_and_b32_e32 v159, 0xffff0000, v150
	v_pk_add_f32 v[196:197], v[156:157], v[158:159] neg_lo:[0,1] neg_hi:[0,1]
	v_cvt_pk_bf16_f32 v154, v196, v197
	v_lshlrev_b32_e32 v156, 16, v151
	v_and_b32_e32 v157, 0xffff0000, v151
	v_lshlrev_b32_e32 v158, 16, v155
	v_and_b32_e32 v159, 0xffff0000, v155
	v_pk_add_f32 v[156:157], v[156:157], v[158:159]
	v_pk_fma_f32 v[156:157], v[20:21], 0.5, v[156:157] op_sel_hi:[1,0,1]
	v_cvt_pk_bf16_f32 v151, v156, v157
	v_pk_fma_f32 v[198:199], v[156:157], v[156:157], v[198:199]
	v_lshlrev_b32_e32 v158, 16, v151
	v_and_b32_e32 v159, 0xffff0000, v151
	v_pk_add_f32 v[196:197], v[156:157], v[158:159] neg_lo:[0,1] neg_hi:[0,1]
	v_cvt_pk_bf16_f32 v155, v196, v197
	global_store_dwordx4 v210, v[148:151], s[10:11] offset:256
	global_store_dwordx4 v210, v[152:155], s[6:7] offset:256
	v_add_f32_e32 v208, v198, v199
	s_waitcnt vmcnt(10)
; __device__ __forceinline__ float bflo(unsigned u) { return __uint_as_float(u << 16); }
;     __device__ __forceinline__ void operator()(const f32x4 (&acc)[2][2][4][2], const Unit& u, int wr, int wc, int fr, int fq) const {
;     ...
;                 for (int bj = 0; bj < 2; ++bj) {
;                     const size_t off = (size_t)row * DM + col0 + bj * HALF;
;                     const u32x4 hh = *(const u32x4*)(HI + off), ll = *(const u32x4*)(LO + off);
;                     float hv[8] = {bflo(hh.x) + bflo(ll.x), bfhi(hh.x) + bfhi(ll.x), bflo(hh.y) + bflo(ll.y), bfhi(hh.y) + bfhi(ll.y),
;                                    bflo(hh.z) + bflo(ll.z), bfhi(hh.z) + bfhi(ll.z), bflo(hh.w) + bflo(ll.w), bfhi(hh.w) + bfhi(ll.w)};
;                     float av[8] = {acc[ai][bj][m][0][0], acc[ai][bj][m][0][1], acc[ai][bj][m][0][2], acc[ai][bj][m][0][3], acc[ai][bj][m][1][0], acc[ai][bj][m][1][1], acc[ai][bj][m][1][2], acc[ai][bj][m][1][3]};
;                     if (GATED) { const u32x4 pp = *(const u32x4*)(PP + off);
;                         const float pv[8] = {bflo(pp.x), bfhi(pp.x), bflo(pp.y), bfhi(pp.y), bflo(pp.z), bfhi(pp.z), bflo(pp.w), bfhi(pp.w)};
; #pragma unroll
;                         for (int e = 0; e < 8; ++e) av[e] = fast_sigmoid(av[e] * rs) * pv[e]; }
;                     else {
; #pragma unroll
;                         for (int e = 0; e < 8; ++e) av[e] *= alpha; }
;                     float lo[8];
; #pragma unroll
;                     for (int e = 0; e < 8; ++e) { hv[e] += av[e]; sq += hv[e] * hv[e]; }
;                     u32x4 wh; wh.x = pk2(hv[0], hv[1]); wh.y = pk2(hv[2], hv[3]); wh.z = pk2(hv[4], hv[5]); wh.w = pk2(hv[6], hv[7]);
;                     lo[0] = hv[0] - bflo(wh.x); lo[1] = hv[1] - bfhi(wh.x); lo[2] = hv[2] - bflo(wh.y); lo[3] = hv[3] - bfhi(wh.y);
;                     lo[4] = hv[4] - bflo(wh.z); lo[5] = hv[5] - bfhi(wh.z); lo[6] = hv[6] - bflo(wh.w); lo[7] = hv[7] - bfhi(wh.w);
;                     u32x4 wl; wl.x = pk2(lo[0], lo[1]); wl.y = pk2(lo[2], lo[3]); wl.z = pk2(lo[4], lo[5]); wl.w = pk2(lo[6], lo[7]);
;                     *(u32x4*)(HO + off) = wh; *(u32x4*)(LO + off) = wl;
;                 }
;                 sq += __shfl_xor(sq, 16); sq += __shfl_xor(sq, 32);
;                 if (fq == 0) ssq_out[(size_t)row * 16 + 4 * u.pn + wc] = sq;
	v_lshlrev_b32_e32 v156, 16, v164
	v_and_b32_e32 v157, 0xffff0000, v164
	v_lshlrev_b32_e32 v158, 16, v168
	v_and_b32_e32 v159, 0xffff0000, v168
	v_pk_add_f32 v[156:157], v[156:157], v[158:159]
	v_pk_fma_f32 v[156:157], v[14:15], 0.5, v[156:157] op_sel_hi:[1,0,1]
	v_cvt_pk_bf16_f32 v164, v156, v157
	v_pk_mul_f32 v[198:199], v[156:157], v[156:157]
	v_lshlrev_b32_e32 v158, 16, v164
	v_and_b32_e32 v159, 0xffff0000, v164
	v_pk_add_f32 v[196:197], v[156:157], v[158:159] neg_lo:[0,1] neg_hi:[0,1]
	v_cvt_pk_bf16_f32 v168, v196, v197
	v_lshlrev_b32_e32 v156, 16, v165
	v_and_b32_e32 v157, 0xffff0000, v165
	v_lshlrev_b32_e32 v158, 16, v169
	v_and_b32_e32 v159, 0xffff0000, v169
	v_pk_add_f32 v[156:157], v[156:157], v[158:159]
	v_pk_fma_f32 v[156:157], v[16:17], 0.5, v[156:157] op_sel_hi:[1,0,1]
	v_cvt_pk_bf16_f32 v165, v156, v157
	v_pk_fma_f32 v[198:199], v[156:157], v[156:157], v[198:199]
	v_lshlrev_b32_e32 v158, 16, v165
	v_and_b32_e32 v159, 0xffff0000, v165
	v_pk_add_f32 v[196:197], v[156:157], v[158:159] neg_lo:[0,1] neg_hi:[0,1]
	v_cvt_pk_bf16_f32 v169, v196, v197
	v_lshlrev_b32_e32 v156, 16, v166
	v_and_b32_e32 v157, 0xffff0000, v166
	v_lshlrev_b32_e32 v158, 16, v170
	v_and_b32_e32 v159, 0xffff0000, v170
	v_pk_add_f32 v[156:157], v[156:157], v[158:159]
	v_pk_fma_f32 v[156:157], v[10:11], 0.5, v[156:157] op_sel_hi:[1,0,1]
	v_cvt_pk_bf16_f32 v166, v156, v157
	v_pk_fma_f32 v[198:199], v[156:157], v[156:157], v[198:199]
	v_lshlrev_b32_e32 v158, 16, v166
	v_and_b32_e32 v159, 0xffff0000, v166
	v_pk_add_f32 v[196:197], v[156:157], v[158:159] neg_lo:[0,1] neg_hi:[0,1]
	v_cvt_pk_bf16_f32 v170, v196, v197
	v_lshlrev_b32_e32 v156, 16, v167
	v_and_b32_e32 v157, 0xffff0000, v167
	v_lshlrev_b32_e32 v158, 16, v171
	v_and_b32_e32 v159, 0xffff0000, v171
	v_pk_add_f32 v[156:157], v[156:157], v[158:159]
	v_pk_fma_f32 v[156:157], v[12:13], 0.5, v[156:157] op_sel_hi:[1,0,1]
	v_cvt_pk_bf16_f32 v167, v156, v157
	v_pk_fma_f32 v[198:199], v[156:157], v[156:157], v[198:199]
	v_lshlrev_b32_e32 v158, 16, v167
	v_and_b32_e32 v159, 0xffff0000, v167
	v_pk_add_f32 v[196:197], v[156:157], v[158:159] neg_lo:[0,1] neg_hi:[0,1]
	v_cvt_pk_bf16_f32 v171, v196, v197
	global_store_dwordx4 v211, v[164:167], s[10:11]
	global_store_dwordx4 v211, v[168:171], s[6:7]
	s_waitcnt vmcnt(10)
	v_lshlrev_b32_e32 v156, 16, v172
	v_and_b32_e32 v157, 0xffff0000, v172
	v_lshlrev_b32_e32 v158, 16, v176
	v_and_b32_e32 v159, 0xffff0000, v176
	v_pk_add_f32 v[156:157], v[156:157], v[158:159]
	v_pk_fma_f32 v[156:157], v[6:7], 0.5, v[156:157] op_sel_hi:[1,0,1]
	v_cvt_pk_bf16_f32 v172, v156, v157
	v_pk_fma_f32 v[198:199], v[156:157], v[156:157], v[198:199]
	v_lshlrev_b32_e32 v158, 16, v172
	v_and_b32_e32 v159, 0xffff0000, v172
	v_pk_add_f32 v[196:197], v[156:157], v[158:159] neg_lo:[0,1] neg_hi:[0,1]
	v_cvt_pk_bf16_f32 v176, v196, v197
	v_lshlrev_b32_e32 v156, 16, v173
	v_and_b32_e32 v157, 0xffff0000, v173
	v_lshlrev_b32_e32 v158, 16, v177
	v_and_b32_e32 v159, 0xffff0000, v177
	v_pk_add_f32 v[156:157], v[156:157], v[158:159]
	v_pk_fma_f32 v[156:157], v[8:9], 0.5, v[156:157] op_sel_hi:[1,0,1]
	v_cvt_pk_bf16_f32 v173, v156, v157
	v_pk_fma_f32 v[198:199], v[156:157], v[156:157], v[198:199]
	v_lshlrev_b32_e32 v158, 16, v173
	v_and_b32_e32 v159, 0xffff0000, v173
	v_pk_add_f32 v[196:197], v[156:157], v[158:159] neg_lo:[0,1] neg_hi:[0,1]
	v_cvt_pk_bf16_f32 v177, v196, v197
	v_lshlrev_b32_e32 v156, 16, v174
	v_and_b32_e32 v157, 0xffff0000, v174
	v_lshlrev_b32_e32 v158, 16, v178
	v_and_b32_e32 v159, 0xffff0000, v178
	v_pk_add_f32 v[156:157], v[156:157], v[158:159]
	v_pk_fma_f32 v[156:157], v[2:3], 0.5, v[156:157] op_sel_hi:[1,0,1]
	v_cvt_pk_bf16_f32 v174, v156, v157
	v_pk_fma_f32 v[198:199], v[156:157], v[156:157], v[198:199]
	v_lshlrev_b32_e32 v158, 16, v174
	v_and_b32_e32 v159, 0xffff0000, v174
	v_pk_add_f32 v[196:197], v[156:157], v[158:159] neg_lo:[0,1] neg_hi:[0,1]
	v_cvt_pk_bf16_f32 v178, v196, v197
	v_lshlrev_b32_e32 v156, 16, v175
	v_and_b32_e32 v157, 0xffff0000, v175
	v_lshlrev_b32_e32 v158, 16, v179
	v_and_b32_e32 v159, 0xffff0000, v179
	v_pk_add_f32 v[156:157], v[156:157], v[158:159]
	v_pk_fma_f32 v[156:157], v[4:5], 0.5, v[156:157] op_sel_hi:[1,0,1]
	v_cvt_pk_bf16_f32 v175, v156, v157
	v_pk_fma_f32 v[198:199], v[156:157], v[156:157], v[198:199]
	v_lshlrev_b32_e32 v158, 16, v175
	v_and_b32_e32 v159, 0xffff0000, v175
	v_pk_add_f32 v[196:197], v[156:157], v[158:159] neg_lo:[0,1] neg_hi:[0,1]
	v_cvt_pk_bf16_f32 v179, v196, v197
	global_store_dwordx4 v211, v[172:175], s[10:11] offset:256
	global_store_dwordx4 v211, v[176:179], s[6:7] offset:256
	v_add_f32_e32 v209, v198, v199
	ds_bpermute_b32 v140, v214, v200
	ds_bpermute_b32 v141, v214, v201
	ds_bpermute_b32 v142, v214, v202
	ds_bpermute_b32 v143, v214, v203
	ds_bpermute_b32 v144, v214, v206
	ds_bpermute_b32 v145, v214, v207
	ds_bpermute_b32 v146, v214, v208
	ds_bpermute_b32 v147, v214, v209
	v_readlane_b32 s52, v250, 35
	v_readlane_b32 s53, v250, 36
	s_waitcnt lgkmcnt(0)
	v_add_f32_e32 v200, v200, v140
	v_add_f32_e32 v201, v201, v141
	v_add_f32_e32 v202, v202, v142
	v_add_f32_e32 v203, v203, v143
	v_add_f32_e32 v206, v206, v144
	v_add_f32_e32 v207, v207, v145
	v_add_f32_e32 v208, v208, v146
	v_add_f32_e32 v209, v209, v147
	ds_bpermute_b32 v140, v215, v200
	ds_bpermute_b32 v141, v215, v201
	ds_bpermute_b32 v142, v215, v202
	ds_bpermute_b32 v143, v215, v203
	ds_bpermute_b32 v144, v215, v206
	ds_bpermute_b32 v145, v215, v207
	ds_bpermute_b32 v146, v215, v208
	ds_bpermute_b32 v147, v215, v209
	s_waitcnt lgkmcnt(0)
	v_add_f32_e32 v200, v200, v140
	v_add_f32_e32 v201, v201, v141
	v_add_f32_e32 v202, v202, v142
	v_add_f32_e32 v203, v203, v143
	v_add_f32_e32 v206, v206, v144
	v_add_f32_e32 v207, v207, v145
	v_add_f32_e32 v208, v208, v146
	v_add_f32_e32 v209, v209, v147
	s_and_saveexec_b64 s[12:13], s[44:45]
	s_cbranch_execz .Lepir_f1d_skip
	global_store_dword v216, v200, s[52:53]
	global_store_dword v216, v201, s[52:53] offset:1024
	global_store_dword v216, v202, s[52:53] offset:2048
	global_store_dword v216, v203, s[52:53] offset:3072
	global_store_dword v217, v206, s[52:53]
	global_store_dword v217, v207, s[52:53] offset:1024
	global_store_dword v217, v208, s[52:53] offset:2048
	global_store_dword v217, v209, s[52:53] offset:3072

;     __device__ __forceinline__ void operator()(const f32x4 (&acc)[2][2][4][2], const Unit& u, int wr, int wc, int fr, int fq) const {
;     ...
;                     const size_t off = (size_t)row * DM + col0 + bj * HALF;
;                     const u32x4 hh = *(const u32x4*)(HI + off), ll = *(const u32x4*)(LO + off);
.LBB0_1068:
	s_cmp_eq_u32 s53, 6
	s_cbranch_scc0 .Lpre_wout_skip
	v_readlane_b32 s100, v254, 18
	v_readlane_b32 s101, v254, 19
	s_mov_b64 s[98:99], s[14:15]
	v_lshl_add_u32 v243, s40, 8, v160
	v_lshl_or_b32 v246, s4, 8, v162
	v_lshl_add_u32 v243, v243, 10, v246
	v_lshlrev_b32_e32 v243, 1, v243
	s_nop 1
	global_load_dwordx4 v[226:229], v243, s[100:101]
	global_load_dwordx4 v[230:233], v243, s[98:99]
	global_load_dwordx4 v[234:237], v243, s[100:101] offset:256
	global_load_dwordx4 v[242:245], v243, s[98:99] offset:256

; __device__ __forceinline__ float bflo(unsigned u) { return __uint_as_float(u << 16); }
;     __device__ __forceinline__ void operator()(const f32x4 (&acc)[2][2][4][2], const Unit& u, int wr, int wc, int fr, int fq) const {
;     ...
;                 const int row = row0 + ai * HALF + m * 16;
;                 float rs = 0.f; if (GATED) rs = rsqrtf(row_ssq(ssq_in, 16, 4, row, fq) * (1.f / 1024.f) + EPS);
;                 float sq = 0.f;
; #pragma unroll
;                 for (int bj = 0; bj < 2; ++bj) {
;                     const size_t off = (size_t)row * DM + col0 + bj * HALF;
;                     const u32x4 hh = *(const u32x4*)(HI + off), ll = *(const u32x4*)(LO + off);
;                     float hv[8] = {bflo(hh.x) + bflo(ll.x), bfhi(hh.x) + bfhi(ll.x), bflo(hh.y) + bflo(ll.y), bfhi(hh.y) + bfhi(ll.y),
;                                    bflo(hh.z) + bflo(ll.z), bfhi(hh.z) + bfhi(ll.z), bflo(hh.w) + bflo(ll.w), bfhi(hh.w) + bfhi(ll.w)};
;                     float av[8] = {acc[ai][bj][m][0][0], acc[ai][bj][m][0][1], acc[ai][bj][m][0][2], acc[ai][bj][m][0][3], acc[ai][bj][m][1][0], acc[ai][bj][m][1][1], acc[ai][bj][m][1][2], acc[ai][bj][m][1][3]};
;                     if (GATED) { const u32x4 pp = *(const u32x4*)(PP + off);
;                         const float pv[8] = {bflo(pp.x), bfhi(pp.x), bflo(pp.y), bfhi(pp.y), bflo(pp.z), bfhi(pp.z), bflo(pp.w), bfhi(pp.w)};
; #pragma unroll
;                         for (int e = 0; e < 8; ++e) av[e] = fast_sigmoid(av[e] * rs) * pv[e]; }
;                     else {
; #pragma unroll
;                         for (int e = 0; e < 8; ++e) av[e] *= alpha; }
;                     float lo[8];
; #pragma unroll
;                     for (int e = 0; e < 8; ++e) { hv[e] += av[e]; sq += hv[e] * hv[e]; }
;                     u32x4 wh; wh.x = pk2(hv[0], hv[1]); wh.y = pk2(hv[2], hv[3]); wh.z = pk2(hv[4], hv[5]); wh.w = pk2(hv[6], hv[7]);
;                     lo[0] = hv[0] - bflo(wh.x); lo[1] = hv[1] - bfhi(wh.x); lo[2] = hv[2] - bflo(wh.y); lo[3] = hv[3] - bfhi(wh.y);
;                     lo[4] = hv[4] - bflo(wh.z); lo[5] = hv[5] - bfhi(wh.z); lo[6] = hv[6] - bflo(wh.w); lo[7] = hv[7] - bfhi(wh.w);
;                     u32x4 wl; wl.x = pk2(lo[0], lo[1]); wl.y = pk2(lo[2], lo[3]); wl.z = pk2(lo[4], lo[5]); wl.w = pk2(lo[6], lo[7]);
;                     *(u32x4*)(HO + off) = wh; *(u32x4*)(LO + off) = wl;
.LBB0_1071:
	v_and_b32_e32 v158, 64, v241
	v_xor_b32_e32 v214, 16, v241
	v_add_u32_e32 v158, 64, v158
	v_cmp_lt_i32_e32 vcc, v214, v158
	v_lshl_add_u32 v156, s40, 8, v160
	v_lshl_or_b32 v157, s4, 8, v162
	v_cndmask_b32_e32 v214, v241, v214, vcc
	v_lshlrev_b32_e32 v214, 2, v214
	v_xor_b32_e32 v215, 32, v241
	v_cmp_lt_i32_e32 vcc, v215, v158
	v_readlane_b32 s10, v254, 18
	v_readlane_b32 s11, v254, 19
	s_nop 1
	v_cndmask_b32_e32 v215, v241, v215, vcc
	v_lshlrev_b32_e32 v215, 2, v215
	v_lshl_add_u32 v213, v156, 10, v157
	v_lshlrev_b32_e32 v213, 1, v213
	s_lshl_b32 s40, s4, 4
	s_lshl_b32 s0, s48, 2
	s_add_i32 s40, s40, s0
	v_lshlrev_b32_e32 v216, 6, v156
	v_add_u32_e32 v216, s40, v216
	v_add_u32_e32 v217, 0x2000, v216
	v_readlane_b32 s30, v251, 4
	v_readlane_b32 s31, v251, 5
	s_nop 1
	v_add_u32_e32 v211, 0x8000, v213
	global_load_dwordx4 v[164:167], v211, s[10:11]
	global_load_dwordx4 v[168:171], v211, s[14:15]
	global_load_dwordx4 v[172:175], v211, s[10:11] offset:256
	global_load_dwordx4 v[176:179], v211, s[14:15] offset:256
	v_add_u32_e32 v212, 0x10000, v213
	global_load_dwordx4 v[180:183], v212, s[10:11]
	global_load_dwordx4 v[184:187], v212, s[14:15]
	global_load_dwordx4 v[188:191], v212, s[10:11] offset:256
	global_load_dwordx4 v[192:195], v212, s[14:15] offset:256
	v_add_u32_e32 v210, 0x18000, v213
	global_load_dwordx4 v[140:143], v210, s[10:11]
	global_load_dwordx4 v[144:147], v210, s[14:15]
	global_load_dwordx4 v[148:151], v210, s[10:11] offset:256
	global_load_dwordx4 v[152:155], v210, s[14:15] offset:256
	s_waitcnt vmcnt(12)
	v_lshlrev_b32_e32 v156, 16, v226
	v_and_b32_e32 v157, 0xffff0000, v226
	v_lshlrev_b32_e32 v158, 16, v230
	v_and_b32_e32 v159, 0xffff0000, v230
	v_pk_add_f32 v[156:157], v[156:157], v[158:159]
	v_pk_add_f32 v[156:157], v[126:127], v[156:157]
	v_cvt_pk_bf16_f32 v226, v156, v157
	v_pk_mul_f32 v[198:199], v[156:157], v[156:157]
	v_lshlrev_b32_e32 v158, 16, v226
	v_and_b32_e32 v159, 0xffff0000, v226
	v_pk_add_f32 v[196:197], v[156:157], v[158:159] neg_lo:[0,1] neg_hi:[0,1]
	v_cvt_pk_bf16_f32 v230, v196, v197
	v_lshlrev_b32_e32 v156, 16, v227
	v_and_b32_e32 v157, 0xffff0000, v227
	v_lshlrev_b32_e32 v158, 16, v231
	v_and_b32_e32 v159, 0xffff0000, v231
	v_pk_add_f32 v[156:157], v[156:157], v[158:159]
	v_pk_add_f32 v[156:157], v[128:129], v[156:157]
	v_cvt_pk_bf16_f32 v227, v156, v157
	v_pk_fma_f32 v[198:199], v[156:157], v[156:157], v[198:199]
	v_lshlrev_b32_e32 v158, 16, v227
	v_and_b32_e32 v159, 0xffff0000, v227
	v_pk_add_f32 v[196:197], v[156:157], v[158:159] neg_lo:[0,1] neg_hi:[0,1]
	v_cvt_pk_bf16_f32 v231, v196, v197
	v_lshlrev_b32_e32 v156, 16, v228
	v_and_b32_e32 v157, 0xffff0000, v228
	v_lshlrev_b32_e32 v158, 16, v232
	v_and_b32_e32 v159, 0xffff0000, v232
	v_pk_add_f32 v[156:157], v[156:157], v[158:159]
	v_pk_add_f32 v[156:157], v[122:123], v[156:157]
	v_cvt_pk_bf16_f32 v228, v156, v157
	v_pk_fma_f32 v[198:199], v[156:157], v[156:157], v[198:199]
	v_lshlrev_b32_e32 v158, 16, v228
	v_and_b32_e32 v159, 0xffff0000, v228
	v_pk_add_f32 v[196:197], v[156:157], v[158:159] neg_lo:[0,1] neg_hi:[0,1]
	v_cvt_pk_bf16_f32 v232, v196, v197
	v_lshlrev_b32_e32 v156, 16, v229
	v_and_b32_e32 v157, 0xffff0000, v229
	v_lshlrev_b32_e32 v158, 16, v233
	v_and_b32_e32 v159, 0xffff0000, v233
	v_pk_add_f32 v[156:157], v[156:157], v[158:159]
	v_pk_add_f32 v[156:157], v[124:125], v[156:157]
	v_cvt_pk_bf16_f32 v229, v156, v157
	v_pk_fma_f32 v[198:199], v[156:157], v[156:157], v[198:199]
	v_lshlrev_b32_e32 v158, 16, v229
	v_and_b32_e32 v159, 0xffff0000, v229
	v_pk_add_f32 v[196:197], v[156:157], v[158:159] neg_lo:[0,1] neg_hi:[0,1]
	v_cvt_pk_bf16_f32 v233, v196, v197
	global_store_dwordx4 v213, v[226:229], s[10:11]
	global_store_dwordx4 v213, v[230:233], s[14:15]
	v_lshlrev_b32_e32 v156, 16, v234
	v_and_b32_e32 v157, 0xffff0000, v234
	v_lshlrev_b32_e32 v158, 16, v242
	v_and_b32_e32 v159, 0xffff0000, v242
	v_pk_add_f32 v[156:157], v[156:157], v[158:159]
	v_pk_add_f32 v[156:157], v[118:119], v[156:157]
	v_cvt_pk_bf16_f32 v234, v156, v157
	v_pk_fma_f32 v[198:199], v[156:157], v[156:157], v[198:199]
	v_lshlrev_b32_e32 v158, 16, v234
	v_and_b32_e32 v159, 0xffff0000, v234
	v_pk_add_f32 v[196:197], v[156:157], v[158:159] neg_lo:[0,1] neg_hi:[0,1]
	v_cvt_pk_bf16_f32 v242, v196, v197
	v_lshlrev_b32_e32 v156, 16, v235
	v_and_b32_e32 v157, 0xffff0000, v235
	v_lshlrev_b32_e32 v158, 16, v243
	v_and_b32_e32 v159, 0xffff0000, v243
	v_pk_add_f32 v[156:157], v[156:157], v[158:159]
	v_pk_add_f32 v[156:157], v[120:121], v[156:157]
	v_cvt_pk_bf16_f32 v235, v156, v157
	v_pk_fma_f32 v[198:199], v[156:157], v[156:157], v[198:199]
	v_lshlrev_b32_e32 v158, 16, v235
	v_and_b32_e32 v159, 0xffff0000, v235
	v_pk_add_f32 v[196:197], v[156:157], v[158:159] neg_lo:[0,1] neg_hi:[0,1]
	v_cvt_pk_bf16_f32 v243, v196, v197
	v_lshlrev_b32_e32 v156, 16, v236
	v_and_b32_e32 v157, 0xffff0000, v236
	v_lshlrev_b32_e32 v158, 16, v244
	v_and_b32_e32 v159, 0xffff0000, v244
	v_pk_add_f32 v[156:157], v[156:157], v[158:159]
	v_pk_add_f32 v[156:157], v[114:115], v[156:157]
	v_cvt_pk_bf16_f32 v236, v156, v157
	v_pk_fma_f32 v[198:199], v[156:157], v[156:157], v[198:199]
	v_lshlrev_b32_e32 v158, 16, v236
	v_and_b32_e32 v159, 0xffff0000, v236
	v_pk_add_f32 v[196:197], v[156:157], v[158:159] neg_lo:[0,1] neg_hi:[0,1]
	v_cvt_pk_bf16_f32 v244, v196, v197
	v_lshlrev_b32_e32 v156, 16, v237
	v_and_b32_e32 v157, 0xffff0000, v237
	v_lshlrev_b32_e32 v158, 16, v245
	v_and_b32_e32 v159, 0xffff0000, v245
	v_pk_add_f32 v[156:157], v[156:157], v[158:159]
	v_pk_add_f32 v[156:157], v[116:117], v[156:157]
	v_cvt_pk_bf16_f32 v237, v156, v157
	v_pk_fma_f32 v[198:199], v[156:157], v[156:157], v[198:199]
	v_lshlrev_b32_e32 v158, 16, v237
	v_and_b32_e32 v159, 0xffff0000, v237
	v_pk_add_f32 v[196:197], v[156:157], v[158:159] neg_lo:[0,1] neg_hi:[0,1]
	v_cvt_pk_bf16_f32 v245, v196, v197
	global_store_dwordx4 v213, v[234:237], s[10:11] offset:256
	global_store_dwordx4 v213, v[242:245], s[14:15] offset:256
	v_add_f32_e32 v200, v198, v199
	s_waitcnt vmcnt(14)
; __device__ __forceinline__ unsigned pk2(float lo, float hi) { f32x2_t v = {lo, hi}; bf16x2_t b = __builtin_convertvector(v, bf16x2_t); return __builtin_bit_cast(unsigned, b); }
; __device__ __forceinline__ float bflo(unsigned u) { return __uint_as_float(u << 16); }
;     __device__ __forceinline__ void operator()(const f32x4 (&acc)[2][2][4][2], const Unit& u, int wr, int wc, int fr, int fq) const {
;     ...
;                 for (int bj = 0; bj < 2; ++bj) {
;                     const size_t off = (size_t)row * DM + col0 + bj * HALF;
;                     const u32x4 hh = *(const u32x4*)(HI + off), ll = *(const u32x4*)(LO + off);
;                     float hv[8] = {bflo(hh.x) + bflo(ll.x), bfhi(hh.x) + bfhi(ll.x), bflo(hh.y) + bflo(ll.y), bfhi(hh.y) + bfhi(ll.y),
;                                    bflo(hh.z) + bflo(ll.z), bfhi(hh.z) + bfhi(ll.z), bflo(hh.w) + bflo(ll.w), bfhi(hh.w) + bfhi(ll.w)};
;                     float av[8] = {acc[ai][bj][m][0][0], acc[ai][bj][m][0][1], acc[ai][bj][m][0][2], acc[ai][bj][m][0][3], acc[ai][bj][m][1][0], acc[ai][bj][m][1][1], acc[ai][bj][m][1][2], acc[ai][bj][m][1][3]};
;                     if (GATED) { const u32x4 pp = *(const u32x4*)(PP + off);
;                         const float pv[8] = {bflo(pp.x), bfhi(pp.x), bflo(pp.y), bfhi(pp.y), bflo(pp.z), bfhi(pp.z), bflo(pp.w), bfhi(pp.w)};
; #pragma unroll
;                         for (int e = 0; e < 8; ++e) av[e] = fast_sigmoid(av[e] * rs) * pv[e]; }
;                     else {
; #pragma unroll
;                         for (int e = 0; e < 8; ++e) av[e] *= alpha; }
;                     float lo[8];
; #pragma unroll
;                     for (int e = 0; e < 8; ++e) { hv[e] += av[e]; sq += hv[e] * hv[e]; }
;                     u32x4 wh; wh.x = pk2(hv[0], hv[1]); wh.y = pk2(hv[2], hv[3]); wh.z = pk2(hv[4], hv[5]); wh.w = pk2(hv[6], hv[7]);
;                     lo[0] = hv[0] - bflo(wh.x); lo[1] = hv[1] - bfhi(wh.x); lo[2] = hv[2] - bflo(wh.y); lo[3] = hv[3] - bfhi(wh.y);
;                     lo[4] = hv[4] - bflo(wh.z); lo[5] = hv[5] - bfhi(wh.z); lo[6] = hv[6] - bflo(wh.w); lo[7] = hv[7] - bfhi(wh.w);
;                     u32x4 wl; wl.x = pk2(lo[0], lo[1]); wl.y = pk2(lo[2], lo[3]); wl.z = pk2(lo[4], lo[5]); wl.w = pk2(lo[6], lo[7]);
;                     *(u32x4*)(HO + off) = wh; *(u32x4*)(LO + off) = wl;
	v_lshlrev_b32_e32 v156, 16, v164
	v_and_b32_e32 v157, 0xffff0000, v164
	v_lshlrev_b32_e32 v158, 16, v168
	v_and_b32_e32 v159, 0xffff0000, v168
	v_pk_add_f32 v[156:157], v[156:157], v[158:159]
	v_pk_add_f32 v[156:157], v[110:111], v[156:157]
	v_cvt_pk_bf16_f32 v164, v156, v157
	v_pk_mul_f32 v[198:199], v[156:157], v[156:157]
	v_lshlrev_b32_e32 v158, 16, v164
	v_and_b32_e32 v159, 0xffff0000, v164
	v_pk_add_f32 v[196:197], v[156:157], v[158:159] neg_lo:[0,1] neg_hi:[0,1]
	v_cvt_pk_bf16_f32 v168, v196, v197
	v_lshlrev_b32_e32 v156, 16, v165
	v_and_b32_e32 v157, 0xffff0000, v165
	v_lshlrev_b32_e32 v158, 16, v169
	v_and_b32_e32 v159, 0xffff0000, v169
	v_pk_add_f32 v[156:157], v[156:157], v[158:159]
	v_pk_add_f32 v[156:157], v[112:113], v[156:157]
	v_cvt_pk_bf16_f32 v165, v156, v157
	v_pk_fma_f32 v[198:199], v[156:157], v[156:157], v[198:199]
	v_lshlrev_b32_e32 v158, 16, v165
	v_and_b32_e32 v159, 0xffff0000, v165
	v_pk_add_f32 v[196:197], v[156:157], v[158:159] neg_lo:[0,1] neg_hi:[0,1]
	v_cvt_pk_bf16_f32 v169, v196, v197
	v_lshlrev_b32_e32 v156, 16, v166
	v_and_b32_e32 v157, 0xffff0000, v166
	v_lshlrev_b32_e32 v158, 16, v170
	v_and_b32_e32 v159, 0xffff0000, v170
	v_pk_add_f32 v[156:157], v[156:157], v[158:159]
	v_pk_add_f32 v[156:157], v[106:107], v[156:157]
	v_cvt_pk_bf16_f32 v166, v156, v157
	v_pk_fma_f32 v[198:199], v[156:157], v[156:157], v[198:199]
	v_lshlrev_b32_e32 v158, 16, v166
	v_and_b32_e32 v159, 0xffff0000, v166
	v_pk_add_f32 v[196:197], v[156:157], v[158:159] neg_lo:[0,1] neg_hi:[0,1]
	v_cvt_pk_bf16_f32 v170, v196, v197
	v_lshlrev_b32_e32 v156, 16, v167
	v_and_b32_e32 v157, 0xffff0000, v167
	v_lshlrev_b32_e32 v158, 16, v171
	v_and_b32_e32 v159, 0xffff0000, v171
	v_pk_add_f32 v[156:157], v[156:157], v[158:159]
	v_pk_add_f32 v[156:157], v[108:109], v[156:157]
	v_cvt_pk_bf16_f32 v167, v156, v157
	v_pk_fma_f32 v[198:199], v[156:157], v[156:157], v[198:199]
	v_lshlrev_b32_e32 v158, 16, v167
	v_and_b32_e32 v159, 0xffff0000, v167
	v_pk_add_f32 v[196:197], v[156:157], v[158:159] neg_lo:[0,1] neg_hi:[0,1]
	v_cvt_pk_bf16_f32 v171, v196, v197
	global_store_dwordx4 v211, v[164:167], s[10:11]
	global_store_dwordx4 v211, v[168:171], s[14:15]
	s_waitcnt vmcnt(14)
	v_lshlrev_b32_e32 v156, 16, v172
	v_and_b32_e32 v157, 0xffff0000, v172
	v_lshlrev_b32_e32 v158, 16, v176
	v_and_b32_e32 v159, 0xffff0000, v176
	v_pk_add_f32 v[156:157], v[156:157], v[158:159]
	v_pk_add_f32 v[156:157], v[102:103], v[156:157]
	v_cvt_pk_bf16_f32 v172, v156, v157
	v_pk_fma_f32 v[198:199], v[156:157], v[156:157], v[198:199]
	v_lshlrev_b32_e32 v158, 16, v172
	v_and_b32_e32 v159, 0xffff0000, v172
	v_pk_add_f32 v[196:197], v[156:157], v[158:159] neg_lo:[0,1] neg_hi:[0,1]
	v_cvt_pk_bf16_f32 v176, v196, v197
	v_lshlrev_b32_e32 v156, 16, v173
	v_and_b32_e32 v157, 0xffff0000, v173
	v_lshlrev_b32_e32 v158, 16, v177
	v_and_b32_e32 v159, 0xffff0000, v177
	v_pk_add_f32 v[156:157], v[156:157], v[158:159]
	v_pk_add_f32 v[156:157], v[104:105], v[156:157]
	v_cvt_pk_bf16_f32 v173, v156, v157
	v_pk_fma_f32 v[198:199], v[156:157], v[156:157], v[198:199]
	v_lshlrev_b32_e32 v158, 16, v173
	v_and_b32_e32 v159, 0xffff0000, v173
	v_pk_add_f32 v[196:197], v[156:157], v[158:159] neg_lo:[0,1] neg_hi:[0,1]
	v_cvt_pk_bf16_f32 v177, v196, v197
	v_lshlrev_b32_e32 v156, 16, v174
	v_and_b32_e32 v157, 0xffff0000, v174
	v_lshlrev_b32_e32 v158, 16, v178
	v_and_b32_e32 v159, 0xffff0000, v178
	v_pk_add_f32 v[156:157], v[156:157], v[158:159]
	v_pk_add_f32 v[156:157], v[98:99], v[156:157]
	v_cvt_pk_bf16_f32 v174, v156, v157
	v_pk_fma_f32 v[198:199], v[156:157], v[156:157], v[198:199]
	v_lshlrev_b32_e32 v158, 16, v174
	v_and_b32_e32 v159, 0xffff0000, v174
	v_pk_add_f32 v[196:197], v[156:157], v[158:159] neg_lo:[0,1] neg_hi:[0,1]
	v_cvt_pk_bf16_f32 v178, v196, v197
	v_lshlrev_b32_e32 v156, 16, v175
	v_and_b32_e32 v157, 0xffff0000, v175
	v_lshlrev_b32_e32 v158, 16, v179
	v_and_b32_e32 v159, 0xffff0000, v179
	v_pk_add_f32 v[156:157], v[156:157], v[158:159]
	v_pk_add_f32 v[156:157], v[100:101], v[156:157]
	v_cvt_pk_bf16_f32 v175, v156, v157
	v_pk_fma_f32 v[198:199], v[156:157], v[156:157], v[198:199]
	v_lshlrev_b32_e32 v158, 16, v175
	v_and_b32_e32 v159, 0xffff0000, v175
	v_pk_add_f32 v[196:197], v[156:157], v[158:159] neg_lo:[0,1] neg_hi:[0,1]
	v_cvt_pk_bf16_f32 v179, v196, v197
	global_store_dwordx4 v211, v[172:175], s[10:11] offset:256
	global_store_dwordx4 v211, v[176:179], s[14:15] offset:256
	v_add_f32_e32 v201, v198, v199
	s_nop 0
	v_add_u32_e32 v211, 0x40000, v213
	global_load_dwordx4 v[164:167], v211, s[10:11]
	global_load_dwordx4 v[168:171], v211, s[14:15]
	global_load_dwordx4 v[172:175], v211, s[10:11] offset:256
	global_load_dwordx4 v[176:179], v211, s[14:15] offset:256
	s_waitcnt vmcnt(18)
; __device__ __forceinline__ unsigned pk2(float lo, float hi) { f32x2_t v = {lo, hi}; bf16x2_t b = __builtin_convertvector(v, bf16x2_t); return __builtin_bit_cast(unsigned, b); }
; __device__ __forceinline__ float bflo(unsigned u) { return __uint_as_float(u << 16); }
;     __device__ __forceinline__ void operator()(const f32x4 (&acc)[2][2][4][2], const Unit& u, int wr, int wc, int fr, int fq) const {
;     ...
;                 for (int bj = 0; bj < 2; ++bj) {
;                     const size_t off = (size_t)row * DM + col0 + bj * HALF;
;                     const u32x4 hh = *(const u32x4*)(HI + off), ll = *(const u32x4*)(LO + off);
;                     float hv[8] = {bflo(hh.x) + bflo(ll.x), bfhi(hh.x) + bfhi(ll.x), bflo(hh.y) + bflo(ll.y), bfhi(hh.y) + bfhi(ll.y),
;                                    bflo(hh.z) + bflo(ll.z), bfhi(hh.z) + bfhi(ll.z), bflo(hh.w) + bflo(ll.w), bfhi(hh.w) + bfhi(ll.w)};
;                     float av[8] = {acc[ai][bj][m][0][0], acc[ai][bj][m][0][1], acc[ai][bj][m][0][2], acc[ai][bj][m][0][3], acc[ai][bj][m][1][0], acc[ai][bj][m][1][1], acc[ai][bj][m][1][2], acc[ai][bj][m][1][3]};
;                     if (GATED) { const u32x4 pp = *(const u32x4*)(PP + off);
;                         const float pv[8] = {bflo(pp.x), bfhi(pp.x), bflo(pp.y), bfhi(pp.y), bflo(pp.z), bfhi(pp.z), bflo(pp.w), bfhi(pp.w)};
; #pragma unroll
;                         for (int e = 0; e < 8; ++e) av[e] = fast_sigmoid(av[e] * rs) * pv[e]; }
;                     else {
; #pragma unroll
;                         for (int e = 0; e < 8; ++e) av[e] *= alpha; }
;                     float lo[8];
; #pragma unroll
;                     for (int e = 0; e < 8; ++e) { hv[e] += av[e]; sq += hv[e] * hv[e]; }
;                     u32x4 wh; wh.x = pk2(hv[0], hv[1]); wh.y = pk2(hv[2], hv[3]); wh.z = pk2(hv[4], hv[5]); wh.w = pk2(hv[6], hv[7]);
;                     lo[0] = hv[0] - bflo(wh.x); lo[1] = hv[1] - bfhi(wh.x); lo[2] = hv[2] - bflo(wh.y); lo[3] = hv[3] - bfhi(wh.y);
;                     lo[4] = hv[4] - bflo(wh.z); lo[5] = hv[5] - bfhi(wh.z); lo[6] = hv[6] - bflo(wh.w); lo[7] = hv[7] - bfhi(wh.w);
;                     u32x4 wl; wl.x = pk2(lo[0], lo[1]); wl.y = pk2(lo[2], lo[3]); wl.z = pk2(lo[4], lo[5]); wl.w = pk2(lo[6], lo[7]);
;                     *(u32x4*)(HO + off) = wh; *(u32x4*)(LO + off) = wl;
	v_lshlrev_b32_e32 v156, 16, v180
	v_and_b32_e32 v157, 0xffff0000, v180
	v_lshlrev_b32_e32 v158, 16, v184
	v_and_b32_e32 v159, 0xffff0000, v184
	v_pk_add_f32 v[156:157], v[156:157], v[158:159]
	v_pk_add_f32 v[156:157], v[94:95], v[156:157]
	v_cvt_pk_bf16_f32 v180, v156, v157
	v_pk_mul_f32 v[198:199], v[156:157], v[156:157]
	v_lshlrev_b32_e32 v158, 16, v180
	v_and_b32_e32 v159, 0xffff0000, v180
	v_pk_add_f32 v[196:197], v[156:157], v[158:159] neg_lo:[0,1] neg_hi:[0,1]
	v_cvt_pk_bf16_f32 v184, v196, v197
	v_lshlrev_b32_e32 v156, 16, v181
	v_and_b32_e32 v157, 0xffff0000, v181
	v_lshlrev_b32_e32 v158, 16, v185
	v_and_b32_e32 v159, 0xffff0000, v185
	v_pk_add_f32 v[156:157], v[156:157], v[158:159]
	v_pk_add_f32 v[156:157], v[96:97], v[156:157]
	v_cvt_pk_bf16_f32 v181, v156, v157
	v_pk_fma_f32 v[198:199], v[156:157], v[156:157], v[198:199]
	v_lshlrev_b32_e32 v158, 16, v181
	v_and_b32_e32 v159, 0xffff0000, v181
	v_pk_add_f32 v[196:197], v[156:157], v[158:159] neg_lo:[0,1] neg_hi:[0,1]
	v_cvt_pk_bf16_f32 v185, v196, v197
	v_lshlrev_b32_e32 v156, 16, v182
	v_and_b32_e32 v157, 0xffff0000, v182
	v_lshlrev_b32_e32 v158, 16, v186
	v_and_b32_e32 v159, 0xffff0000, v186
	v_pk_add_f32 v[156:157], v[156:157], v[158:159]
	v_pk_add_f32 v[156:157], v[90:91], v[156:157]
	v_cvt_pk_bf16_f32 v182, v156, v157
	v_pk_fma_f32 v[198:199], v[156:157], v[156:157], v[198:199]
	v_lshlrev_b32_e32 v158, 16, v182
	v_and_b32_e32 v159, 0xffff0000, v182
	v_pk_add_f32 v[196:197], v[156:157], v[158:159] neg_lo:[0,1] neg_hi:[0,1]
	v_cvt_pk_bf16_f32 v186, v196, v197
	v_lshlrev_b32_e32 v156, 16, v183
	v_and_b32_e32 v157, 0xffff0000, v183
	v_lshlrev_b32_e32 v158, 16, v187
	v_and_b32_e32 v159, 0xffff0000, v187
	v_pk_add_f32 v[156:157], v[156:157], v[158:159]
	v_pk_add_f32 v[156:157], v[92:93], v[156:157]
	v_cvt_pk_bf16_f32 v183, v156, v157
	v_pk_fma_f32 v[198:199], v[156:157], v[156:157], v[198:199]
	v_lshlrev_b32_e32 v158, 16, v183
	v_and_b32_e32 v159, 0xffff0000, v183
	v_pk_add_f32 v[196:197], v[156:157], v[158:159] neg_lo:[0,1] neg_hi:[0,1]
	v_cvt_pk_bf16_f32 v187, v196, v197
	global_store_dwordx4 v212, v[180:183], s[10:11]
	global_store_dwordx4 v212, v[184:187], s[14:15]
	s_waitcnt vmcnt(18)
	v_lshlrev_b32_e32 v156, 16, v188
	v_and_b32_e32 v157, 0xffff0000, v188
	v_lshlrev_b32_e32 v158, 16, v192
	v_and_b32_e32 v159, 0xffff0000, v192
	v_pk_add_f32 v[156:157], v[156:157], v[158:159]
	v_pk_add_f32 v[156:157], v[86:87], v[156:157]
	v_cvt_pk_bf16_f32 v188, v156, v157
	v_pk_fma_f32 v[198:199], v[156:157], v[156:157], v[198:199]
	v_lshlrev_b32_e32 v158, 16, v188
	v_and_b32_e32 v159, 0xffff0000, v188
	v_pk_add_f32 v[196:197], v[156:157], v[158:159] neg_lo:[0,1] neg_hi:[0,1]
	v_cvt_pk_bf16_f32 v192, v196, v197
	v_lshlrev_b32_e32 v156, 16, v189
	v_and_b32_e32 v157, 0xffff0000, v189
	v_lshlrev_b32_e32 v158, 16, v193
	v_and_b32_e32 v159, 0xffff0000, v193
	v_pk_add_f32 v[156:157], v[156:157], v[158:159]
	v_pk_add_f32 v[156:157], v[88:89], v[156:157]
	v_cvt_pk_bf16_f32 v189, v156, v157
	v_pk_fma_f32 v[198:199], v[156:157], v[156:157], v[198:199]
	v_lshlrev_b32_e32 v158, 16, v189
	v_and_b32_e32 v159, 0xffff0000, v189
	v_pk_add_f32 v[196:197], v[156:157], v[158:159] neg_lo:[0,1] neg_hi:[0,1]
	v_cvt_pk_bf16_f32 v193, v196, v197
	v_lshlrev_b32_e32 v156, 16, v190
	v_and_b32_e32 v157, 0xffff0000, v190
	v_lshlrev_b32_e32 v158, 16, v194
	v_and_b32_e32 v159, 0xffff0000, v194
	v_pk_add_f32 v[156:157], v[156:157], v[158:159]
	v_pk_add_f32 v[156:157], v[82:83], v[156:157]
	v_cvt_pk_bf16_f32 v190, v156, v157
	v_pk_fma_f32 v[198:199], v[156:157], v[156:157], v[198:199]
	v_lshlrev_b32_e32 v158, 16, v190
	v_and_b32_e32 v159, 0xffff0000, v190
	v_pk_add_f32 v[196:197], v[156:157], v[158:159] neg_lo:[0,1] neg_hi:[0,1]
	v_cvt_pk_bf16_f32 v194, v196, v197
	v_lshlrev_b32_e32 v156, 16, v191
	v_and_b32_e32 v157, 0xffff0000, v191
	v_lshlrev_b32_e32 v158, 16, v195
	v_and_b32_e32 v159, 0xffff0000, v195
	v_pk_add_f32 v[156:157], v[156:157], v[158:159]
	v_pk_add_f32 v[156:157], v[84:85], v[156:157]
	v_cvt_pk_bf16_f32 v191, v156, v157
	v_pk_fma_f32 v[198:199], v[156:157], v[156:157], v[198:199]
	v_lshlrev_b32_e32 v158, 16, v191
	v_and_b32_e32 v159, 0xffff0000, v191
	v_pk_add_f32 v[196:197], v[156:157], v[158:159] neg_lo:[0,1] neg_hi:[0,1]
	v_cvt_pk_bf16_f32 v195, v196, v197
	global_store_dwordx4 v212, v[188:191], s[10:11] offset:256
	global_store_dwordx4 v212, v[192:195], s[14:15] offset:256
	v_add_f32_e32 v202, v198, v199
	s_nop 0
	v_add_u32_e32 v212, 0x48000, v213
	global_load_dwordx4 v[180:183], v212, s[10:11]
	global_load_dwordx4 v[184:187], v212, s[14:15]
	global_load_dwordx4 v[188:191], v212, s[10:11] offset:256
	global_load_dwordx4 v[192:195], v212, s[14:15] offset:256
	s_waitcnt vmcnt(22)
; __device__ __forceinline__ unsigned pk2(float lo, float hi) { f32x2_t v = {lo, hi}; bf16x2_t b = __builtin_convertvector(v, bf16x2_t); return __builtin_bit_cast(unsigned, b); }
; __device__ __forceinline__ float bflo(unsigned u) { return __uint_as_float(u << 16); }
;     __device__ __forceinline__ void operator()(const f32x4 (&acc)[2][2][4][2], const Unit& u, int wr, int wc, int fr, int fq) const {
;     ...
;                 for (int bj = 0; bj < 2; ++bj) {
;                     const size_t off = (size_t)row * DM + col0 + bj * HALF;
;                     const u32x4 hh = *(const u32x4*)(HI + off), ll = *(const u32x4*)(LO + off);
;                     float hv[8] = {bflo(hh.x) + bflo(ll.x), bfhi(hh.x) + bfhi(ll.x), bflo(hh.y) + bflo(ll.y), bfhi(hh.y) + bfhi(ll.y),
;                                    bflo(hh.z) + bflo(ll.z), bfhi(hh.z) + bfhi(ll.z), bflo(hh.w) + bflo(ll.w), bfhi(hh.w) + bfhi(ll.w)};
;                     float av[8] = {acc[ai][bj][m][0][0], acc[ai][bj][m][0][1], acc[ai][bj][m][0][2], acc[ai][bj][m][0][3], acc[ai][bj][m][1][0], acc[ai][bj][m][1][1], acc[ai][bj][m][1][2], acc[ai][bj][m][1][3]};
;                     if (GATED) { const u32x4 pp = *(const u32x4*)(PP + off);
;                         const float pv[8] = {bflo(pp.x), bfhi(pp.x), bflo(pp.y), bfhi(pp.y), bflo(pp.z), bfhi(pp.z), bflo(pp.w), bfhi(pp.w)};
; #pragma unroll
;                         for (int e = 0; e < 8; ++e) av[e] = fast_sigmoid(av[e] * rs) * pv[e]; }
;                     else {
; #pragma unroll
;                         for (int e = 0; e < 8; ++e) av[e] *= alpha; }
;                     float lo[8];
; #pragma unroll
;                     for (int e = 0; e < 8; ++e) { hv[e] += av[e]; sq += hv[e] * hv[e]; }
;                     u32x4 wh; wh.x = pk2(hv[0], hv[1]); wh.y = pk2(hv[2], hv[3]); wh.z = pk2(hv[4], hv[5]); wh.w = pk2(hv[6], hv[7]);
;                     lo[0] = hv[0] - bflo(wh.x); lo[1] = hv[1] - bfhi(wh.x); lo[2] = hv[2] - bflo(wh.y); lo[3] = hv[3] - bfhi(wh.y);
;                     lo[4] = hv[4] - bflo(wh.z); lo[5] = hv[5] - bfhi(wh.z); lo[6] = hv[6] - bflo(wh.w); lo[7] = hv[7] - bfhi(wh.w);
;                     u32x4 wl; wl.x = pk2(lo[0], lo[1]); wl.y = pk2(lo[2], lo[3]); wl.z = pk2(lo[4], lo[5]); wl.w = pk2(lo[6], lo[7]);
;                     *(u32x4*)(HO + off) = wh; *(u32x4*)(LO + off) = wl;
	v_lshlrev_b32_e32 v156, 16, v140
	v_and_b32_e32 v157, 0xffff0000, v140
	v_lshlrev_b32_e32 v158, 16, v144
	v_and_b32_e32 v159, 0xffff0000, v144
	v_pk_add_f32 v[156:157], v[156:157], v[158:159]
	v_pk_add_f32 v[156:157], v[78:79], v[156:157]
	v_cvt_pk_bf16_f32 v140, v156, v157
	v_pk_mul_f32 v[198:199], v[156:157], v[156:157]
	v_lshlrev_b32_e32 v158, 16, v140
	v_and_b32_e32 v159, 0xffff0000, v140
	v_pk_add_f32 v[196:197], v[156:157], v[158:159] neg_lo:[0,1] neg_hi:[0,1]
	v_cvt_pk_bf16_f32 v144, v196, v197
	v_lshlrev_b32_e32 v156, 16, v141
	v_and_b32_e32 v157, 0xffff0000, v141
	v_lshlrev_b32_e32 v158, 16, v145
	v_and_b32_e32 v159, 0xffff0000, v145
	v_pk_add_f32 v[156:157], v[156:157], v[158:159]
	v_pk_add_f32 v[156:157], v[80:81], v[156:157]
	v_cvt_pk_bf16_f32 v141, v156, v157
	v_pk_fma_f32 v[198:199], v[156:157], v[156:157], v[198:199]
	v_lshlrev_b32_e32 v158, 16, v141
	v_and_b32_e32 v159, 0xffff0000, v141
	v_pk_add_f32 v[196:197], v[156:157], v[158:159] neg_lo:[0,1] neg_hi:[0,1]
	v_cvt_pk_bf16_f32 v145, v196, v197
	v_lshlrev_b32_e32 v156, 16, v142
	v_and_b32_e32 v157, 0xffff0000, v142
	v_lshlrev_b32_e32 v158, 16, v146
	v_and_b32_e32 v159, 0xffff0000, v146
	v_pk_add_f32 v[156:157], v[156:157], v[158:159]
	v_pk_add_f32 v[156:157], v[74:75], v[156:157]
	v_cvt_pk_bf16_f32 v142, v156, v157
	v_pk_fma_f32 v[198:199], v[156:157], v[156:157], v[198:199]
	v_lshlrev_b32_e32 v158, 16, v142
	v_and_b32_e32 v159, 0xffff0000, v142
	v_pk_add_f32 v[196:197], v[156:157], v[158:159] neg_lo:[0,1] neg_hi:[0,1]
	v_cvt_pk_bf16_f32 v146, v196, v197
	v_lshlrev_b32_e32 v156, 16, v143
	v_and_b32_e32 v157, 0xffff0000, v143
	v_lshlrev_b32_e32 v158, 16, v147
	v_and_b32_e32 v159, 0xffff0000, v147
	v_pk_add_f32 v[156:157], v[156:157], v[158:159]
	v_pk_add_f32 v[156:157], v[76:77], v[156:157]
	v_cvt_pk_bf16_f32 v143, v156, v157
	v_pk_fma_f32 v[198:199], v[156:157], v[156:157], v[198:199]
	v_lshlrev_b32_e32 v158, 16, v143
	v_and_b32_e32 v159, 0xffff0000, v143
	v_pk_add_f32 v[196:197], v[156:157], v[158:159] neg_lo:[0,1] neg_hi:[0,1]
	v_cvt_pk_bf16_f32 v147, v196, v197
	global_store_dwordx4 v210, v[140:143], s[10:11]
	global_store_dwordx4 v210, v[144:147], s[14:15]
	s_waitcnt vmcnt(22)
	v_lshlrev_b32_e32 v156, 16, v148
	v_and_b32_e32 v157, 0xffff0000, v148
	v_lshlrev_b32_e32 v158, 16, v152
	v_and_b32_e32 v159, 0xffff0000, v152
	v_pk_add_f32 v[156:157], v[156:157], v[158:159]
	v_pk_add_f32 v[156:157], v[70:71], v[156:157]
	v_cvt_pk_bf16_f32 v148, v156, v157
	v_pk_fma_f32 v[198:199], v[156:157], v[156:157], v[198:199]
	v_lshlrev_b32_e32 v158, 16, v148
	v_and_b32_e32 v159, 0xffff0000, v148
	v_pk_add_f32 v[196:197], v[156:157], v[158:159] neg_lo:[0,1] neg_hi:[0,1]
	v_cvt_pk_bf16_f32 v152, v196, v197
	v_lshlrev_b32_e32 v156, 16, v149
	v_and_b32_e32 v157, 0xffff0000, v149
	v_lshlrev_b32_e32 v158, 16, v153
	v_and_b32_e32 v159, 0xffff0000, v153
	v_pk_add_f32 v[156:157], v[156:157], v[158:159]
	v_pk_add_f32 v[156:157], v[72:73], v[156:157]
	v_cvt_pk_bf16_f32 v149, v156, v157
	v_pk_fma_f32 v[198:199], v[156:157], v[156:157], v[198:199]
	v_lshlrev_b32_e32 v158, 16, v149
	v_and_b32_e32 v159, 0xffff0000, v149
	v_pk_add_f32 v[196:197], v[156:157], v[158:159] neg_lo:[0,1] neg_hi:[0,1]
	v_cvt_pk_bf16_f32 v153, v196, v197
	v_lshlrev_b32_e32 v156, 16, v150
	v_and_b32_e32 v157, 0xffff0000, v150
	v_lshlrev_b32_e32 v158, 16, v154
	v_and_b32_e32 v159, 0xffff0000, v154
	v_pk_add_f32 v[156:157], v[156:157], v[158:159]
	v_pk_add_f32 v[156:157], v[66:67], v[156:157]
	v_cvt_pk_bf16_f32 v150, v156, v157
	v_pk_fma_f32 v[198:199], v[156:157], v[156:157], v[198:199]
	v_lshlrev_b32_e32 v158, 16, v150
	v_and_b32_e32 v159, 0xffff0000, v150
	v_pk_add_f32 v[196:197], v[156:157], v[158:159] neg_lo:[0,1] neg_hi:[0,1]
	v_cvt_pk_bf16_f32 v154, v196, v197
	v_lshlrev_b32_e32 v156, 16, v151
	v_and_b32_e32 v157, 0xffff0000, v151
	v_lshlrev_b32_e32 v158, 16, v155
	v_and_b32_e32 v159, 0xffff0000, v155
	v_pk_add_f32 v[156:157], v[156:157], v[158:159]
	v_pk_add_f32 v[156:157], v[68:69], v[156:157]
	v_cvt_pk_bf16_f32 v151, v156, v157
	v_pk_fma_f32 v[198:199], v[156:157], v[156:157], v[198:199]
	v_lshlrev_b32_e32 v158, 16, v151
	v_and_b32_e32 v159, 0xffff0000, v151
	v_pk_add_f32 v[196:197], v[156:157], v[158:159] neg_lo:[0,1] neg_hi:[0,1]
	v_cvt_pk_bf16_f32 v155, v196, v197
	global_store_dwordx4 v210, v[148:151], s[10:11] offset:256
	global_store_dwordx4 v210, v[152:155], s[14:15] offset:256
	v_add_f32_e32 v203, v198, v199
	s_nop 0
	v_add_u32_e32 v210, 0x50000, v213
	global_load_dwordx4 v[140:143], v210, s[10:11]
	global_load_dwordx4 v[144:147], v210, s[14:15]
	global_load_dwordx4 v[148:151], v210, s[10:11] offset:256
	global_load_dwordx4 v[152:155], v210, s[14:15] offset:256
	s_waitcnt vmcnt(18)
; __device__ __forceinline__ unsigned pk2(float lo, float hi) { f32x2_t v = {lo, hi}; bf16x2_t b = __builtin_convertvector(v, bf16x2_t); return __builtin_bit_cast(unsigned, b); }
; __device__ __forceinline__ float bflo(unsigned u) { return __uint_as_float(u << 16); }
;     __device__ __forceinline__ void operator()(const f32x4 (&acc)[2][2][4][2], const Unit& u, int wr, int wc, int fr, int fq) const {
;     ...
;                 for (int bj = 0; bj < 2; ++bj) {
;                     const size_t off = (size_t)row * DM + col0 + bj * HALF;
;                     const u32x4 hh = *(const u32x4*)(HI + off), ll = *(const u32x4*)(LO + off);
;                     float hv[8] = {bflo(hh.x) + bflo(ll.x), bfhi(hh.x) + bfhi(ll.x), bflo(hh.y) + bflo(ll.y), bfhi(hh.y) + bfhi(ll.y),
;                                    bflo(hh.z) + bflo(ll.z), bfhi(hh.z) + bfhi(ll.z), bflo(hh.w) + bflo(ll.w), bfhi(hh.w) + bfhi(ll.w)};
;                     float av[8] = {acc[ai][bj][m][0][0], acc[ai][bj][m][0][1], acc[ai][bj][m][0][2], acc[ai][bj][m][0][3], acc[ai][bj][m][1][0], acc[ai][bj][m][1][1], acc[ai][bj][m][1][2], acc[ai][bj][m][1][3]};
;                     if (GATED) { const u32x4 pp = *(const u32x4*)(PP + off);
;                         const float pv[8] = {bflo(pp.x), bfhi(pp.x), bflo(pp.y), bfhi(pp.y), bflo(pp.z), bfhi(pp.z), bflo(pp.w), bfhi(pp.w)};
; #pragma unroll
;                         for (int e = 0; e < 8; ++e) av[e] = fast_sigmoid(av[e] * rs) * pv[e]; }
;                     else {
; #pragma unroll
;                         for (int e = 0; e < 8; ++e) av[e] *= alpha; }
;                     float lo[8];
; #pragma unroll
;                     for (int e = 0; e < 8; ++e) { hv[e] += av[e]; sq += hv[e] * hv[e]; }
;                     u32x4 wh; wh.x = pk2(hv[0], hv[1]); wh.y = pk2(hv[2], hv[3]); wh.z = pk2(hv[4], hv[5]); wh.w = pk2(hv[6], hv[7]);
;                     lo[0] = hv[0] - bflo(wh.x); lo[1] = hv[1] - bfhi(wh.x); lo[2] = hv[2] - bflo(wh.y); lo[3] = hv[3] - bfhi(wh.y);
;                     lo[4] = hv[4] - bflo(wh.z); lo[5] = hv[5] - bfhi(wh.z); lo[6] = hv[6] - bflo(wh.w); lo[7] = hv[7] - bfhi(wh.w);
;                     u32x4 wl; wl.x = pk2(lo[0], lo[1]); wl.y = pk2(lo[2], lo[3]); wl.z = pk2(lo[4], lo[5]); wl.w = pk2(lo[6], lo[7]);
;                     *(u32x4*)(HO + off) = wh; *(u32x4*)(LO + off) = wl;
	v_lshlrev_b32_e32 v156, 16, v164
	v_and_b32_e32 v157, 0xffff0000, v164
	v_lshlrev_b32_e32 v158, 16, v168
	v_and_b32_e32 v159, 0xffff0000, v168
	v_pk_add_f32 v[156:157], v[156:157], v[158:159]
	v_pk_add_f32 v[156:157], v[62:63], v[156:157]
	v_cvt_pk_bf16_f32 v164, v156, v157
	v_pk_mul_f32 v[198:199], v[156:157], v[156:157]
	v_lshlrev_b32_e32 v158, 16, v164
	v_and_b32_e32 v159, 0xffff0000, v164
	v_pk_add_f32 v[196:197], v[156:157], v[158:159] neg_lo:[0,1] neg_hi:[0,1]
	v_cvt_pk_bf16_f32 v168, v196, v197
	v_lshlrev_b32_e32 v156, 16, v165
	v_and_b32_e32 v157, 0xffff0000, v165
	v_lshlrev_b32_e32 v158, 16, v169
	v_and_b32_e32 v159, 0xffff0000, v169
	v_pk_add_f32 v[156:157], v[156:157], v[158:159]
	v_pk_add_f32 v[156:157], v[64:65], v[156:157]
	v_cvt_pk_bf16_f32 v165, v156, v157
	v_pk_fma_f32 v[198:199], v[156:157], v[156:157], v[198:199]
	v_lshlrev_b32_e32 v158, 16, v165
	v_and_b32_e32 v159, 0xffff0000, v165
	v_pk_add_f32 v[196:197], v[156:157], v[158:159] neg_lo:[0,1] neg_hi:[0,1]
	v_cvt_pk_bf16_f32 v169, v196, v197
	v_lshlrev_b32_e32 v156, 16, v166
	v_and_b32_e32 v157, 0xffff0000, v166
	v_lshlrev_b32_e32 v158, 16, v170
	v_and_b32_e32 v159, 0xffff0000, v170
	v_pk_add_f32 v[156:157], v[156:157], v[158:159]
	v_pk_add_f32 v[156:157], v[58:59], v[156:157]
	v_cvt_pk_bf16_f32 v166, v156, v157
	v_pk_fma_f32 v[198:199], v[156:157], v[156:157], v[198:199]
	v_lshlrev_b32_e32 v158, 16, v166
	v_and_b32_e32 v159, 0xffff0000, v166
	v_pk_add_f32 v[196:197], v[156:157], v[158:159] neg_lo:[0,1] neg_hi:[0,1]
	v_cvt_pk_bf16_f32 v170, v196, v197
	v_lshlrev_b32_e32 v156, 16, v167
	v_and_b32_e32 v157, 0xffff0000, v167
	v_lshlrev_b32_e32 v158, 16, v171
	v_and_b32_e32 v159, 0xffff0000, v171
	v_pk_add_f32 v[156:157], v[156:157], v[158:159]
	v_pk_add_f32 v[156:157], v[60:61], v[156:157]
	v_cvt_pk_bf16_f32 v167, v156, v157
	v_pk_fma_f32 v[198:199], v[156:157], v[156:157], v[198:199]
	v_lshlrev_b32_e32 v158, 16, v167
	v_and_b32_e32 v159, 0xffff0000, v167
	v_pk_add_f32 v[196:197], v[156:157], v[158:159] neg_lo:[0,1] neg_hi:[0,1]
	v_cvt_pk_bf16_f32 v171, v196, v197
	global_store_dwordx4 v211, v[164:167], s[10:11]
	global_store_dwordx4 v211, v[168:171], s[14:15]
	s_waitcnt vmcnt(18)
	v_lshlrev_b32_e32 v156, 16, v172
	v_and_b32_e32 v157, 0xffff0000, v172
	v_lshlrev_b32_e32 v158, 16, v176
	v_and_b32_e32 v159, 0xffff0000, v176
	v_pk_add_f32 v[156:157], v[156:157], v[158:159]
	v_pk_add_f32 v[156:157], v[54:55], v[156:157]
	v_cvt_pk_bf16_f32 v172, v156, v157
	v_pk_fma_f32 v[198:199], v[156:157], v[156:157], v[198:199]
	v_lshlrev_b32_e32 v158, 16, v172
	v_and_b32_e32 v159, 0xffff0000, v172
	v_pk_add_f32 v[196:197], v[156:157], v[158:159] neg_lo:[0,1] neg_hi:[0,1]
	v_cvt_pk_bf16_f32 v176, v196, v197
	v_lshlrev_b32_e32 v156, 16, v173
	v_and_b32_e32 v157, 0xffff0000, v173
	v_lshlrev_b32_e32 v158, 16, v177
	v_and_b32_e32 v159, 0xffff0000, v177
	v_pk_add_f32 v[156:157], v[156:157], v[158:159]
	v_pk_add_f32 v[156:157], v[56:57], v[156:157]
	v_cvt_pk_bf16_f32 v173, v156, v157
	v_pk_fma_f32 v[198:199], v[156:157], v[156:157], v[198:199]
	v_lshlrev_b32_e32 v158, 16, v173
	v_and_b32_e32 v159, 0xffff0000, v173
	v_pk_add_f32 v[196:197], v[156:157], v[158:159] neg_lo:[0,1] neg_hi:[0,1]
	v_cvt_pk_bf16_f32 v177, v196, v197
	v_lshlrev_b32_e32 v156, 16, v174
	v_and_b32_e32 v157, 0xffff0000, v174
	v_lshlrev_b32_e32 v158, 16, v178
	v_and_b32_e32 v159, 0xffff0000, v178
	v_pk_add_f32 v[156:157], v[156:157], v[158:159]
	v_pk_add_f32 v[156:157], v[50:51], v[156:157]
	v_cvt_pk_bf16_f32 v174, v156, v157
	v_pk_fma_f32 v[198:199], v[156:157], v[156:157], v[198:199]
	v_lshlrev_b32_e32 v158, 16, v174
	v_and_b32_e32 v159, 0xffff0000, v174
	v_pk_add_f32 v[196:197], v[156:157], v[158:159] neg_lo:[0,1] neg_hi:[0,1]
	v_cvt_pk_bf16_f32 v178, v196, v197
	v_lshlrev_b32_e32 v156, 16, v175
	v_and_b32_e32 v157, 0xffff0000, v175
	v_lshlrev_b32_e32 v158, 16, v179
	v_and_b32_e32 v159, 0xffff0000, v179
	v_pk_add_f32 v[156:157], v[156:157], v[158:159]
	v_pk_add_f32 v[156:157], v[52:53], v[156:157]
	v_cvt_pk_bf16_f32 v175, v156, v157
	v_pk_fma_f32 v[198:199], v[156:157], v[156:157], v[198:199]
	v_lshlrev_b32_e32 v158, 16, v175
	v_and_b32_e32 v159, 0xffff0000, v175
	v_pk_add_f32 v[196:197], v[156:157], v[158:159] neg_lo:[0,1] neg_hi:[0,1]
	v_cvt_pk_bf16_f32 v179, v196, v197
	global_store_dwordx4 v211, v[172:175], s[10:11] offset:256
	global_store_dwordx4 v211, v[176:179], s[14:15] offset:256
	v_add_f32_e32 v206, v198, v199
	s_nop 0
	v_add_u32_e32 v211, 0x58000, v213
	global_load_dwordx4 v[164:167], v211, s[10:11]
	global_load_dwordx4 v[168:171], v211, s[14:15]
	global_load_dwordx4 v[172:175], v211, s[10:11] offset:256
	global_load_dwordx4 v[176:179], v211, s[14:15] offset:256
	s_waitcnt vmcnt(18)
; __device__ __forceinline__ unsigned pk2(float lo, float hi) { f32x2_t v = {lo, hi}; bf16x2_t b = __builtin_convertvector(v, bf16x2_t); return __builtin_bit_cast(unsigned, b); }
; __device__ __forceinline__ float bflo(unsigned u) { return __uint_as_float(u << 16); }
;     __device__ __forceinline__ void operator()(const f32x4 (&acc)[2][2][4][2], const Unit& u, int wr, int wc, int fr, int fq) const {
;     ...
;                 for (int bj = 0; bj < 2; ++bj) {
;                     const size_t off = (size_t)row * DM + col0 + bj * HALF;
;                     const u32x4 hh = *(const u32x4*)(HI + off), ll = *(const u32x4*)(LO + off);
;                     float hv[8] = {bflo(hh.x) + bflo(ll.x), bfhi(hh.x) + bfhi(ll.x), bflo(hh.y) + bflo(ll.y), bfhi(hh.y) + bfhi(ll.y),
;                                    bflo(hh.z) + bflo(ll.z), bfhi(hh.z) + bfhi(ll.z), bflo(hh.w) + bflo(ll.w), bfhi(hh.w) + bfhi(ll.w)};
;                     float av[8] = {acc[ai][bj][m][0][0], acc[ai][bj][m][0][1], acc[ai][bj][m][0][2], acc[ai][bj][m][0][3], acc[ai][bj][m][1][0], acc[ai][bj][m][1][1], acc[ai][bj][m][1][2], acc[ai][bj][m][1][3]};
;                     if (GATED) { const u32x4 pp = *(const u32x4*)(PP + off);
;                         const float pv[8] = {bflo(pp.x), bfhi(pp.x), bflo(pp.y), bfhi(pp.y), bflo(pp.z), bfhi(pp.z), bflo(pp.w), bfhi(pp.w)};
; #pragma unroll
;                         for (int e = 0; e < 8; ++e) av[e] = fast_sigmoid(av[e] * rs) * pv[e]; }
;                     else {
; #pragma unroll
;                         for (int e = 0; e < 8; ++e) av[e] *= alpha; }
;                     float lo[8];
; #pragma unroll
;                     for (int e = 0; e < 8; ++e) { hv[e] += av[e]; sq += hv[e] * hv[e]; }
;                     u32x4 wh; wh.x = pk2(hv[0], hv[1]); wh.y = pk2(hv[2], hv[3]); wh.z = pk2(hv[4], hv[5]); wh.w = pk2(hv[6], hv[7]);
;                     lo[0] = hv[0] - bflo(wh.x); lo[1] = hv[1] - bfhi(wh.x); lo[2] = hv[2] - bflo(wh.y); lo[3] = hv[3] - bfhi(wh.y);
;                     lo[4] = hv[4] - bflo(wh.z); lo[5] = hv[5] - bfhi(wh.z); lo[6] = hv[6] - bflo(wh.w); lo[7] = hv[7] - bfhi(wh.w);
;                     u32x4 wl; wl.x = pk2(lo[0], lo[1]); wl.y = pk2(lo[2], lo[3]); wl.z = pk2(lo[4], lo[5]); wl.w = pk2(lo[6], lo[7]);
;                     *(u32x4*)(HO + off) = wh; *(u32x4*)(LO + off) = wl;
	v_lshlrev_b32_e32 v156, 16, v180
	v_and_b32_e32 v157, 0xffff0000, v180
	v_lshlrev_b32_e32 v158, 16, v184
	v_and_b32_e32 v159, 0xffff0000, v184
	v_pk_add_f32 v[156:157], v[156:157], v[158:159]
	v_pk_add_f32 v[156:157], v[46:47], v[156:157]
	v_cvt_pk_bf16_f32 v180, v156, v157
	v_pk_mul_f32 v[198:199], v[156:157], v[156:157]
	v_lshlrev_b32_e32 v158, 16, v180
	v_and_b32_e32 v159, 0xffff0000, v180
	v_pk_add_f32 v[196:197], v[156:157], v[158:159] neg_lo:[0,1] neg_hi:[0,1]
	v_cvt_pk_bf16_f32 v184, v196, v197
	v_lshlrev_b32_e32 v156, 16, v181
	v_and_b32_e32 v157, 0xffff0000, v181
	v_lshlrev_b32_e32 v158, 16, v185
	v_and_b32_e32 v159, 0xffff0000, v185
	v_pk_add_f32 v[156:157], v[156:157], v[158:159]
	v_pk_add_f32 v[156:157], v[48:49], v[156:157]
	v_cvt_pk_bf16_f32 v181, v156, v157
	v_pk_fma_f32 v[198:199], v[156:157], v[156:157], v[198:199]
	v_lshlrev_b32_e32 v158, 16, v181
	v_and_b32_e32 v159, 0xffff0000, v181
	v_pk_add_f32 v[196:197], v[156:157], v[158:159] neg_lo:[0,1] neg_hi:[0,1]
	v_cvt_pk_bf16_f32 v185, v196, v197
	v_lshlrev_b32_e32 v156, 16, v182
	v_and_b32_e32 v157, 0xffff0000, v182
	v_lshlrev_b32_e32 v158, 16, v186
	v_and_b32_e32 v159, 0xffff0000, v186
	v_pk_add_f32 v[156:157], v[156:157], v[158:159]
	v_pk_add_f32 v[156:157], v[42:43], v[156:157]
	v_cvt_pk_bf16_f32 v182, v156, v157
	v_pk_fma_f32 v[198:199], v[156:157], v[156:157], v[198:199]
	v_lshlrev_b32_e32 v158, 16, v182
	v_and_b32_e32 v159, 0xffff0000, v182
	v_pk_add_f32 v[196:197], v[156:157], v[158:159] neg_lo:[0,1] neg_hi:[0,1]
	v_cvt_pk_bf16_f32 v186, v196, v197
	v_lshlrev_b32_e32 v156, 16, v183
	v_and_b32_e32 v157, 0xffff0000, v183
	v_lshlrev_b32_e32 v158, 16, v187
	v_and_b32_e32 v159, 0xffff0000, v187
	v_pk_add_f32 v[156:157], v[156:157], v[158:159]
	v_pk_add_f32 v[156:157], v[44:45], v[156:157]
	v_cvt_pk_bf16_f32 v183, v156, v157
	v_pk_fma_f32 v[198:199], v[156:157], v[156:157], v[198:199]
	v_lshlrev_b32_e32 v158, 16, v183
	v_and_b32_e32 v159, 0xffff0000, v183
	v_pk_add_f32 v[196:197], v[156:157], v[158:159] neg_lo:[0,1] neg_hi:[0,1]
	v_cvt_pk_bf16_f32 v187, v196, v197
	global_store_dwordx4 v212, v[180:183], s[10:11]
	global_store_dwordx4 v212, v[184:187], s[14:15]
	s_waitcnt vmcnt(18)
	v_lshlrev_b32_e32 v156, 16, v188
	v_and_b32_e32 v157, 0xffff0000, v188
	v_lshlrev_b32_e32 v158, 16, v192
	v_and_b32_e32 v159, 0xffff0000, v192
	v_pk_add_f32 v[156:157], v[156:157], v[158:159]
	v_pk_add_f32 v[156:157], v[38:39], v[156:157]
	v_cvt_pk_bf16_f32 v188, v156, v157
	v_pk_fma_f32 v[198:199], v[156:157], v[156:157], v[198:199]
	v_lshlrev_b32_e32 v158, 16, v188
	v_and_b32_e32 v159, 0xffff0000, v188
	v_pk_add_f32 v[196:197], v[156:157], v[158:159] neg_lo:[0,1] neg_hi:[0,1]
	v_cvt_pk_bf16_f32 v192, v196, v197
	v_lshlrev_b32_e32 v156, 16, v189
	v_and_b32_e32 v157, 0xffff0000, v189
	v_lshlrev_b32_e32 v158, 16, v193
	v_and_b32_e32 v159, 0xffff0000, v193
	v_pk_add_f32 v[156:157], v[156:157], v[158:159]
	v_pk_add_f32 v[156:157], v[40:41], v[156:157]
	v_cvt_pk_bf16_f32 v189, v156, v157
	v_pk_fma_f32 v[198:199], v[156:157], v[156:157], v[198:199]
	v_lshlrev_b32_e32 v158, 16, v189
	v_and_b32_e32 v159, 0xffff0000, v189
	v_pk_add_f32 v[196:197], v[156:157], v[158:159] neg_lo:[0,1] neg_hi:[0,1]
	v_cvt_pk_bf16_f32 v193, v196, v197
	v_lshlrev_b32_e32 v156, 16, v190
	v_and_b32_e32 v157, 0xffff0000, v190
	v_lshlrev_b32_e32 v158, 16, v194
	v_and_b32_e32 v159, 0xffff0000, v194
	v_pk_add_f32 v[156:157], v[156:157], v[158:159]
	v_pk_add_f32 v[156:157], v[34:35], v[156:157]
	v_cvt_pk_bf16_f32 v190, v156, v157
	v_pk_fma_f32 v[198:199], v[156:157], v[156:157], v[198:199]
	v_lshlrev_b32_e32 v158, 16, v190
	v_and_b32_e32 v159, 0xffff0000, v190
	v_pk_add_f32 v[196:197], v[156:157], v[158:159] neg_lo:[0,1] neg_hi:[0,1]
	v_cvt_pk_bf16_f32 v194, v196, v197
	v_lshlrev_b32_e32 v156, 16, v191
	v_and_b32_e32 v157, 0xffff0000, v191
	v_lshlrev_b32_e32 v158, 16, v195
	v_and_b32_e32 v159, 0xffff0000, v195
	v_pk_add_f32 v[156:157], v[156:157], v[158:159]
	v_pk_add_f32 v[156:157], v[36:37], v[156:157]
	v_cvt_pk_bf16_f32 v191, v156, v157
	v_pk_fma_f32 v[198:199], v[156:157], v[156:157], v[198:199]
	v_lshlrev_b32_e32 v158, 16, v191
	v_and_b32_e32 v159, 0xffff0000, v191
	v_pk_add_f32 v[196:197], v[156:157], v[158:159] neg_lo:[0,1] neg_hi:[0,1]
	v_cvt_pk_bf16_f32 v195, v196, v197
	global_store_dwordx4 v212, v[188:191], s[10:11] offset:256
	global_store_dwordx4 v212, v[192:195], s[14:15] offset:256
	v_add_f32_e32 v207, v198, v199
	s_waitcnt vmcnt(14)
	v_lshlrev_b32_e32 v156, 16, v140
	v_and_b32_e32 v157, 0xffff0000, v140
	v_lshlrev_b32_e32 v158, 16, v144
	v_and_b32_e32 v159, 0xffff0000, v144
	v_pk_add_f32 v[156:157], v[156:157], v[158:159]
	v_pk_add_f32 v[156:157], v[30:31], v[156:157]
	v_cvt_pk_bf16_f32 v140, v156, v157
	v_pk_mul_f32 v[198:199], v[156:157], v[156:157]
	v_lshlrev_b32_e32 v158, 16, v140
	v_and_b32_e32 v159, 0xffff0000, v140
	v_pk_add_f32 v[196:197], v[156:157], v[158:159] neg_lo:[0,1] neg_hi:[0,1]
	v_cvt_pk_bf16_f32 v144, v196, v197
	v_lshlrev_b32_e32 v156, 16, v141
	v_and_b32_e32 v157, 0xffff0000, v141
	v_lshlrev_b32_e32 v158, 16, v145
	v_and_b32_e32 v159, 0xffff0000, v145
	v_pk_add_f32 v[156:157], v[156:157], v[158:159]
	v_pk_add_f32 v[156:157], v[32:33], v[156:157]
	v_cvt_pk_bf16_f32 v141, v156, v157
	v_pk_fma_f32 v[198:199], v[156:157], v[156:157], v[198:199]
	v_lshlrev_b32_e32 v158, 16, v141
	v_and_b32_e32 v159, 0xffff0000, v141
	v_pk_add_f32 v[196:197], v[156:157], v[158:159] neg_lo:[0,1] neg_hi:[0,1]
	v_cvt_pk_bf16_f32 v145, v196, v197
	v_lshlrev_b32_e32 v156, 16, v142
	v_and_b32_e32 v157, 0xffff0000, v142
	v_lshlrev_b32_e32 v158, 16, v146
	v_and_b32_e32 v159, 0xffff0000, v146
	v_pk_add_f32 v[156:157], v[156:157], v[158:159]
	v_pk_add_f32 v[156:157], v[26:27], v[156:157]
	v_cvt_pk_bf16_f32 v142, v156, v157
	v_pk_fma_f32 v[198:199], v[156:157], v[156:157], v[198:199]
	v_lshlrev_b32_e32 v158, 16, v142
	v_and_b32_e32 v159, 0xffff0000, v142
	v_pk_add_f32 v[196:197], v[156:157], v[158:159] neg_lo:[0,1] neg_hi:[0,1]
	v_cvt_pk_bf16_f32 v146, v196, v197
	v_lshlrev_b32_e32 v156, 16, v143
	v_and_b32_e32 v157, 0xffff0000, v143
	v_lshlrev_b32_e32 v158, 16, v147
	v_and_b32_e32 v159, 0xffff0000, v147
	v_pk_add_f32 v[156:157], v[156:157], v[158:159]
	v_pk_add_f32 v[156:157], v[28:29], v[156:157]
	v_cvt_pk_bf16_f32 v143, v156, v157
	v_pk_fma_f32 v[198:199], v[156:157], v[156:157], v[198:199]
	v_lshlrev_b32_e32 v158, 16, v143
	v_and_b32_e32 v159, 0xffff0000, v143
	v_pk_add_f32 v[196:197], v[156:157], v[158:159] neg_lo:[0,1] neg_hi:[0,1]
	v_cvt_pk_bf16_f32 v147, v196, v197
	global_store_dwordx4 v210, v[140:143], s[10:11]
	global_store_dwordx4 v210, v[144:147], s[14:15]
	s_waitcnt vmcnt(14)
; __device__ __forceinline__ unsigned pk2(float lo, float hi) { f32x2_t v = {lo, hi}; bf16x2_t b = __builtin_convertvector(v, bf16x2_t); return __builtin_bit_cast(unsigned, b); }
; __device__ __forceinline__ float bflo(unsigned u) { return __uint_as_float(u << 16); }
;     __device__ __forceinline__ void operator()(const f32x4 (&acc)[2][2][4][2], const Unit& u, int wr, int wc, int fr, int fq) const {
;     ...
;                 for (int bj = 0; bj < 2; ++bj) {
;                     const size_t off = (size_t)row * DM + col0 + bj * HALF;
;                     const u32x4 hh = *(const u32x4*)(HI + off), ll = *(const u32x4*)(LO + off);
;                     float hv[8] = {bflo(hh.x) + bflo(ll.x), bfhi(hh.x) + bfhi(ll.x), bflo(hh.y) + bflo(ll.y), bfhi(hh.y) + bfhi(ll.y),
;                                    bflo(hh.z) + bflo(ll.z), bfhi(hh.z) + bfhi(ll.z), bflo(hh.w) + bflo(ll.w), bfhi(hh.w) + bfhi(ll.w)};
;                     float av[8] = {acc[ai][bj][m][0][0], acc[ai][bj][m][0][1], acc[ai][bj][m][0][2], acc[ai][bj][m][0][3], acc[ai][bj][m][1][0], acc[ai][bj][m][1][1], acc[ai][bj][m][1][2], acc[ai][bj][m][1][3]};
;                     if (GATED) { const u32x4 pp = *(const u32x4*)(PP + off);
;                         const float pv[8] = {bflo(pp.x), bfhi(pp.x), bflo(pp.y), bfhi(pp.y), bflo(pp.z), bfhi(pp.z), bflo(pp.w), bfhi(pp.w)};
; #pragma unroll
;                         for (int e = 0; e < 8; ++e) av[e] = fast_sigmoid(av[e] * rs) * pv[e]; }
;                     else {
; #pragma unroll
;                         for (int e = 0; e < 8; ++e) av[e] *= alpha; }
;                     float lo[8];
; #pragma unroll
;                     for (int e = 0; e < 8; ++e) { hv[e] += av[e]; sq += hv[e] * hv[e]; }
;                     u32x4 wh; wh.x = pk2(hv[0], hv[1]); wh.y = pk2(hv[2], hv[3]); wh.z = pk2(hv[4], hv[5]); wh.w = pk2(hv[6], hv[7]);
;                     lo[0] = hv[0] - bflo(wh.x); lo[1] = hv[1] - bfhi(wh.x); lo[2] = hv[2] - bflo(wh.y); lo[3] = hv[3] - bfhi(wh.y);
;                     lo[4] = hv[4] - bflo(wh.z); lo[5] = hv[5] - bfhi(wh.z); lo[6] = hv[6] - bflo(wh.w); lo[7] = hv[7] - bfhi(wh.w);
;                     u32x4 wl; wl.x = pk2(lo[0], lo[1]); wl.y = pk2(lo[2], lo[3]); wl.z = pk2(lo[4], lo[5]); wl.w = pk2(lo[6], lo[7]);
;                     *(u32x4*)(HO + off) = wh; *(u32x4*)(LO + off) = wl;
	v_lshlrev_b32_e32 v156, 16, v148
	v_and_b32_e32 v157, 0xffff0000, v148
	v_lshlrev_b32_e32 v158, 16, v152
	v_and_b32_e32 v159, 0xffff0000, v152
	v_pk_add_f32 v[156:157], v[156:157], v[158:159]
	v_pk_add_f32 v[156:157], v[22:23], v[156:157]
	v_cvt_pk_bf16_f32 v148, v156, v157
	v_pk_fma_f32 v[198:199], v[156:157], v[156:157], v[198:199]
	v_lshlrev_b32_e32 v158, 16, v148
	v_and_b32_e32 v159, 0xffff0000, v148
	v_pk_add_f32 v[196:197], v[156:157], v[158:159] neg_lo:[0,1] neg_hi:[0,1]
	v_cvt_pk_bf16_f32 v152, v196, v197
	v_lshlrev_b32_e32 v156, 16, v149
	v_and_b32_e32 v157, 0xffff0000, v149
	v_lshlrev_b32_e32 v158, 16, v153
	v_and_b32_e32 v159, 0xffff0000, v153
	v_pk_add_f32 v[156:157], v[156:157], v[158:159]
	v_pk_add_f32 v[156:157], v[24:25], v[156:157]
	v_cvt_pk_bf16_f32 v149, v156, v157
	v_pk_fma_f32 v[198:199], v[156:157], v[156:157], v[198:199]
	v_lshlrev_b32_e32 v158, 16, v149
	v_and_b32_e32 v159, 0xffff0000, v149
	v_pk_add_f32 v[196:197], v[156:157], v[158:159] neg_lo:[0,1] neg_hi:[0,1]
	v_cvt_pk_bf16_f32 v153, v196, v197
	v_lshlrev_b32_e32 v156, 16, v150
	v_and_b32_e32 v157, 0xffff0000, v150
	v_lshlrev_b32_e32 v158, 16, v154
	v_and_b32_e32 v159, 0xffff0000, v154
	v_pk_add_f32 v[156:157], v[156:157], v[158:159]
	v_pk_add_f32 v[156:157], v[18:19], v[156:157]
	v_cvt_pk_bf16_f32 v150, v156, v157
	v_pk_fma_f32 v[198:199], v[156:157], v[156:157], v[198:199]
	v_lshlrev_b32_e32 v158, 16, v150
	v_and_b32_e32 v159, 0xffff0000, v150
	v_pk_add_f32 v[196:197], v[156:157], v[158:159] neg_lo:[0,1] neg_hi:[0,1]
	v_cvt_pk_bf16_f32 v154, v196, v197
	v_lshlrev_b32_e32 v156, 16, v151
	v_and_b32_e32 v157, 0xffff0000, v151
	v_lshlrev_b32_e32 v158, 16, v155
	v_and_b32_e32 v159, 0xffff0000, v155
	v_pk_add_f32 v[156:157], v[156:157], v[158:159]
	v_pk_add_f32 v[156:157], v[20:21], v[156:157]
	v_cvt_pk_bf16_f32 v151, v156, v157
	v_pk_fma_f32 v[198:199], v[156:157], v[156:157], v[198:199]
	v_lshlrev_b32_e32 v158, 16, v151
	v_and_b32_e32 v159, 0xffff0000, v151
	v_pk_add_f32 v[196:197], v[156:157], v[158:159] neg_lo:[0,1] neg_hi:[0,1]
	v_cvt_pk_bf16_f32 v155, v196, v197
	global_store_dwordx4 v210, v[148:151], s[10:11] offset:256
	global_store_dwordx4 v210, v[152:155], s[14:15] offset:256
	v_add_f32_e32 v208, v198, v199
	s_waitcnt vmcnt(10)
	v_lshlrev_b32_e32 v156, 16, v164
	v_and_b32_e32 v157, 0xffff0000, v164
	v_lshlrev_b32_e32 v158, 16, v168
	v_and_b32_e32 v159, 0xffff0000, v168
	v_pk_add_f32 v[156:157], v[156:157], v[158:159]
	v_pk_add_f32 v[156:157], v[14:15], v[156:157]
	v_cvt_pk_bf16_f32 v164, v156, v157
	v_pk_mul_f32 v[198:199], v[156:157], v[156:157]
	v_lshlrev_b32_e32 v158, 16, v164
	v_and_b32_e32 v159, 0xffff0000, v164
	v_pk_add_f32 v[196:197], v[156:157], v[158:159] neg_lo:[0,1] neg_hi:[0,1]
	v_cvt_pk_bf16_f32 v168, v196, v197
	v_lshlrev_b32_e32 v156, 16, v165
	v_and_b32_e32 v157, 0xffff0000, v165
	v_lshlrev_b32_e32 v158, 16, v169
	v_and_b32_e32 v159, 0xffff0000, v169
	v_pk_add_f32 v[156:157], v[156:157], v[158:159]
	v_pk_add_f32 v[156:157], v[16:17], v[156:157]
	v_cvt_pk_bf16_f32 v165, v156, v157
	v_pk_fma_f32 v[198:199], v[156:157], v[156:157], v[198:199]
	v_lshlrev_b32_e32 v158, 16, v165
	v_and_b32_e32 v159, 0xffff0000, v165
	v_pk_add_f32 v[196:197], v[156:157], v[158:159] neg_lo:[0,1] neg_hi:[0,1]
	v_cvt_pk_bf16_f32 v169, v196, v197
	v_lshlrev_b32_e32 v156, 16, v166
	v_and_b32_e32 v157, 0xffff0000, v166
	v_lshlrev_b32_e32 v158, 16, v170
	v_and_b32_e32 v159, 0xffff0000, v170
	v_pk_add_f32 v[156:157], v[156:157], v[158:159]
	v_pk_add_f32 v[156:157], v[10:11], v[156:157]
	v_cvt_pk_bf16_f32 v166, v156, v157
	v_pk_fma_f32 v[198:199], v[156:157], v[156:157], v[198:199]
	v_lshlrev_b32_e32 v158, 16, v166
	v_and_b32_e32 v159, 0xffff0000, v166
	v_pk_add_f32 v[196:197], v[156:157], v[158:159] neg_lo:[0,1] neg_hi:[0,1]
	v_cvt_pk_bf16_f32 v170, v196, v197
	v_lshlrev_b32_e32 v156, 16, v167
	v_and_b32_e32 v157, 0xffff0000, v167
	v_lshlrev_b32_e32 v158, 16, v171
	v_and_b32_e32 v159, 0xffff0000, v171
	v_pk_add_f32 v[156:157], v[156:157], v[158:159]
	v_pk_add_f32 v[156:157], v[12:13], v[156:157]
	v_cvt_pk_bf16_f32 v167, v156, v157
	v_pk_fma_f32 v[198:199], v[156:157], v[156:157], v[198:199]
	v_lshlrev_b32_e32 v158, 16, v167
	v_and_b32_e32 v159, 0xffff0000, v167
	v_pk_add_f32 v[196:197], v[156:157], v[158:159] neg_lo:[0,1] neg_hi:[0,1]
	v_cvt_pk_bf16_f32 v171, v196, v197
	global_store_dwordx4 v211, v[164:167], s[10:11]
	global_store_dwordx4 v211, v[168:171], s[14:15]
	s_waitcnt vmcnt(10)
; __device__ __forceinline__ float bflo(unsigned u) { return __uint_as_float(u << 16); }
;     __device__ __forceinline__ void operator()(const f32x4 (&acc)[2][2][4][2], const Unit& u, int wr, int wc, int fr, int fq) const {
;     ...
;                 for (int bj = 0; bj < 2; ++bj) {
;                     const size_t off = (size_t)row * DM + col0 + bj * HALF;
;                     const u32x4 hh = *(const u32x4*)(HI + off), ll = *(const u32x4*)(LO + off);
;                     float hv[8] = {bflo(hh.x) + bflo(ll.x), bfhi(hh.x) + bfhi(ll.x), bflo(hh.y) + bflo(ll.y), bfhi(hh.y) + bfhi(ll.y),
;                                    bflo(hh.z) + bflo(ll.z), bfhi(hh.z) + bfhi(ll.z), bflo(hh.w) + bflo(ll.w), bfhi(hh.w) + bfhi(ll.w)};
;                     float av[8] = {acc[ai][bj][m][0][0], acc[ai][bj][m][0][1], acc[ai][bj][m][0][2], acc[ai][bj][m][0][3], acc[ai][bj][m][1][0], acc[ai][bj][m][1][1], acc[ai][bj][m][1][2], acc[ai][bj][m][1][3]};
;                     if (GATED) { const u32x4 pp = *(const u32x4*)(PP + off);
;                         const float pv[8] = {bflo(pp.x), bfhi(pp.x), bflo(pp.y), bfhi(pp.y), bflo(pp.z), bfhi(pp.z), bflo(pp.w), bfhi(pp.w)};
; #pragma unroll
;                         for (int e = 0; e < 8; ++e) av[e] = fast_sigmoid(av[e] * rs) * pv[e]; }
;                     else {
; #pragma unroll
;                         for (int e = 0; e < 8; ++e) av[e] *= alpha; }
;                     float lo[8];
; #pragma unroll
;                     for (int e = 0; e < 8; ++e) { hv[e] += av[e]; sq += hv[e] * hv[e]; }
;                     u32x4 wh; wh.x = pk2(hv[0], hv[1]); wh.y = pk2(hv[2], hv[3]); wh.z = pk2(hv[4], hv[5]); wh.w = pk2(hv[6], hv[7]);
;                     lo[0] = hv[0] - bflo(wh.x); lo[1] = hv[1] - bfhi(wh.x); lo[2] = hv[2] - bflo(wh.y); lo[3] = hv[3] - bfhi(wh.y);
;                     lo[4] = hv[4] - bflo(wh.z); lo[5] = hv[5] - bfhi(wh.z); lo[6] = hv[6] - bflo(wh.w); lo[7] = hv[7] - bfhi(wh.w);
;                     u32x4 wl; wl.x = pk2(lo[0], lo[1]); wl.y = pk2(lo[2], lo[3]); wl.z = pk2(lo[4], lo[5]); wl.w = pk2(lo[6], lo[7]);
;                     *(u32x4*)(HO + off) = wh; *(u32x4*)(LO + off) = wl;
;                 }
;                 sq += __shfl_xor(sq, 16); sq += __shfl_xor(sq, 32);
;                 if (fq == 0) ssq_out[(size_t)row * 16 + 4 * u.pn + wc] = sq;
	v_lshlrev_b32_e32 v156, 16, v172
	v_and_b32_e32 v157, 0xffff0000, v172
	v_lshlrev_b32_e32 v158, 16, v176
	v_and_b32_e32 v159, 0xffff0000, v176
	v_pk_add_f32 v[156:157], v[156:157], v[158:159]
	v_pk_add_f32 v[156:157], v[6:7], v[156:157]
	v_cvt_pk_bf16_f32 v172, v156, v157
	v_pk_fma_f32 v[198:199], v[156:157], v[156:157], v[198:199]
	v_lshlrev_b32_e32 v158, 16, v172
	v_and_b32_e32 v159, 0xffff0000, v172
	v_pk_add_f32 v[196:197], v[156:157], v[158:159] neg_lo:[0,1] neg_hi:[0,1]
	v_cvt_pk_bf16_f32 v176, v196, v197
	v_lshlrev_b32_e32 v156, 16, v173
	v_and_b32_e32 v157, 0xffff0000, v173
	v_lshlrev_b32_e32 v158, 16, v177
	v_and_b32_e32 v159, 0xffff0000, v177
	v_pk_add_f32 v[156:157], v[156:157], v[158:159]
	v_pk_add_f32 v[156:157], v[8:9], v[156:157]
	v_cvt_pk_bf16_f32 v173, v156, v157
	v_pk_fma_f32 v[198:199], v[156:157], v[156:157], v[198:199]
	v_lshlrev_b32_e32 v158, 16, v173
	v_and_b32_e32 v159, 0xffff0000, v173
	v_pk_add_f32 v[196:197], v[156:157], v[158:159] neg_lo:[0,1] neg_hi:[0,1]
	v_cvt_pk_bf16_f32 v177, v196, v197
	v_lshlrev_b32_e32 v156, 16, v174
	v_and_b32_e32 v157, 0xffff0000, v174
	v_lshlrev_b32_e32 v158, 16, v178
	v_and_b32_e32 v159, 0xffff0000, v178
	v_pk_add_f32 v[156:157], v[156:157], v[158:159]
	v_pk_add_f32 v[156:157], v[2:3], v[156:157]
	v_cvt_pk_bf16_f32 v174, v156, v157
	v_pk_fma_f32 v[198:199], v[156:157], v[156:157], v[198:199]
	v_lshlrev_b32_e32 v158, 16, v174
	v_and_b32_e32 v159, 0xffff0000, v174
	v_pk_add_f32 v[196:197], v[156:157], v[158:159] neg_lo:[0,1] neg_hi:[0,1]
	v_cvt_pk_bf16_f32 v178, v196, v197
	v_lshlrev_b32_e32 v156, 16, v175
	v_and_b32_e32 v157, 0xffff0000, v175
	v_lshlrev_b32_e32 v158, 16, v179
	v_and_b32_e32 v159, 0xffff0000, v179
	v_pk_add_f32 v[156:157], v[156:157], v[158:159]
	v_pk_add_f32 v[156:157], v[4:5], v[156:157]
	v_cvt_pk_bf16_f32 v175, v156, v157
	v_pk_fma_f32 v[198:199], v[156:157], v[156:157], v[198:199]
	v_lshlrev_b32_e32 v158, 16, v175
	v_and_b32_e32 v159, 0xffff0000, v175
	v_pk_add_f32 v[196:197], v[156:157], v[158:159] neg_lo:[0,1] neg_hi:[0,1]
	v_cvt_pk_bf16_f32 v179, v196, v197
	global_store_dwordx4 v211, v[172:175], s[10:11] offset:256
	global_store_dwordx4 v211, v[176:179], s[14:15] offset:256
	v_add_f32_e32 v209, v198, v199
	ds_bpermute_b32 v140, v214, v200
	ds_bpermute_b32 v141, v214, v201
	ds_bpermute_b32 v142, v214, v202
	ds_bpermute_b32 v143, v214, v203
	ds_bpermute_b32 v144, v214, v206
	ds_bpermute_b32 v145, v214, v207
	ds_bpermute_b32 v146, v214, v208
	ds_bpermute_b32 v147, v214, v209
	s_waitcnt lgkmcnt(0)
	v_add_f32_e32 v200, v200, v140
	v_add_f32_e32 v201, v201, v141
	v_add_f32_e32 v202, v202, v142
	v_add_f32_e32 v203, v203, v143
	v_add_f32_e32 v206, v206, v144
	v_add_f32_e32 v207, v207, v145
	v_add_f32_e32 v208, v208, v146
	v_add_f32_e32 v209, v209, v147
	ds_bpermute_b32 v140, v215, v200
	ds_bpermute_b32 v141, v215, v201
	ds_bpermute_b32 v142, v215, v202
	ds_bpermute_b32 v143, v215, v203
	ds_bpermute_b32 v144, v215, v206
	ds_bpermute_b32 v145, v215, v207
	ds_bpermute_b32 v146, v215, v208
	ds_bpermute_b32 v147, v215, v209
	s_waitcnt lgkmcnt(0)
	v_add_f32_e32 v200, v200, v140
	v_add_f32_e32 v201, v201, v141
	v_add_f32_e32 v202, v202, v142
	v_add_f32_e32 v203, v203, v143
	v_add_f32_e32 v206, v206, v144
	v_add_f32_e32 v207, v207, v145
	v_add_f32_e32 v208, v208, v146
	v_add_f32_e32 v209, v209, v147
	s_and_saveexec_b64 s[26:27], s[44:45]
	s_cbranch_execz .Lepir_wout_skip
	global_store_dword v216, v200, s[16:17]
	global_store_dword v216, v201, s[16:17] offset:1024
	global_store_dword v216, v202, s[16:17] offset:2048
	global_store_dword v216, v203, s[16:17] offset:3072
	global_store_dword v217, v206, s[16:17]
	global_store_dword v217, v207, s[16:17] offset:1024
	global_store_dword v217, v208, s[16:17] offset:2048
	global_store_dword v217, v209, s[16:17] offset:3072

;     __device__ __forceinline__ void operator()(const f32x4 (&acc)[2][2][4][2], const Unit& u, int wr, int wc, int fr, int fq) const {
;     ...
;                     const size_t off = (size_t)row * DM + col0 + bj * HALF;
;                     const u32x4 hh = *(const u32x4*)(HI + off), ll = *(const u32x4*)(LO + off);
.LBB0_1247:
	s_cmp_eq_u32 s34, 36
	s_cbranch_scc0 .Lpre_f2d_skip
	v_readlane_b32 s100, v253, 35
	v_readlane_b32 s101, v253, 36
	v_readlane_b32 s98, v250, 49
	v_readlane_b32 s99, v250, 50
	v_lshl_add_u32 v243, s31, 8, v160
	v_lshl_or_b32 v246, s4, 8, v162
	v_lshl_add_u32 v243, v243, 10, v246
	v_lshlrev_b32_e32 v243, 1, v243
	s_nop 1
	global_load_dwordx4 v[226:229], v243, s[100:101]
	global_load_dwordx4 v[230:233], v243, s[98:99]
	global_load_dwordx4 v[234:237], v243, s[100:101] offset:256
	global_load_dwordx4 v[242:245], v243, s[98:99] offset:256

; __device__ __forceinline__ float bflo(unsigned u) { return __uint_as_float(u << 16); }
;     __device__ __forceinline__ void operator()(const f32x4 (&acc)[2][2][4][2], const Unit& u, int wr, int wc, int fr, int fq) const {
;     ...
;                 const int row = row0 + ai * HALF + m * 16;
;                 float rs = 0.f; if (GATED) rs = rsqrtf(row_ssq(ssq_in, 16, 4, row, fq) * (1.f / 1024.f) + EPS);
;                 float sq = 0.f;
; #pragma unroll
;                 for (int bj = 0; bj < 2; ++bj) {
;                     const size_t off = (size_t)row * DM + col0 + bj * HALF;
;                     const u32x4 hh = *(const u32x4*)(HI + off), ll = *(const u32x4*)(LO + off);
;                     float hv[8] = {bflo(hh.x) + bflo(ll.x), bfhi(hh.x) + bfhi(ll.x), bflo(hh.y) + bflo(ll.y), bfhi(hh.y) + bfhi(ll.y),
;                                    bflo(hh.z) + bflo(ll.z), bfhi(hh.z) + bfhi(ll.z), bflo(hh.w) + bflo(ll.w), bfhi(hh.w) + bfhi(ll.w)};
;                     float av[8] = {acc[ai][bj][m][0][0], acc[ai][bj][m][0][1], acc[ai][bj][m][0][2], acc[ai][bj][m][0][3], acc[ai][bj][m][1][0], acc[ai][bj][m][1][1], acc[ai][bj][m][1][2], acc[ai][bj][m][1][3]};
;                     if (GATED) { const u32x4 pp = *(const u32x4*)(PP + off);
;                         const float pv[8] = {bflo(pp.x), bfhi(pp.x), bflo(pp.y), bfhi(pp.y), bflo(pp.z), bfhi(pp.z), bflo(pp.w), bfhi(pp.w)};
; #pragma unroll
;                         for (int e = 0; e < 8; ++e) av[e] = fast_sigmoid(av[e] * rs) * pv[e]; }
;                     else {
; #pragma unroll
;                         for (int e = 0; e < 8; ++e) av[e] *= alpha; }
;                     float lo[8];
; #pragma unroll
;                     for (int e = 0; e < 8; ++e) { hv[e] += av[e]; sq += hv[e] * hv[e]; }
;                     u32x4 wh; wh.x = pk2(hv[0], hv[1]); wh.y = pk2(hv[2], hv[3]); wh.z = pk2(hv[4], hv[5]); wh.w = pk2(hv[6], hv[7]);
;                     lo[0] = hv[0] - bflo(wh.x); lo[1] = hv[1] - bfhi(wh.x); lo[2] = hv[2] - bflo(wh.y); lo[3] = hv[3] - bfhi(wh.y);
;                     lo[4] = hv[4] - bflo(wh.z); lo[5] = hv[5] - bfhi(wh.z); lo[6] = hv[6] - bflo(wh.w); lo[7] = hv[7] - bfhi(wh.w);
;                     u32x4 wl; wl.x = pk2(lo[0], lo[1]); wl.y = pk2(lo[2], lo[3]); wl.z = pk2(lo[4], lo[5]); wl.w = pk2(lo[6], lo[7]);
;                     *(u32x4*)(HO + off) = wh; *(u32x4*)(LO + off) = wl;
.LBB0_1250:
	v_and_b32_e32 v158, 64, v241
	v_xor_b32_e32 v214, 16, v241
	v_add_u32_e32 v158, 64, v158
	v_cmp_lt_i32_e32 vcc, v214, v158
	v_lshl_add_u32 v156, s31, 8, v160
	v_lshl_or_b32 v157, s4, 8, v162
	v_cndmask_b32_e32 v214, v241, v214, vcc
	v_lshlrev_b32_e32 v214, 2, v214
	v_xor_b32_e32 v215, 32, v241
	v_cmp_lt_i32_e32 vcc, v215, v158
	v_readlane_b32 s10, v253, 35
	v_readlane_b32 s11, v253, 36
	v_readlane_b32 s6, v250, 49
	v_readlane_b32 s7, v250, 50
	s_nop 1
	v_cndmask_b32_e32 v215, v241, v215, vcc
	v_lshlrev_b32_e32 v215, 2, v215
	v_lshl_add_u32 v213, v156, 10, v157
	v_lshlrev_b32_e32 v213, 1, v213
	s_lshl_b32 s40, s4, 4
	s_lshl_b32 s50, s25, 2
	s_add_i32 s40, s40, s50
	v_lshlrev_b32_e32 v216, 6, v156
	v_add_u32_e32 v216, s40, v216
	v_add_u32_e32 v217, 0x2000, v216
	s_nop 1
	v_add_u32_e32 v211, 0x8000, v213
	global_load_dwordx4 v[164:167], v211, s[10:11]
	global_load_dwordx4 v[168:171], v211, s[6:7]
	global_load_dwordx4 v[172:175], v211, s[10:11] offset:256
	global_load_dwordx4 v[176:179], v211, s[6:7] offset:256
	v_add_u32_e32 v212, 0x10000, v213
	global_load_dwordx4 v[180:183], v212, s[10:11]
	global_load_dwordx4 v[184:187], v212, s[6:7]
	global_load_dwordx4 v[188:191], v212, s[10:11] offset:256
	global_load_dwordx4 v[192:195], v212, s[6:7] offset:256
	v_add_u32_e32 v210, 0x18000, v213
	global_load_dwordx4 v[140:143], v210, s[10:11]
	global_load_dwordx4 v[144:147], v210, s[6:7]
	global_load_dwordx4 v[148:151], v210, s[10:11] offset:256
	global_load_dwordx4 v[152:155], v210, s[6:7] offset:256
	s_waitcnt vmcnt(12)
	v_lshlrev_b32_e32 v156, 16, v226
	v_and_b32_e32 v157, 0xffff0000, v226
	v_lshlrev_b32_e32 v158, 16, v230
	v_and_b32_e32 v159, 0xffff0000, v230
	v_pk_add_f32 v[156:157], v[156:157], v[158:159]
	v_pk_fma_f32 v[156:157], v[126:127], 0.5, v[156:157] op_sel_hi:[1,0,1]
	v_cvt_pk_bf16_f32 v226, v156, v157
	v_pk_mul_f32 v[198:199], v[156:157], v[156:157]
	v_lshlrev_b32_e32 v158, 16, v226
	v_and_b32_e32 v159, 0xffff0000, v226
	v_pk_add_f32 v[196:197], v[156:157], v[158:159] neg_lo:[0,1] neg_hi:[0,1]
	v_cvt_pk_bf16_f32 v230, v196, v197
	v_lshlrev_b32_e32 v156, 16, v227
	v_and_b32_e32 v157, 0xffff0000, v227
	v_lshlrev_b32_e32 v158, 16, v231
	v_and_b32_e32 v159, 0xffff0000, v231
	v_pk_add_f32 v[156:157], v[156:157], v[158:159]
	v_pk_fma_f32 v[156:157], v[128:129], 0.5, v[156:157] op_sel_hi:[1,0,1]
	v_cvt_pk_bf16_f32 v227, v156, v157
	v_pk_fma_f32 v[198:199], v[156:157], v[156:157], v[198:199]
	v_lshlrev_b32_e32 v158, 16, v227
	v_and_b32_e32 v159, 0xffff0000, v227
	v_pk_add_f32 v[196:197], v[156:157], v[158:159] neg_lo:[0,1] neg_hi:[0,1]
	v_cvt_pk_bf16_f32 v231, v196, v197
	v_lshlrev_b32_e32 v156, 16, v228
	v_and_b32_e32 v157, 0xffff0000, v228
	v_lshlrev_b32_e32 v158, 16, v232
	v_and_b32_e32 v159, 0xffff0000, v232
	v_pk_add_f32 v[156:157], v[156:157], v[158:159]
	v_pk_fma_f32 v[156:157], v[122:123], 0.5, v[156:157] op_sel_hi:[1,0,1]
	v_cvt_pk_bf16_f32 v228, v156, v157
	v_pk_fma_f32 v[198:199], v[156:157], v[156:157], v[198:199]
	v_lshlrev_b32_e32 v158, 16, v228
	v_and_b32_e32 v159, 0xffff0000, v228
	v_pk_add_f32 v[196:197], v[156:157], v[158:159] neg_lo:[0,1] neg_hi:[0,1]
	v_cvt_pk_bf16_f32 v232, v196, v197
	v_lshlrev_b32_e32 v156, 16, v229
	v_and_b32_e32 v157, 0xffff0000, v229
	v_lshlrev_b32_e32 v158, 16, v233
	v_and_b32_e32 v159, 0xffff0000, v233
	v_pk_add_f32 v[156:157], v[156:157], v[158:159]
	v_pk_fma_f32 v[156:157], v[124:125], 0.5, v[156:157] op_sel_hi:[1,0,1]
	v_cvt_pk_bf16_f32 v229, v156, v157
	v_pk_fma_f32 v[198:199], v[156:157], v[156:157], v[198:199]
	v_lshlrev_b32_e32 v158, 16, v229
	v_and_b32_e32 v159, 0xffff0000, v229
	v_pk_add_f32 v[196:197], v[156:157], v[158:159] neg_lo:[0,1] neg_hi:[0,1]
	v_cvt_pk_bf16_f32 v233, v196, v197
	global_store_dwordx4 v213, v[226:229], s[10:11]
	global_store_dwordx4 v213, v[230:233], s[6:7]
	v_lshlrev_b32_e32 v156, 16, v234
	v_and_b32_e32 v157, 0xffff0000, v234
	v_lshlrev_b32_e32 v158, 16, v242
	v_and_b32_e32 v159, 0xffff0000, v242
	v_pk_add_f32 v[156:157], v[156:157], v[158:159]
	v_pk_fma_f32 v[156:157], v[118:119], 0.5, v[156:157] op_sel_hi:[1,0,1]
	v_cvt_pk_bf16_f32 v234, v156, v157
	v_pk_fma_f32 v[198:199], v[156:157], v[156:157], v[198:199]
	v_lshlrev_b32_e32 v158, 16, v234
	v_and_b32_e32 v159, 0xffff0000, v234
	v_pk_add_f32 v[196:197], v[156:157], v[158:159] neg_lo:[0,1] neg_hi:[0,1]
	v_cvt_pk_bf16_f32 v242, v196, v197
	v_lshlrev_b32_e32 v156, 16, v235
	v_and_b32_e32 v157, 0xffff0000, v235
	v_lshlrev_b32_e32 v158, 16, v243
	v_and_b32_e32 v159, 0xffff0000, v243
	v_pk_add_f32 v[156:157], v[156:157], v[158:159]
	v_pk_fma_f32 v[156:157], v[120:121], 0.5, v[156:157] op_sel_hi:[1,0,1]
	v_cvt_pk_bf16_f32 v235, v156, v157
	v_pk_fma_f32 v[198:199], v[156:157], v[156:157], v[198:199]
	v_lshlrev_b32_e32 v158, 16, v235
	v_and_b32_e32 v159, 0xffff0000, v235
	v_pk_add_f32 v[196:197], v[156:157], v[158:159] neg_lo:[0,1] neg_hi:[0,1]
	v_cvt_pk_bf16_f32 v243, v196, v197
	v_lshlrev_b32_e32 v156, 16, v236
	v_and_b32_e32 v157, 0xffff0000, v236
	v_lshlrev_b32_e32 v158, 16, v244
	v_and_b32_e32 v159, 0xffff0000, v244
	v_pk_add_f32 v[156:157], v[156:157], v[158:159]
	v_pk_fma_f32 v[156:157], v[114:115], 0.5, v[156:157] op_sel_hi:[1,0,1]
	v_cvt_pk_bf16_f32 v236, v156, v157
	v_pk_fma_f32 v[198:199], v[156:157], v[156:157], v[198:199]
	v_lshlrev_b32_e32 v158, 16, v236
	v_and_b32_e32 v159, 0xffff0000, v236
	v_pk_add_f32 v[196:197], v[156:157], v[158:159] neg_lo:[0,1] neg_hi:[0,1]
	v_cvt_pk_bf16_f32 v244, v196, v197
	v_lshlrev_b32_e32 v156, 16, v237
	v_and_b32_e32 v157, 0xffff0000, v237
	v_lshlrev_b32_e32 v158, 16, v245
	v_and_b32_e32 v159, 0xffff0000, v245
	v_pk_add_f32 v[156:157], v[156:157], v[158:159]
	v_pk_fma_f32 v[156:157], v[116:117], 0.5, v[156:157] op_sel_hi:[1,0,1]
	v_cvt_pk_bf16_f32 v237, v156, v157
	v_pk_fma_f32 v[198:199], v[156:157], v[156:157], v[198:199]
	v_lshlrev_b32_e32 v158, 16, v237
	v_and_b32_e32 v159, 0xffff0000, v237
	v_pk_add_f32 v[196:197], v[156:157], v[158:159] neg_lo:[0,1] neg_hi:[0,1]
	v_cvt_pk_bf16_f32 v245, v196, v197
	global_store_dwordx4 v213, v[234:237], s[10:11] offset:256
	global_store_dwordx4 v213, v[242:245], s[6:7] offset:256
	v_add_f32_e32 v200, v198, v199
	s_waitcnt vmcnt(14)
; __device__ __forceinline__ unsigned pk2(float lo, float hi) { f32x2_t v = {lo, hi}; bf16x2_t b = __builtin_convertvector(v, bf16x2_t); return __builtin_bit_cast(unsigned, b); }
; __device__ __forceinline__ float bflo(unsigned u) { return __uint_as_float(u << 16); }
;     __device__ __forceinline__ void operator()(const f32x4 (&acc)[2][2][4][2], const Unit& u, int wr, int wc, int fr, int fq) const {
;     ...
;                 for (int bj = 0; bj < 2; ++bj) {
;                     const size_t off = (size_t)row * DM + col0 + bj * HALF;
;                     const u32x4 hh = *(const u32x4*)(HI + off), ll = *(const u32x4*)(LO + off);
;                     float hv[8] = {bflo(hh.x) + bflo(ll.x), bfhi(hh.x) + bfhi(ll.x), bflo(hh.y) + bflo(ll.y), bfhi(hh.y) + bfhi(ll.y),
;                                    bflo(hh.z) + bflo(ll.z), bfhi(hh.z) + bfhi(ll.z), bflo(hh.w) + bflo(ll.w), bfhi(hh.w) + bfhi(ll.w)};
;                     float av[8] = {acc[ai][bj][m][0][0], acc[ai][bj][m][0][1], acc[ai][bj][m][0][2], acc[ai][bj][m][0][3], acc[ai][bj][m][1][0], acc[ai][bj][m][1][1], acc[ai][bj][m][1][2], acc[ai][bj][m][1][3]};
;                     if (GATED) { const u32x4 pp = *(const u32x4*)(PP + off);
;                         const float pv[8] = {bflo(pp.x), bfhi(pp.x), bflo(pp.y), bfhi(pp.y), bflo(pp.z), bfhi(pp.z), bflo(pp.w), bfhi(pp.w)};
; #pragma unroll
;                         for (int e = 0; e < 8; ++e) av[e] = fast_sigmoid(av[e] * rs) * pv[e]; }
;                     else {
; #pragma unroll
;                         for (int e = 0; e < 8; ++e) av[e] *= alpha; }
;                     float lo[8];
; #pragma unroll
;                     for (int e = 0; e < 8; ++e) { hv[e] += av[e]; sq += hv[e] * hv[e]; }
;                     u32x4 wh; wh.x = pk2(hv[0], hv[1]); wh.y = pk2(hv[2], hv[3]); wh.z = pk2(hv[4], hv[5]); wh.w = pk2(hv[6], hv[7]);
;                     lo[0] = hv[0] - bflo(wh.x); lo[1] = hv[1] - bfhi(wh.x); lo[2] = hv[2] - bflo(wh.y); lo[3] = hv[3] - bfhi(wh.y);
;                     lo[4] = hv[4] - bflo(wh.z); lo[5] = hv[5] - bfhi(wh.z); lo[6] = hv[6] - bflo(wh.w); lo[7] = hv[7] - bfhi(wh.w);
;                     u32x4 wl; wl.x = pk2(lo[0], lo[1]); wl.y = pk2(lo[2], lo[3]); wl.z = pk2(lo[4], lo[5]); wl.w = pk2(lo[6], lo[7]);
;                     *(u32x4*)(HO + off) = wh; *(u32x4*)(LO + off) = wl;
	v_lshlrev_b32_e32 v156, 16, v164
	v_and_b32_e32 v157, 0xffff0000, v164
	v_lshlrev_b32_e32 v158, 16, v168
	v_and_b32_e32 v159, 0xffff0000, v168
	v_pk_add_f32 v[156:157], v[156:157], v[158:159]
	v_pk_fma_f32 v[156:157], v[110:111], 0.5, v[156:157] op_sel_hi:[1,0,1]
	v_cvt_pk_bf16_f32 v164, v156, v157
	v_pk_mul_f32 v[198:199], v[156:157], v[156:157]
	v_lshlrev_b32_e32 v158, 16, v164
	v_and_b32_e32 v159, 0xffff0000, v164
	v_pk_add_f32 v[196:197], v[156:157], v[158:159] neg_lo:[0,1] neg_hi:[0,1]
	v_cvt_pk_bf16_f32 v168, v196, v197
	v_lshlrev_b32_e32 v156, 16, v165
	v_and_b32_e32 v157, 0xffff0000, v165
	v_lshlrev_b32_e32 v158, 16, v169
	v_and_b32_e32 v159, 0xffff0000, v169
	v_pk_add_f32 v[156:157], v[156:157], v[158:159]
	v_pk_fma_f32 v[156:157], v[112:113], 0.5, v[156:157] op_sel_hi:[1,0,1]
	v_cvt_pk_bf16_f32 v165, v156, v157
	v_pk_fma_f32 v[198:199], v[156:157], v[156:157], v[198:199]
	v_lshlrev_b32_e32 v158, 16, v165
	v_and_b32_e32 v159, 0xffff0000, v165
	v_pk_add_f32 v[196:197], v[156:157], v[158:159] neg_lo:[0,1] neg_hi:[0,1]
	v_cvt_pk_bf16_f32 v169, v196, v197
	v_lshlrev_b32_e32 v156, 16, v166
	v_and_b32_e32 v157, 0xffff0000, v166
	v_lshlrev_b32_e32 v158, 16, v170
	v_and_b32_e32 v159, 0xffff0000, v170
	v_pk_add_f32 v[156:157], v[156:157], v[158:159]
	v_pk_fma_f32 v[156:157], v[106:107], 0.5, v[156:157] op_sel_hi:[1,0,1]
	v_cvt_pk_bf16_f32 v166, v156, v157
	v_pk_fma_f32 v[198:199], v[156:157], v[156:157], v[198:199]
	v_lshlrev_b32_e32 v158, 16, v166
	v_and_b32_e32 v159, 0xffff0000, v166
	v_pk_add_f32 v[196:197], v[156:157], v[158:159] neg_lo:[0,1] neg_hi:[0,1]
	v_cvt_pk_bf16_f32 v170, v196, v197
	v_lshlrev_b32_e32 v156, 16, v167
	v_and_b32_e32 v157, 0xffff0000, v167
	v_lshlrev_b32_e32 v158, 16, v171
	v_and_b32_e32 v159, 0xffff0000, v171
	v_pk_add_f32 v[156:157], v[156:157], v[158:159]
	v_pk_fma_f32 v[156:157], v[108:109], 0.5, v[156:157] op_sel_hi:[1,0,1]
	v_cvt_pk_bf16_f32 v167, v156, v157
	v_pk_fma_f32 v[198:199], v[156:157], v[156:157], v[198:199]
	v_lshlrev_b32_e32 v158, 16, v167
	v_and_b32_e32 v159, 0xffff0000, v167
	v_pk_add_f32 v[196:197], v[156:157], v[158:159] neg_lo:[0,1] neg_hi:[0,1]
	v_cvt_pk_bf16_f32 v171, v196, v197
	global_store_dwordx4 v211, v[164:167], s[10:11]
	global_store_dwordx4 v211, v[168:171], s[6:7]
	s_waitcnt vmcnt(14)
	v_lshlrev_b32_e32 v156, 16, v172
	v_and_b32_e32 v157, 0xffff0000, v172
	v_lshlrev_b32_e32 v158, 16, v176
	v_and_b32_e32 v159, 0xffff0000, v176
	v_pk_add_f32 v[156:157], v[156:157], v[158:159]
	v_pk_fma_f32 v[156:157], v[102:103], 0.5, v[156:157] op_sel_hi:[1,0,1]
	v_cvt_pk_bf16_f32 v172, v156, v157
	v_pk_fma_f32 v[198:199], v[156:157], v[156:157], v[198:199]
	v_lshlrev_b32_e32 v158, 16, v172
	v_and_b32_e32 v159, 0xffff0000, v172
	v_pk_add_f32 v[196:197], v[156:157], v[158:159] neg_lo:[0,1] neg_hi:[0,1]
	v_cvt_pk_bf16_f32 v176, v196, v197
	v_lshlrev_b32_e32 v156, 16, v173
	v_and_b32_e32 v157, 0xffff0000, v173
	v_lshlrev_b32_e32 v158, 16, v177
	v_and_b32_e32 v159, 0xffff0000, v177
	v_pk_add_f32 v[156:157], v[156:157], v[158:159]
	v_pk_fma_f32 v[156:157], v[104:105], 0.5, v[156:157] op_sel_hi:[1,0,1]
	v_cvt_pk_bf16_f32 v173, v156, v157
	v_pk_fma_f32 v[198:199], v[156:157], v[156:157], v[198:199]
	v_lshlrev_b32_e32 v158, 16, v173
	v_and_b32_e32 v159, 0xffff0000, v173
	v_pk_add_f32 v[196:197], v[156:157], v[158:159] neg_lo:[0,1] neg_hi:[0,1]
	v_cvt_pk_bf16_f32 v177, v196, v197
	v_lshlrev_b32_e32 v156, 16, v174
	v_and_b32_e32 v157, 0xffff0000, v174
	v_lshlrev_b32_e32 v158, 16, v178
	v_and_b32_e32 v159, 0xffff0000, v178
	v_pk_add_f32 v[156:157], v[156:157], v[158:159]
	v_pk_fma_f32 v[156:157], v[98:99], 0.5, v[156:157] op_sel_hi:[1,0,1]
	v_cvt_pk_bf16_f32 v174, v156, v157
	v_pk_fma_f32 v[198:199], v[156:157], v[156:157], v[198:199]
	v_lshlrev_b32_e32 v158, 16, v174
	v_and_b32_e32 v159, 0xffff0000, v174
	v_pk_add_f32 v[196:197], v[156:157], v[158:159] neg_lo:[0,1] neg_hi:[0,1]
	v_cvt_pk_bf16_f32 v178, v196, v197
	v_lshlrev_b32_e32 v156, 16, v175
	v_and_b32_e32 v157, 0xffff0000, v175
	v_lshlrev_b32_e32 v158, 16, v179
	v_and_b32_e32 v159, 0xffff0000, v179
	v_pk_add_f32 v[156:157], v[156:157], v[158:159]
	v_pk_fma_f32 v[156:157], v[100:101], 0.5, v[156:157] op_sel_hi:[1,0,1]
	v_cvt_pk_bf16_f32 v175, v156, v157
	v_pk_fma_f32 v[198:199], v[156:157], v[156:157], v[198:199]
	v_lshlrev_b32_e32 v158, 16, v175
	v_and_b32_e32 v159, 0xffff0000, v175
	v_pk_add_f32 v[196:197], v[156:157], v[158:159] neg_lo:[0,1] neg_hi:[0,1]
	v_cvt_pk_bf16_f32 v179, v196, v197
	global_store_dwordx4 v211, v[172:175], s[10:11] offset:256
	global_store_dwordx4 v211, v[176:179], s[6:7] offset:256
	v_add_f32_e32 v201, v198, v199
	s_nop 0
	v_add_u32_e32 v211, 0x40000, v213
	global_load_dwordx4 v[164:167], v211, s[10:11]
	global_load_dwordx4 v[168:171], v211, s[6:7]
	global_load_dwordx4 v[172:175], v211, s[10:11] offset:256
	global_load_dwordx4 v[176:179], v211, s[6:7] offset:256
	s_waitcnt vmcnt(18)
; __device__ __forceinline__ unsigned pk2(float lo, float hi) { f32x2_t v = {lo, hi}; bf16x2_t b = __builtin_convertvector(v, bf16x2_t); return __builtin_bit_cast(unsigned, b); }
; __device__ __forceinline__ float bflo(unsigned u) { return __uint_as_float(u << 16); }
;     __device__ __forceinline__ void operator()(const f32x4 (&acc)[2][2][4][2], const Unit& u, int wr, int wc, int fr, int fq) const {
;     ...
;                 for (int bj = 0; bj < 2; ++bj) {
;                     const size_t off = (size_t)row * DM + col0 + bj * HALF;
;                     const u32x4 hh = *(const u32x4*)(HI + off), ll = *(const u32x4*)(LO + off);
;                     float hv[8] = {bflo(hh.x) + bflo(ll.x), bfhi(hh.x) + bfhi(ll.x), bflo(hh.y) + bflo(ll.y), bfhi(hh.y) + bfhi(ll.y),
;                                    bflo(hh.z) + bflo(ll.z), bfhi(hh.z) + bfhi(ll.z), bflo(hh.w) + bflo(ll.w), bfhi(hh.w) + bfhi(ll.w)};
;                     float av[8] = {acc[ai][bj][m][0][0], acc[ai][bj][m][0][1], acc[ai][bj][m][0][2], acc[ai][bj][m][0][3], acc[ai][bj][m][1][0], acc[ai][bj][m][1][1], acc[ai][bj][m][1][2], acc[ai][bj][m][1][3]};
;                     if (GATED) { const u32x4 pp = *(const u32x4*)(PP + off);
;                         const float pv[8] = {bflo(pp.x), bfhi(pp.x), bflo(pp.y), bfhi(pp.y), bflo(pp.z), bfhi(pp.z), bflo(pp.w), bfhi(pp.w)};
; #pragma unroll
;                         for (int e = 0; e < 8; ++e) av[e] = fast_sigmoid(av[e] * rs) * pv[e]; }
;                     else {
; #pragma unroll
;                         for (int e = 0; e < 8; ++e) av[e] *= alpha; }
;                     float lo[8];
; #pragma unroll
;                     for (int e = 0; e < 8; ++e) { hv[e] += av[e]; sq += hv[e] * hv[e]; }
;                     u32x4 wh; wh.x = pk2(hv[0], hv[1]); wh.y = pk2(hv[2], hv[3]); wh.z = pk2(hv[4], hv[5]); wh.w = pk2(hv[6], hv[7]);
;                     lo[0] = hv[0] - bflo(wh.x); lo[1] = hv[1] - bfhi(wh.x); lo[2] = hv[2] - bflo(wh.y); lo[3] = hv[3] - bfhi(wh.y);
;                     lo[4] = hv[4] - bflo(wh.z); lo[5] = hv[5] - bfhi(wh.z); lo[6] = hv[6] - bflo(wh.w); lo[7] = hv[7] - bfhi(wh.w);
;                     u32x4 wl; wl.x = pk2(lo[0], lo[1]); wl.y = pk2(lo[2], lo[3]); wl.z = pk2(lo[4], lo[5]); wl.w = pk2(lo[6], lo[7]);
;                     *(u32x4*)(HO + off) = wh; *(u32x4*)(LO + off) = wl;
	v_lshlrev_b32_e32 v156, 16, v180
	v_and_b32_e32 v157, 0xffff0000, v180
	v_lshlrev_b32_e32 v158, 16, v184
	v_and_b32_e32 v159, 0xffff0000, v184
	v_pk_add_f32 v[156:157], v[156:157], v[158:159]
	v_pk_fma_f32 v[156:157], v[94:95], 0.5, v[156:157] op_sel_hi:[1,0,1]
	v_cvt_pk_bf16_f32 v180, v156, v157
	v_pk_mul_f32 v[198:199], v[156:157], v[156:157]
	v_lshlrev_b32_e32 v158, 16, v180
	v_and_b32_e32 v159, 0xffff0000, v180
	v_pk_add_f32 v[196:197], v[156:157], v[158:159] neg_lo:[0,1] neg_hi:[0,1]
	v_cvt_pk_bf16_f32 v184, v196, v197
	v_lshlrev_b32_e32 v156, 16, v181
	v_and_b32_e32 v157, 0xffff0000, v181
	v_lshlrev_b32_e32 v158, 16, v185
	v_and_b32_e32 v159, 0xffff0000, v185
	v_pk_add_f32 v[156:157], v[156:157], v[158:159]
	v_pk_fma_f32 v[156:157], v[96:97], 0.5, v[156:157] op_sel_hi:[1,0,1]
	v_cvt_pk_bf16_f32 v181, v156, v157
	v_pk_fma_f32 v[198:199], v[156:157], v[156:157], v[198:199]
	v_lshlrev_b32_e32 v158, 16, v181
	v_and_b32_e32 v159, 0xffff0000, v181
	v_pk_add_f32 v[196:197], v[156:157], v[158:159] neg_lo:[0,1] neg_hi:[0,1]
	v_cvt_pk_bf16_f32 v185, v196, v197
	v_lshlrev_b32_e32 v156, 16, v182
	v_and_b32_e32 v157, 0xffff0000, v182
	v_lshlrev_b32_e32 v158, 16, v186
	v_and_b32_e32 v159, 0xffff0000, v186
	v_pk_add_f32 v[156:157], v[156:157], v[158:159]
	v_pk_fma_f32 v[156:157], v[90:91], 0.5, v[156:157] op_sel_hi:[1,0,1]
	v_cvt_pk_bf16_f32 v182, v156, v157
	v_pk_fma_f32 v[198:199], v[156:157], v[156:157], v[198:199]
	v_lshlrev_b32_e32 v158, 16, v182
	v_and_b32_e32 v159, 0xffff0000, v182
	v_pk_add_f32 v[196:197], v[156:157], v[158:159] neg_lo:[0,1] neg_hi:[0,1]
	v_cvt_pk_bf16_f32 v186, v196, v197
	v_lshlrev_b32_e32 v156, 16, v183
	v_and_b32_e32 v157, 0xffff0000, v183
	v_lshlrev_b32_e32 v158, 16, v187
	v_and_b32_e32 v159, 0xffff0000, v187
	v_pk_add_f32 v[156:157], v[156:157], v[158:159]
	v_pk_fma_f32 v[156:157], v[92:93], 0.5, v[156:157] op_sel_hi:[1,0,1]
	v_cvt_pk_bf16_f32 v183, v156, v157
	v_pk_fma_f32 v[198:199], v[156:157], v[156:157], v[198:199]
	v_lshlrev_b32_e32 v158, 16, v183
	v_and_b32_e32 v159, 0xffff0000, v183
	v_pk_add_f32 v[196:197], v[156:157], v[158:159] neg_lo:[0,1] neg_hi:[0,1]
	v_cvt_pk_bf16_f32 v187, v196, v197
	global_store_dwordx4 v212, v[180:183], s[10:11]
	global_store_dwordx4 v212, v[184:187], s[6:7]
	s_waitcnt vmcnt(18)
	v_lshlrev_b32_e32 v156, 16, v188
	v_and_b32_e32 v157, 0xffff0000, v188
	v_lshlrev_b32_e32 v158, 16, v192
	v_and_b32_e32 v159, 0xffff0000, v192
	v_pk_add_f32 v[156:157], v[156:157], v[158:159]
	v_pk_fma_f32 v[156:157], v[86:87], 0.5, v[156:157] op_sel_hi:[1,0,1]
	v_cvt_pk_bf16_f32 v188, v156, v157
	v_pk_fma_f32 v[198:199], v[156:157], v[156:157], v[198:199]
	v_lshlrev_b32_e32 v158, 16, v188
	v_and_b32_e32 v159, 0xffff0000, v188
	v_pk_add_f32 v[196:197], v[156:157], v[158:159] neg_lo:[0,1] neg_hi:[0,1]
	v_cvt_pk_bf16_f32 v192, v196, v197
	v_lshlrev_b32_e32 v156, 16, v189
	v_and_b32_e32 v157, 0xffff0000, v189
	v_lshlrev_b32_e32 v158, 16, v193
	v_and_b32_e32 v159, 0xffff0000, v193
	v_pk_add_f32 v[156:157], v[156:157], v[158:159]
	v_pk_fma_f32 v[156:157], v[88:89], 0.5, v[156:157] op_sel_hi:[1,0,1]
	v_cvt_pk_bf16_f32 v189, v156, v157
	v_pk_fma_f32 v[198:199], v[156:157], v[156:157], v[198:199]
	v_lshlrev_b32_e32 v158, 16, v189
	v_and_b32_e32 v159, 0xffff0000, v189
	v_pk_add_f32 v[196:197], v[156:157], v[158:159] neg_lo:[0,1] neg_hi:[0,1]
	v_cvt_pk_bf16_f32 v193, v196, v197
	v_lshlrev_b32_e32 v156, 16, v190
	v_and_b32_e32 v157, 0xffff0000, v190
	v_lshlrev_b32_e32 v158, 16, v194
	v_and_b32_e32 v159, 0xffff0000, v194
	v_pk_add_f32 v[156:157], v[156:157], v[158:159]
	v_pk_fma_f32 v[156:157], v[82:83], 0.5, v[156:157] op_sel_hi:[1,0,1]
	v_cvt_pk_bf16_f32 v190, v156, v157
	v_pk_fma_f32 v[198:199], v[156:157], v[156:157], v[198:199]
	v_lshlrev_b32_e32 v158, 16, v190
	v_and_b32_e32 v159, 0xffff0000, v190
	v_pk_add_f32 v[196:197], v[156:157], v[158:159] neg_lo:[0,1] neg_hi:[0,1]
	v_cvt_pk_bf16_f32 v194, v196, v197
	v_lshlrev_b32_e32 v156, 16, v191
	v_and_b32_e32 v157, 0xffff0000, v191
	v_lshlrev_b32_e32 v158, 16, v195
	v_and_b32_e32 v159, 0xffff0000, v195
	v_pk_add_f32 v[156:157], v[156:157], v[158:159]
	v_pk_fma_f32 v[156:157], v[84:85], 0.5, v[156:157] op_sel_hi:[1,0,1]
	v_cvt_pk_bf16_f32 v191, v156, v157
	v_pk_fma_f32 v[198:199], v[156:157], v[156:157], v[198:199]
	v_lshlrev_b32_e32 v158, 16, v191
	v_and_b32_e32 v159, 0xffff0000, v191
	v_pk_add_f32 v[196:197], v[156:157], v[158:159] neg_lo:[0,1] neg_hi:[0,1]
	v_cvt_pk_bf16_f32 v195, v196, v197
	global_store_dwordx4 v212, v[188:191], s[10:11] offset:256
	global_store_dwordx4 v212, v[192:195], s[6:7] offset:256
	v_add_f32_e32 v202, v198, v199
	s_nop 0
	v_add_u32_e32 v212, 0x48000, v213
	global_load_dwordx4 v[180:183], v212, s[10:11]
	global_load_dwordx4 v[184:187], v212, s[6:7]
	global_load_dwordx4 v[188:191], v212, s[10:11] offset:256
	global_load_dwordx4 v[192:195], v212, s[6:7] offset:256
	s_waitcnt vmcnt(22)
; __device__ __forceinline__ unsigned pk2(float lo, float hi) { f32x2_t v = {lo, hi}; bf16x2_t b = __builtin_convertvector(v, bf16x2_t); return __builtin_bit_cast(unsigned, b); }
; __device__ __forceinline__ float bflo(unsigned u) { return __uint_as_float(u << 16); }
;     __device__ __forceinline__ void operator()(const f32x4 (&acc)[2][2][4][2], const Unit& u, int wr, int wc, int fr, int fq) const {
;     ...
;                 for (int bj = 0; bj < 2; ++bj) {
;                     const size_t off = (size_t)row * DM + col0 + bj * HALF;
;                     const u32x4 hh = *(const u32x4*)(HI + off), ll = *(const u32x4*)(LO + off);
;                     float hv[8] = {bflo(hh.x) + bflo(ll.x), bfhi(hh.x) + bfhi(ll.x), bflo(hh.y) + bflo(ll.y), bfhi(hh.y) + bfhi(ll.y),
;                                    bflo(hh.z) + bflo(ll.z), bfhi(hh.z) + bfhi(ll.z), bflo(hh.w) + bflo(ll.w), bfhi(hh.w) + bfhi(ll.w)};
;                     float av[8] = {acc[ai][bj][m][0][0], acc[ai][bj][m][0][1], acc[ai][bj][m][0][2], acc[ai][bj][m][0][3], acc[ai][bj][m][1][0], acc[ai][bj][m][1][1], acc[ai][bj][m][1][2], acc[ai][bj][m][1][3]};
;                     if (GATED) { const u32x4 pp = *(const u32x4*)(PP + off);
;                         const float pv[8] = {bflo(pp.x), bfhi(pp.x), bflo(pp.y), bfhi(pp.y), bflo(pp.z), bfhi(pp.z), bflo(pp.w), bfhi(pp.w)};
; #pragma unroll
;                         for (int e = 0; e < 8; ++e) av[e] = fast_sigmoid(av[e] * rs) * pv[e]; }
;                     else {
; #pragma unroll
;                         for (int e = 0; e < 8; ++e) av[e] *= alpha; }
;                     float lo[8];
; #pragma unroll
;                     for (int e = 0; e < 8; ++e) { hv[e] += av[e]; sq += hv[e] * hv[e]; }
;                     u32x4 wh; wh.x = pk2(hv[0], hv[1]); wh.y = pk2(hv[2], hv[3]); wh.z = pk2(hv[4], hv[5]); wh.w = pk2(hv[6], hv[7]);
;                     lo[0] = hv[0] - bflo(wh.x); lo[1] = hv[1] - bfhi(wh.x); lo[2] = hv[2] - bflo(wh.y); lo[3] = hv[3] - bfhi(wh.y);
;                     lo[4] = hv[4] - bflo(wh.z); lo[5] = hv[5] - bfhi(wh.z); lo[6] = hv[6] - bflo(wh.w); lo[7] = hv[7] - bfhi(wh.w);
;                     u32x4 wl; wl.x = pk2(lo[0], lo[1]); wl.y = pk2(lo[2], lo[3]); wl.z = pk2(lo[4], lo[5]); wl.w = pk2(lo[6], lo[7]);
;                     *(u32x4*)(HO + off) = wh; *(u32x4*)(LO + off) = wl;
	v_lshlrev_b32_e32 v156, 16, v140
	v_and_b32_e32 v157, 0xffff0000, v140
	v_lshlrev_b32_e32 v158, 16, v144
	v_and_b32_e32 v159, 0xffff0000, v144
	v_pk_add_f32 v[156:157], v[156:157], v[158:159]
	v_pk_fma_f32 v[156:157], v[78:79], 0.5, v[156:157] op_sel_hi:[1,0,1]
	v_cvt_pk_bf16_f32 v140, v156, v157
	v_pk_mul_f32 v[198:199], v[156:157], v[156:157]
	v_lshlrev_b32_e32 v158, 16, v140
	v_and_b32_e32 v159, 0xffff0000, v140
	v_pk_add_f32 v[196:197], v[156:157], v[158:159] neg_lo:[0,1] neg_hi:[0,1]
	v_cvt_pk_bf16_f32 v144, v196, v197
	v_lshlrev_b32_e32 v156, 16, v141
	v_and_b32_e32 v157, 0xffff0000, v141
	v_lshlrev_b32_e32 v158, 16, v145
	v_and_b32_e32 v159, 0xffff0000, v145
	v_pk_add_f32 v[156:157], v[156:157], v[158:159]
	v_pk_fma_f32 v[156:157], v[80:81], 0.5, v[156:157] op_sel_hi:[1,0,1]
	v_cvt_pk_bf16_f32 v141, v156, v157
	v_pk_fma_f32 v[198:199], v[156:157], v[156:157], v[198:199]
	v_lshlrev_b32_e32 v158, 16, v141
	v_and_b32_e32 v159, 0xffff0000, v141
	v_pk_add_f32 v[196:197], v[156:157], v[158:159] neg_lo:[0,1] neg_hi:[0,1]
	v_cvt_pk_bf16_f32 v145, v196, v197
	v_lshlrev_b32_e32 v156, 16, v142
	v_and_b32_e32 v157, 0xffff0000, v142
	v_lshlrev_b32_e32 v158, 16, v146
	v_and_b32_e32 v159, 0xffff0000, v146
	v_pk_add_f32 v[156:157], v[156:157], v[158:159]
	v_pk_fma_f32 v[156:157], v[74:75], 0.5, v[156:157] op_sel_hi:[1,0,1]
	v_cvt_pk_bf16_f32 v142, v156, v157
	v_pk_fma_f32 v[198:199], v[156:157], v[156:157], v[198:199]
	v_lshlrev_b32_e32 v158, 16, v142
	v_and_b32_e32 v159, 0xffff0000, v142
	v_pk_add_f32 v[196:197], v[156:157], v[158:159] neg_lo:[0,1] neg_hi:[0,1]
	v_cvt_pk_bf16_f32 v146, v196, v197
	v_lshlrev_b32_e32 v156, 16, v143
	v_and_b32_e32 v157, 0xffff0000, v143
	v_lshlrev_b32_e32 v158, 16, v147
	v_and_b32_e32 v159, 0xffff0000, v147
	v_pk_add_f32 v[156:157], v[156:157], v[158:159]
	v_pk_fma_f32 v[156:157], v[76:77], 0.5, v[156:157] op_sel_hi:[1,0,1]
	v_cvt_pk_bf16_f32 v143, v156, v157
	v_pk_fma_f32 v[198:199], v[156:157], v[156:157], v[198:199]
	v_lshlrev_b32_e32 v158, 16, v143
	v_and_b32_e32 v159, 0xffff0000, v143
	v_pk_add_f32 v[196:197], v[156:157], v[158:159] neg_lo:[0,1] neg_hi:[0,1]
	v_cvt_pk_bf16_f32 v147, v196, v197
	global_store_dwordx4 v210, v[140:143], s[10:11]
	global_store_dwordx4 v210, v[144:147], s[6:7]
	s_waitcnt vmcnt(22)
	v_lshlrev_b32_e32 v156, 16, v148
	v_and_b32_e32 v157, 0xffff0000, v148
	v_lshlrev_b32_e32 v158, 16, v152
	v_and_b32_e32 v159, 0xffff0000, v152
	v_pk_add_f32 v[156:157], v[156:157], v[158:159]
	v_pk_fma_f32 v[156:157], v[70:71], 0.5, v[156:157] op_sel_hi:[1,0,1]
	v_cvt_pk_bf16_f32 v148, v156, v157
	v_pk_fma_f32 v[198:199], v[156:157], v[156:157], v[198:199]
	v_lshlrev_b32_e32 v158, 16, v148
	v_and_b32_e32 v159, 0xffff0000, v148
	v_pk_add_f32 v[196:197], v[156:157], v[158:159] neg_lo:[0,1] neg_hi:[0,1]
	v_cvt_pk_bf16_f32 v152, v196, v197
	v_lshlrev_b32_e32 v156, 16, v149
	v_and_b32_e32 v157, 0xffff0000, v149
	v_lshlrev_b32_e32 v158, 16, v153
	v_and_b32_e32 v159, 0xffff0000, v153
	v_pk_add_f32 v[156:157], v[156:157], v[158:159]
	v_pk_fma_f32 v[156:157], v[72:73], 0.5, v[156:157] op_sel_hi:[1,0,1]
	v_cvt_pk_bf16_f32 v149, v156, v157
	v_pk_fma_f32 v[198:199], v[156:157], v[156:157], v[198:199]
	v_lshlrev_b32_e32 v158, 16, v149
	v_and_b32_e32 v159, 0xffff0000, v149
	v_pk_add_f32 v[196:197], v[156:157], v[158:159] neg_lo:[0,1] neg_hi:[0,1]
	v_cvt_pk_bf16_f32 v153, v196, v197
	v_lshlrev_b32_e32 v156, 16, v150
	v_and_b32_e32 v157, 0xffff0000, v150
	v_lshlrev_b32_e32 v158, 16, v154
	v_and_b32_e32 v159, 0xffff0000, v154
	v_pk_add_f32 v[156:157], v[156:157], v[158:159]
	v_pk_fma_f32 v[156:157], v[66:67], 0.5, v[156:157] op_sel_hi:[1,0,1]
	v_cvt_pk_bf16_f32 v150, v156, v157
	v_pk_fma_f32 v[198:199], v[156:157], v[156:157], v[198:199]
	v_lshlrev_b32_e32 v158, 16, v150
	v_and_b32_e32 v159, 0xffff0000, v150
	v_pk_add_f32 v[196:197], v[156:157], v[158:159] neg_lo:[0,1] neg_hi:[0,1]
	v_cvt_pk_bf16_f32 v154, v196, v197
	v_lshlrev_b32_e32 v156, 16, v151
	v_and_b32_e32 v157, 0xffff0000, v151
	v_lshlrev_b32_e32 v158, 16, v155
	v_and_b32_e32 v159, 0xffff0000, v155
	v_pk_add_f32 v[156:157], v[156:157], v[158:159]
	v_pk_fma_f32 v[156:157], v[68:69], 0.5, v[156:157] op_sel_hi:[1,0,1]
	v_cvt_pk_bf16_f32 v151, v156, v157
	v_pk_fma_f32 v[198:199], v[156:157], v[156:157], v[198:199]
	v_lshlrev_b32_e32 v158, 16, v151
	v_and_b32_e32 v159, 0xffff0000, v151
	v_pk_add_f32 v[196:197], v[156:157], v[158:159] neg_lo:[0,1] neg_hi:[0,1]
	v_cvt_pk_bf16_f32 v155, v196, v197
	global_store_dwordx4 v210, v[148:151], s[10:11] offset:256
	global_store_dwordx4 v210, v[152:155], s[6:7] offset:256
	v_add_f32_e32 v203, v198, v199
	s_nop 0
	v_add_u32_e32 v210, 0x50000, v213
	global_load_dwordx4 v[140:143], v210, s[10:11]
	global_load_dwordx4 v[144:147], v210, s[6:7]
	global_load_dwordx4 v[148:151], v210, s[10:11] offset:256
	global_load_dwordx4 v[152:155], v210, s[6:7] offset:256
	s_waitcnt vmcnt(18)
; __device__ __forceinline__ unsigned pk2(float lo, float hi) { f32x2_t v = {lo, hi}; bf16x2_t b = __builtin_convertvector(v, bf16x2_t); return __builtin_bit_cast(unsigned, b); }
; __device__ __forceinline__ float bflo(unsigned u) { return __uint_as_float(u << 16); }
;     __device__ __forceinline__ void operator()(const f32x4 (&acc)[2][2][4][2], const Unit& u, int wr, int wc, int fr, int fq) const {
;     ...
;                 for (int bj = 0; bj < 2; ++bj) {
;                     const size_t off = (size_t)row * DM + col0 + bj * HALF;
;                     const u32x4 hh = *(const u32x4*)(HI + off), ll = *(const u32x4*)(LO + off);
;                     float hv[8] = {bflo(hh.x) + bflo(ll.x), bfhi(hh.x) + bfhi(ll.x), bflo(hh.y) + bflo(ll.y), bfhi(hh.y) + bfhi(ll.y),
;                                    bflo(hh.z) + bflo(ll.z), bfhi(hh.z) + bfhi(ll.z), bflo(hh.w) + bflo(ll.w), bfhi(hh.w) + bfhi(ll.w)};
;                     float av[8] = {acc[ai][bj][m][0][0], acc[ai][bj][m][0][1], acc[ai][bj][m][0][2], acc[ai][bj][m][0][3], acc[ai][bj][m][1][0], acc[ai][bj][m][1][1], acc[ai][bj][m][1][2], acc[ai][bj][m][1][3]};
;                     if (GATED) { const u32x4 pp = *(const u32x4*)(PP + off);
;                         const float pv[8] = {bflo(pp.x), bfhi(pp.x), bflo(pp.y), bfhi(pp.y), bflo(pp.z), bfhi(pp.z), bflo(pp.w), bfhi(pp.w)};
; #pragma unroll
;                         for (int e = 0; e < 8; ++e) av[e] = fast_sigmoid(av[e] * rs) * pv[e]; }
;                     else {
; #pragma unroll
;                         for (int e = 0; e < 8; ++e) av[e] *= alpha; }
;                     float lo[8];
; #pragma unroll
;                     for (int e = 0; e < 8; ++e) { hv[e] += av[e]; sq += hv[e] * hv[e]; }
;                     u32x4 wh; wh.x = pk2(hv[0], hv[1]); wh.y = pk2(hv[2], hv[3]); wh.z = pk2(hv[4], hv[5]); wh.w = pk2(hv[6], hv[7]);
;                     lo[0] = hv[0] - bflo(wh.x); lo[1] = hv[1] - bfhi(wh.x); lo[2] = hv[2] - bflo(wh.y); lo[3] = hv[3] - bfhi(wh.y);
;                     lo[4] = hv[4] - bflo(wh.z); lo[5] = hv[5] - bfhi(wh.z); lo[6] = hv[6] - bflo(wh.w); lo[7] = hv[7] - bfhi(wh.w);
;                     u32x4 wl; wl.x = pk2(lo[0], lo[1]); wl.y = pk2(lo[2], lo[3]); wl.z = pk2(lo[4], lo[5]); wl.w = pk2(lo[6], lo[7]);
;                     *(u32x4*)(HO + off) = wh; *(u32x4*)(LO + off) = wl;
;                 }
	v_lshlrev_b32_e32 v156, 16, v164
	v_and_b32_e32 v157, 0xffff0000, v164
	v_lshlrev_b32_e32 v158, 16, v168
	v_and_b32_e32 v159, 0xffff0000, v168
	v_pk_add_f32 v[156:157], v[156:157], v[158:159]
	v_pk_fma_f32 v[156:157], v[62:63], 0.5, v[156:157] op_sel_hi:[1,0,1]
	v_cvt_pk_bf16_f32 v164, v156, v157
	v_pk_mul_f32 v[198:199], v[156:157], v[156:157]
	v_lshlrev_b32_e32 v158, 16, v164
	v_and_b32_e32 v159, 0xffff0000, v164
	v_pk_add_f32 v[196:197], v[156:157], v[158:159] neg_lo:[0,1] neg_hi:[0,1]
	v_cvt_pk_bf16_f32 v168, v196, v197
	v_lshlrev_b32_e32 v156, 16, v165
	v_and_b32_e32 v157, 0xffff0000, v165
	v_lshlrev_b32_e32 v158, 16, v169
	v_and_b32_e32 v159, 0xffff0000, v169
	v_pk_add_f32 v[156:157], v[156:157], v[158:159]
	v_pk_fma_f32 v[156:157], v[64:65], 0.5, v[156:157] op_sel_hi:[1,0,1]
	v_cvt_pk_bf16_f32 v165, v156, v157
	v_pk_fma_f32 v[198:199], v[156:157], v[156:157], v[198:199]
	v_lshlrev_b32_e32 v158, 16, v165
	v_and_b32_e32 v159, 0xffff0000, v165
	v_pk_add_f32 v[196:197], v[156:157], v[158:159] neg_lo:[0,1] neg_hi:[0,1]
	v_cvt_pk_bf16_f32 v169, v196, v197
	v_lshlrev_b32_e32 v156, 16, v166
	v_and_b32_e32 v157, 0xffff0000, v166
	v_lshlrev_b32_e32 v158, 16, v170
	v_and_b32_e32 v159, 0xffff0000, v170
	v_pk_add_f32 v[156:157], v[156:157], v[158:159]
	v_pk_fma_f32 v[156:157], v[58:59], 0.5, v[156:157] op_sel_hi:[1,0,1]
	v_cvt_pk_bf16_f32 v166, v156, v157
	v_pk_fma_f32 v[198:199], v[156:157], v[156:157], v[198:199]
	v_lshlrev_b32_e32 v158, 16, v166
	v_and_b32_e32 v159, 0xffff0000, v166
	v_pk_add_f32 v[196:197], v[156:157], v[158:159] neg_lo:[0,1] neg_hi:[0,1]
	v_cvt_pk_bf16_f32 v170, v196, v197
	v_lshlrev_b32_e32 v156, 16, v167
	v_and_b32_e32 v157, 0xffff0000, v167
	v_lshlrev_b32_e32 v158, 16, v171
	v_and_b32_e32 v159, 0xffff0000, v171
	v_pk_add_f32 v[156:157], v[156:157], v[158:159]
	v_pk_fma_f32 v[156:157], v[60:61], 0.5, v[156:157] op_sel_hi:[1,0,1]
	v_cvt_pk_bf16_f32 v167, v156, v157
	v_pk_fma_f32 v[198:199], v[156:157], v[156:157], v[198:199]
	v_lshlrev_b32_e32 v158, 16, v167
	v_and_b32_e32 v159, 0xffff0000, v167
	v_pk_add_f32 v[196:197], v[156:157], v[158:159] neg_lo:[0,1] neg_hi:[0,1]
	v_cvt_pk_bf16_f32 v171, v196, v197
	global_store_dwordx4 v211, v[164:167], s[10:11]
	global_store_dwordx4 v211, v[168:171], s[6:7]
	s_waitcnt vmcnt(18)
	v_lshlrev_b32_e32 v156, 16, v172
	v_and_b32_e32 v157, 0xffff0000, v172
	v_lshlrev_b32_e32 v158, 16, v176
	v_and_b32_e32 v159, 0xffff0000, v176
	v_pk_add_f32 v[156:157], v[156:157], v[158:159]
	v_pk_fma_f32 v[156:157], v[54:55], 0.5, v[156:157] op_sel_hi:[1,0,1]
	v_cvt_pk_bf16_f32 v172, v156, v157
	v_pk_fma_f32 v[198:199], v[156:157], v[156:157], v[198:199]
	v_lshlrev_b32_e32 v158, 16, v172
	v_and_b32_e32 v159, 0xffff0000, v172
	v_pk_add_f32 v[196:197], v[156:157], v[158:159] neg_lo:[0,1] neg_hi:[0,1]
	v_cvt_pk_bf16_f32 v176, v196, v197
	v_lshlrev_b32_e32 v156, 16, v173
	v_and_b32_e32 v157, 0xffff0000, v173
	v_lshlrev_b32_e32 v158, 16, v177
	v_and_b32_e32 v159, 0xffff0000, v177
	v_pk_add_f32 v[156:157], v[156:157], v[158:159]
	v_pk_fma_f32 v[156:157], v[56:57], 0.5, v[156:157] op_sel_hi:[1,0,1]
	v_cvt_pk_bf16_f32 v173, v156, v157
	v_pk_fma_f32 v[198:199], v[156:157], v[156:157], v[198:199]
	v_lshlrev_b32_e32 v158, 16, v173
	v_and_b32_e32 v159, 0xffff0000, v173
	v_pk_add_f32 v[196:197], v[156:157], v[158:159] neg_lo:[0,1] neg_hi:[0,1]
	v_cvt_pk_bf16_f32 v177, v196, v197
	v_lshlrev_b32_e32 v156, 16, v174
	v_and_b32_e32 v157, 0xffff0000, v174
	v_lshlrev_b32_e32 v158, 16, v178
	v_and_b32_e32 v159, 0xffff0000, v178
	v_pk_add_f32 v[156:157], v[156:157], v[158:159]
	v_pk_fma_f32 v[156:157], v[50:51], 0.5, v[156:157] op_sel_hi:[1,0,1]
	v_cvt_pk_bf16_f32 v174, v156, v157
	v_pk_fma_f32 v[198:199], v[156:157], v[156:157], v[198:199]
	v_lshlrev_b32_e32 v158, 16, v174
	v_and_b32_e32 v159, 0xffff0000, v174
	v_pk_add_f32 v[196:197], v[156:157], v[158:159] neg_lo:[0,1] neg_hi:[0,1]
	v_cvt_pk_bf16_f32 v178, v196, v197
	v_lshlrev_b32_e32 v156, 16, v175
	v_and_b32_e32 v157, 0xffff0000, v175
	v_lshlrev_b32_e32 v158, 16, v179
	v_and_b32_e32 v159, 0xffff0000, v179
	v_pk_add_f32 v[156:157], v[156:157], v[158:159]
	v_pk_fma_f32 v[156:157], v[52:53], 0.5, v[156:157] op_sel_hi:[1,0,1]
	v_cvt_pk_bf16_f32 v175, v156, v157
	v_pk_fma_f32 v[198:199], v[156:157], v[156:157], v[198:199]
	v_lshlrev_b32_e32 v158, 16, v175
	v_and_b32_e32 v159, 0xffff0000, v175
	v_pk_add_f32 v[196:197], v[156:157], v[158:159] neg_lo:[0,1] neg_hi:[0,1]
	v_cvt_pk_bf16_f32 v179, v196, v197
	global_store_dwordx4 v211, v[172:175], s[10:11] offset:256
	global_store_dwordx4 v211, v[176:179], s[6:7] offset:256
	v_add_f32_e32 v206, v198, v199
	s_nop 0
	v_add_u32_e32 v211, 0x58000, v213
	global_load_dwordx4 v[164:167], v211, s[10:11]
	global_load_dwordx4 v[168:171], v211, s[6:7]
	global_load_dwordx4 v[172:175], v211, s[10:11] offset:256
	global_load_dwordx4 v[176:179], v211, s[6:7] offset:256
	s_waitcnt vmcnt(18)
; __device__ __forceinline__ unsigned pk2(float lo, float hi) { f32x2_t v = {lo, hi}; bf16x2_t b = __builtin_convertvector(v, bf16x2_t); return __builtin_bit_cast(unsigned, b); }
; __device__ __forceinline__ float bflo(unsigned u) { return __uint_as_float(u << 16); }
;     __device__ __forceinline__ void operator()(const f32x4 (&acc)[2][2][4][2], const Unit& u, int wr, int wc, int fr, int fq) const {
;     ...
;                 for (int bj = 0; bj < 2; ++bj) {
;                     const size_t off = (size_t)row * DM + col0 + bj * HALF;
;                     const u32x4 hh = *(const u32x4*)(HI + off), ll = *(const u32x4*)(LO + off);
;                     float hv[8] = {bflo(hh.x) + bflo(ll.x), bfhi(hh.x) + bfhi(ll.x), bflo(hh.y) + bflo(ll.y), bfhi(hh.y) + bfhi(ll.y),
;                                    bflo(hh.z) + bflo(ll.z), bfhi(hh.z) + bfhi(ll.z), bflo(hh.w) + bflo(ll.w), bfhi(hh.w) + bfhi(ll.w)};
;                     float av[8] = {acc[ai][bj][m][0][0], acc[ai][bj][m][0][1], acc[ai][bj][m][0][2], acc[ai][bj][m][0][3], acc[ai][bj][m][1][0], acc[ai][bj][m][1][1], acc[ai][bj][m][1][2], acc[ai][bj][m][1][3]};
;                     if (GATED) { const u32x4 pp = *(const u32x4*)(PP + off);
;                         const float pv[8] = {bflo(pp.x), bfhi(pp.x), bflo(pp.y), bfhi(pp.y), bflo(pp.z), bfhi(pp.z), bflo(pp.w), bfhi(pp.w)};
; #pragma unroll
;                         for (int e = 0; e < 8; ++e) av[e] = fast_sigmoid(av[e] * rs) * pv[e]; }
;                     else {
; #pragma unroll
;                         for (int e = 0; e < 8; ++e) av[e] *= alpha; }
;                     float lo[8];
; #pragma unroll
;                     for (int e = 0; e < 8; ++e) { hv[e] += av[e]; sq += hv[e] * hv[e]; }
;                     u32x4 wh; wh.x = pk2(hv[0], hv[1]); wh.y = pk2(hv[2], hv[3]); wh.z = pk2(hv[4], hv[5]); wh.w = pk2(hv[6], hv[7]);
;                     lo[0] = hv[0] - bflo(wh.x); lo[1] = hv[1] - bfhi(wh.x); lo[2] = hv[2] - bflo(wh.y); lo[3] = hv[3] - bfhi(wh.y);
;                     lo[4] = hv[4] - bflo(wh.z); lo[5] = hv[5] - bfhi(wh.z); lo[6] = hv[6] - bflo(wh.w); lo[7] = hv[7] - bfhi(wh.w);
;                     u32x4 wl; wl.x = pk2(lo[0], lo[1]); wl.y = pk2(lo[2], lo[3]); wl.z = pk2(lo[4], lo[5]); wl.w = pk2(lo[6], lo[7]);
;                     *(u32x4*)(HO + off) = wh; *(u32x4*)(LO + off) = wl;
;                 }
	v_lshlrev_b32_e32 v156, 16, v180
	v_and_b32_e32 v157, 0xffff0000, v180
	v_lshlrev_b32_e32 v158, 16, v184
	v_and_b32_e32 v159, 0xffff0000, v184
	v_pk_add_f32 v[156:157], v[156:157], v[158:159]
	v_pk_fma_f32 v[156:157], v[46:47], 0.5, v[156:157] op_sel_hi:[1,0,1]
	v_cvt_pk_bf16_f32 v180, v156, v157
	v_pk_mul_f32 v[198:199], v[156:157], v[156:157]
	v_lshlrev_b32_e32 v158, 16, v180
	v_and_b32_e32 v159, 0xffff0000, v180
	v_pk_add_f32 v[196:197], v[156:157], v[158:159] neg_lo:[0,1] neg_hi:[0,1]
	v_cvt_pk_bf16_f32 v184, v196, v197
	v_lshlrev_b32_e32 v156, 16, v181
	v_and_b32_e32 v157, 0xffff0000, v181
	v_lshlrev_b32_e32 v158, 16, v185
	v_and_b32_e32 v159, 0xffff0000, v185
	v_pk_add_f32 v[156:157], v[156:157], v[158:159]
	v_pk_fma_f32 v[156:157], v[48:49], 0.5, v[156:157] op_sel_hi:[1,0,1]
	v_cvt_pk_bf16_f32 v181, v156, v157
	v_pk_fma_f32 v[198:199], v[156:157], v[156:157], v[198:199]
	v_lshlrev_b32_e32 v158, 16, v181
	v_and_b32_e32 v159, 0xffff0000, v181
	v_pk_add_f32 v[196:197], v[156:157], v[158:159] neg_lo:[0,1] neg_hi:[0,1]
	v_cvt_pk_bf16_f32 v185, v196, v197
	v_lshlrev_b32_e32 v156, 16, v182
	v_and_b32_e32 v157, 0xffff0000, v182
	v_lshlrev_b32_e32 v158, 16, v186
	v_and_b32_e32 v159, 0xffff0000, v186
	v_pk_add_f32 v[156:157], v[156:157], v[158:159]
	v_pk_fma_f32 v[156:157], v[42:43], 0.5, v[156:157] op_sel_hi:[1,0,1]
	v_cvt_pk_bf16_f32 v182, v156, v157
	v_pk_fma_f32 v[198:199], v[156:157], v[156:157], v[198:199]
	v_lshlrev_b32_e32 v158, 16, v182
	v_and_b32_e32 v159, 0xffff0000, v182
	v_pk_add_f32 v[196:197], v[156:157], v[158:159] neg_lo:[0,1] neg_hi:[0,1]
	v_cvt_pk_bf16_f32 v186, v196, v197
	v_lshlrev_b32_e32 v156, 16, v183
	v_and_b32_e32 v157, 0xffff0000, v183
	v_lshlrev_b32_e32 v158, 16, v187
	v_and_b32_e32 v159, 0xffff0000, v187
	v_pk_add_f32 v[156:157], v[156:157], v[158:159]
	v_pk_fma_f32 v[156:157], v[44:45], 0.5, v[156:157] op_sel_hi:[1,0,1]
	v_cvt_pk_bf16_f32 v183, v156, v157
	v_pk_fma_f32 v[198:199], v[156:157], v[156:157], v[198:199]
	v_lshlrev_b32_e32 v158, 16, v183
	v_and_b32_e32 v159, 0xffff0000, v183
	v_pk_add_f32 v[196:197], v[156:157], v[158:159] neg_lo:[0,1] neg_hi:[0,1]
	v_cvt_pk_bf16_f32 v187, v196, v197
	global_store_dwordx4 v212, v[180:183], s[10:11]
	global_store_dwordx4 v212, v[184:187], s[6:7]
	s_waitcnt vmcnt(18)
	v_lshlrev_b32_e32 v156, 16, v188
	v_and_b32_e32 v157, 0xffff0000, v188
	v_lshlrev_b32_e32 v158, 16, v192
	v_and_b32_e32 v159, 0xffff0000, v192
	v_pk_add_f32 v[156:157], v[156:157], v[158:159]
	v_pk_fma_f32 v[156:157], v[38:39], 0.5, v[156:157] op_sel_hi:[1,0,1]
	v_cvt_pk_bf16_f32 v188, v156, v157
	v_pk_fma_f32 v[198:199], v[156:157], v[156:157], v[198:199]
	v_lshlrev_b32_e32 v158, 16, v188
	v_and_b32_e32 v159, 0xffff0000, v188
	v_pk_add_f32 v[196:197], v[156:157], v[158:159] neg_lo:[0,1] neg_hi:[0,1]
	v_cvt_pk_bf16_f32 v192, v196, v197
	v_lshlrev_b32_e32 v156, 16, v189
	v_and_b32_e32 v157, 0xffff0000, v189
	v_lshlrev_b32_e32 v158, 16, v193
	v_and_b32_e32 v159, 0xffff0000, v193
	v_pk_add_f32 v[156:157], v[156:157], v[158:159]
	v_pk_fma_f32 v[156:157], v[40:41], 0.5, v[156:157] op_sel_hi:[1,0,1]
	v_cvt_pk_bf16_f32 v189, v156, v157
	v_pk_fma_f32 v[198:199], v[156:157], v[156:157], v[198:199]
	v_lshlrev_b32_e32 v158, 16, v189
	v_and_b32_e32 v159, 0xffff0000, v189
	v_pk_add_f32 v[196:197], v[156:157], v[158:159] neg_lo:[0,1] neg_hi:[0,1]
	v_cvt_pk_bf16_f32 v193, v196, v197
	v_lshlrev_b32_e32 v156, 16, v190
	v_and_b32_e32 v157, 0xffff0000, v190
	v_lshlrev_b32_e32 v158, 16, v194
	v_and_b32_e32 v159, 0xffff0000, v194
	v_pk_add_f32 v[156:157], v[156:157], v[158:159]
	v_pk_fma_f32 v[156:157], v[34:35], 0.5, v[156:157] op_sel_hi:[1,0,1]
	v_cvt_pk_bf16_f32 v190, v156, v157
	v_pk_fma_f32 v[198:199], v[156:157], v[156:157], v[198:199]
	v_lshlrev_b32_e32 v158, 16, v190
	v_and_b32_e32 v159, 0xffff0000, v190
	v_pk_add_f32 v[196:197], v[156:157], v[158:159] neg_lo:[0,1] neg_hi:[0,1]
	v_cvt_pk_bf16_f32 v194, v196, v197
	v_lshlrev_b32_e32 v156, 16, v191
	v_and_b32_e32 v157, 0xffff0000, v191
	v_lshlrev_b32_e32 v158, 16, v195
	v_and_b32_e32 v159, 0xffff0000, v195
	v_pk_add_f32 v[156:157], v[156:157], v[158:159]
	v_pk_fma_f32 v[156:157], v[36:37], 0.5, v[156:157] op_sel_hi:[1,0,1]
	v_cvt_pk_bf16_f32 v191, v156, v157
	v_pk_fma_f32 v[198:199], v[156:157], v[156:157], v[198:199]
	v_lshlrev_b32_e32 v158, 16, v191
	v_and_b32_e32 v159, 0xffff0000, v191
	v_pk_add_f32 v[196:197], v[156:157], v[158:159] neg_lo:[0,1] neg_hi:[0,1]
	v_cvt_pk_bf16_f32 v195, v196, v197
	global_store_dwordx4 v212, v[188:191], s[10:11] offset:256
	global_store_dwordx4 v212, v[192:195], s[6:7] offset:256
	v_add_f32_e32 v207, v198, v199
	s_waitcnt vmcnt(14)
; __device__ __forceinline__ unsigned pk2(float lo, float hi) { f32x2_t v = {lo, hi}; bf16x2_t b = __builtin_convertvector(v, bf16x2_t); return __builtin_bit_cast(unsigned, b); }
; __device__ __forceinline__ float bflo(unsigned u) { return __uint_as_float(u << 16); }
;     __device__ __forceinline__ void operator()(const f32x4 (&acc)[2][2][4][2], const Unit& u, int wr, int wc, int fr, int fq) const {
;     ...
;                 for (int bj = 0; bj < 2; ++bj) {
;                     const size_t off = (size_t)row * DM + col0 + bj * HALF;
;                     const u32x4 hh = *(const u32x4*)(HI + off), ll = *(const u32x4*)(LO + off);
;                     float hv[8] = {bflo(hh.x) + bflo(ll.x), bfhi(hh.x) + bfhi(ll.x), bflo(hh.y) + bflo(ll.y), bfhi(hh.y) + bfhi(ll.y),
;                                    bflo(hh.z) + bflo(ll.z), bfhi(hh.z) + bfhi(ll.z), bflo(hh.w) + bflo(ll.w), bfhi(hh.w) + bfhi(ll.w)};
;                     float av[8] = {acc[ai][bj][m][0][0], acc[ai][bj][m][0][1], acc[ai][bj][m][0][2], acc[ai][bj][m][0][3], acc[ai][bj][m][1][0], acc[ai][bj][m][1][1], acc[ai][bj][m][1][2], acc[ai][bj][m][1][3]};
;                     if (GATED) { const u32x4 pp = *(const u32x4*)(PP + off);
;                         const float pv[8] = {bflo(pp.x), bfhi(pp.x), bflo(pp.y), bfhi(pp.y), bflo(pp.z), bfhi(pp.z), bflo(pp.w), bfhi(pp.w)};
; #pragma unroll
;                         for (int e = 0; e < 8; ++e) av[e] = fast_sigmoid(av[e] * rs) * pv[e]; }
;                     else {
; #pragma unroll
;                         for (int e = 0; e < 8; ++e) av[e] *= alpha; }
;                     float lo[8];
; #pragma unroll
;                     for (int e = 0; e < 8; ++e) { hv[e] += av[e]; sq += hv[e] * hv[e]; }
;                     u32x4 wh; wh.x = pk2(hv[0], hv[1]); wh.y = pk2(hv[2], hv[3]); wh.z = pk2(hv[4], hv[5]); wh.w = pk2(hv[6], hv[7]);
;                     lo[0] = hv[0] - bflo(wh.x); lo[1] = hv[1] - bfhi(wh.x); lo[2] = hv[2] - bflo(wh.y); lo[3] = hv[3] - bfhi(wh.y);
;                     lo[4] = hv[4] - bflo(wh.z); lo[5] = hv[5] - bfhi(wh.z); lo[6] = hv[6] - bflo(wh.w); lo[7] = hv[7] - bfhi(wh.w);
;                     u32x4 wl; wl.x = pk2(lo[0], lo[1]); wl.y = pk2(lo[2], lo[3]); wl.z = pk2(lo[4], lo[5]); wl.w = pk2(lo[6], lo[7]);
;                     *(u32x4*)(HO + off) = wh; *(u32x4*)(LO + off) = wl;
;                 }
	v_lshlrev_b32_e32 v156, 16, v140
	v_and_b32_e32 v157, 0xffff0000, v140
	v_lshlrev_b32_e32 v158, 16, v144
	v_and_b32_e32 v159, 0xffff0000, v144
	v_pk_add_f32 v[156:157], v[156:157], v[158:159]
	v_pk_fma_f32 v[156:157], v[30:31], 0.5, v[156:157] op_sel_hi:[1,0,1]
	v_cvt_pk_bf16_f32 v140, v156, v157
	v_pk_mul_f32 v[198:199], v[156:157], v[156:157]
	v_lshlrev_b32_e32 v158, 16, v140
	v_and_b32_e32 v159, 0xffff0000, v140
	v_pk_add_f32 v[196:197], v[156:157], v[158:159] neg_lo:[0,1] neg_hi:[0,1]
	v_cvt_pk_bf16_f32 v144, v196, v197
	v_lshlrev_b32_e32 v156, 16, v141
	v_and_b32_e32 v157, 0xffff0000, v141
	v_lshlrev_b32_e32 v158, 16, v145
	v_and_b32_e32 v159, 0xffff0000, v145
	v_pk_add_f32 v[156:157], v[156:157], v[158:159]
	v_pk_fma_f32 v[156:157], v[32:33], 0.5, v[156:157] op_sel_hi:[1,0,1]
	v_cvt_pk_bf16_f32 v141, v156, v157
	v_pk_fma_f32 v[198:199], v[156:157], v[156:157], v[198:199]
	v_lshlrev_b32_e32 v158, 16, v141
	v_and_b32_e32 v159, 0xffff0000, v141
	v_pk_add_f32 v[196:197], v[156:157], v[158:159] neg_lo:[0,1] neg_hi:[0,1]
	v_cvt_pk_bf16_f32 v145, v196, v197
	v_lshlrev_b32_e32 v156, 16, v142
	v_and_b32_e32 v157, 0xffff0000, v142
	v_lshlrev_b32_e32 v158, 16, v146
	v_and_b32_e32 v159, 0xffff0000, v146
	v_pk_add_f32 v[156:157], v[156:157], v[158:159]
	v_pk_fma_f32 v[156:157], v[26:27], 0.5, v[156:157] op_sel_hi:[1,0,1]
	v_cvt_pk_bf16_f32 v142, v156, v157
	v_pk_fma_f32 v[198:199], v[156:157], v[156:157], v[198:199]
	v_lshlrev_b32_e32 v158, 16, v142
	v_and_b32_e32 v159, 0xffff0000, v142
	v_pk_add_f32 v[196:197], v[156:157], v[158:159] neg_lo:[0,1] neg_hi:[0,1]
	v_cvt_pk_bf16_f32 v146, v196, v197
	v_lshlrev_b32_e32 v156, 16, v143
	v_and_b32_e32 v157, 0xffff0000, v143
	v_lshlrev_b32_e32 v158, 16, v147
	v_and_b32_e32 v159, 0xffff0000, v147
	v_pk_add_f32 v[156:157], v[156:157], v[158:159]
	v_pk_fma_f32 v[156:157], v[28:29], 0.5, v[156:157] op_sel_hi:[1,0,1]
	v_cvt_pk_bf16_f32 v143, v156, v157
	v_pk_fma_f32 v[198:199], v[156:157], v[156:157], v[198:199]
	v_lshlrev_b32_e32 v158, 16, v143
	v_and_b32_e32 v159, 0xffff0000, v143
	v_pk_add_f32 v[196:197], v[156:157], v[158:159] neg_lo:[0,1] neg_hi:[0,1]
	v_cvt_pk_bf16_f32 v147, v196, v197
	global_store_dwordx4 v210, v[140:143], s[10:11]
	global_store_dwordx4 v210, v[144:147], s[6:7]
	s_waitcnt vmcnt(14)
	v_lshlrev_b32_e32 v156, 16, v148
	v_and_b32_e32 v157, 0xffff0000, v148
	v_lshlrev_b32_e32 v158, 16, v152
	v_and_b32_e32 v159, 0xffff0000, v152
	v_pk_add_f32 v[156:157], v[156:157], v[158:159]
	v_pk_fma_f32 v[156:157], v[22:23], 0.5, v[156:157] op_sel_hi:[1,0,1]
	v_cvt_pk_bf16_f32 v148, v156, v157
	v_pk_fma_f32 v[198:199], v[156:157], v[156:157], v[198:199]
	v_lshlrev_b32_e32 v158, 16, v148
	v_and_b32_e32 v159, 0xffff0000, v148
	v_pk_add_f32 v[196:197], v[156:157], v[158:159] neg_lo:[0,1] neg_hi:[0,1]
	v_cvt_pk_bf16_f32 v152, v196, v197
	v_lshlrev_b32_e32 v156, 16, v149
	v_and_b32_e32 v157, 0xffff0000, v149
	v_lshlrev_b32_e32 v158, 16, v153
	v_and_b32_e32 v159, 0xffff0000, v153
	v_pk_add_f32 v[156:157], v[156:157], v[158:159]
	v_pk_fma_f32 v[156:157], v[24:25], 0.5, v[156:157] op_sel_hi:[1,0,1]
	v_cvt_pk_bf16_f32 v149, v156, v157
	v_pk_fma_f32 v[198:199], v[156:157], v[156:157], v[198:199]
	v_lshlrev_b32_e32 v158, 16, v149
	v_and_b32_e32 v159, 0xffff0000, v149
	v_pk_add_f32 v[196:197], v[156:157], v[158:159] neg_lo:[0,1] neg_hi:[0,1]
	v_cvt_pk_bf16_f32 v153, v196, v197
	v_lshlrev_b32_e32 v156, 16, v150
	v_and_b32_e32 v157, 0xffff0000, v150
	v_lshlrev_b32_e32 v158, 16, v154
	v_and_b32_e32 v159, 0xffff0000, v154
	v_pk_add_f32 v[156:157], v[156:157], v[158:159]
	v_pk_fma_f32 v[156:157], v[18:19], 0.5, v[156:157] op_sel_hi:[1,0,1]
	v_cvt_pk_bf16_f32 v150, v156, v157
	v_pk_fma_f32 v[198:199], v[156:157], v[156:157], v[198:199]
	v_lshlrev_b32_e32 v158, 16, v150
	v_and_b32_e32 v159, 0xffff0000, v150
	v_pk_add_f32 v[196:197], v[156:157], v[158:159] neg_lo:[0,1] neg_hi:[0,1]
	v_cvt_pk_bf16_f32 v154, v196, v197
	v_lshlrev_b32_e32 v156, 16, v151
	v_and_b32_e32 v157, 0xffff0000, v151
	v_lshlrev_b32_e32 v158, 16, v155
	v_and_b32_e32 v159, 0xffff0000, v155
	v_pk_add_f32 v[156:157], v[156:157], v[158:159]
	v_pk_fma_f32 v[156:157], v[20:21], 0.5, v[156:157] op_sel_hi:[1,0,1]
	v_cvt_pk_bf16_f32 v151, v156, v157
	v_pk_fma_f32 v[198:199], v[156:157], v[156:157], v[198:199]
	v_lshlrev_b32_e32 v158, 16, v151
	v_and_b32_e32 v159, 0xffff0000, v151
	v_pk_add_f32 v[196:197], v[156:157], v[158:159] neg_lo:[0,1] neg_hi:[0,1]
	v_cvt_pk_bf16_f32 v155, v196, v197
	global_store_dwordx4 v210, v[148:151], s[10:11] offset:256
	global_store_dwordx4 v210, v[152:155], s[6:7] offset:256
	v_add_f32_e32 v208, v198, v199
	s_waitcnt vmcnt(10)
; __device__ __forceinline__ float bflo(unsigned u) { return __uint_as_float(u << 16); }
;     __device__ __forceinline__ void operator()(const f32x4 (&acc)[2][2][4][2], const Unit& u, int wr, int wc, int fr, int fq) const {
;     ...
;                 for (int bj = 0; bj < 2; ++bj) {
;                     const size_t off = (size_t)row * DM + col0 + bj * HALF;
;                     const u32x4 hh = *(const u32x4*)(HI + off), ll = *(const u32x4*)(LO + off);
;                     float hv[8] = {bflo(hh.x) + bflo(ll.x), bfhi(hh.x) + bfhi(ll.x), bflo(hh.y) + bflo(ll.y), bfhi(hh.y) + bfhi(ll.y),
;                                    bflo(hh.z) + bflo(ll.z), bfhi(hh.z) + bfhi(ll.z), bflo(hh.w) + bflo(ll.w), bfhi(hh.w) + bfhi(ll.w)};
;                     float av[8] = {acc[ai][bj][m][0][0], acc[ai][bj][m][0][1], acc[ai][bj][m][0][2], acc[ai][bj][m][0][3], acc[ai][bj][m][1][0], acc[ai][bj][m][1][1], acc[ai][bj][m][1][2], acc[ai][bj][m][1][3]};
;                     if (GATED) { const u32x4 pp = *(const u32x4*)(PP + off);
;                         const float pv[8] = {bflo(pp.x), bfhi(pp.x), bflo(pp.y), bfhi(pp.y), bflo(pp.z), bfhi(pp.z), bflo(pp.w), bfhi(pp.w)};
; #pragma unroll
;                         for (int e = 0; e < 8; ++e) av[e] = fast_sigmoid(av[e] * rs) * pv[e]; }
;                     else {
; #pragma unroll
;                         for (int e = 0; e < 8; ++e) av[e] *= alpha; }
;                     float lo[8];
; #pragma unroll
;                     for (int e = 0; e < 8; ++e) { hv[e] += av[e]; sq += hv[e] * hv[e]; }
;                     u32x4 wh; wh.x = pk2(hv[0], hv[1]); wh.y = pk2(hv[2], hv[3]); wh.z = pk2(hv[4], hv[5]); wh.w = pk2(hv[6], hv[7]);
;                     lo[0] = hv[0] - bflo(wh.x); lo[1] = hv[1] - bfhi(wh.x); lo[2] = hv[2] - bflo(wh.y); lo[3] = hv[3] - bfhi(wh.y);
;                     lo[4] = hv[4] - bflo(wh.z); lo[5] = hv[5] - bfhi(wh.z); lo[6] = hv[6] - bflo(wh.w); lo[7] = hv[7] - bfhi(wh.w);
;                     u32x4 wl; wl.x = pk2(lo[0], lo[1]); wl.y = pk2(lo[2], lo[3]); wl.z = pk2(lo[4], lo[5]); wl.w = pk2(lo[6], lo[7]);
;                     *(u32x4*)(HO + off) = wh; *(u32x4*)(LO + off) = wl;
;                 }
;                 sq += __shfl_xor(sq, 16); sq += __shfl_xor(sq, 32);
;                 if (fq == 0) ssq_out[(size_t)row * 16 + 4 * u.pn + wc] = sq;
	v_lshlrev_b32_e32 v156, 16, v164
	v_and_b32_e32 v157, 0xffff0000, v164
	v_lshlrev_b32_e32 v158, 16, v168
	v_and_b32_e32 v159, 0xffff0000, v168
	v_pk_add_f32 v[156:157], v[156:157], v[158:159]
	v_pk_fma_f32 v[156:157], v[14:15], 0.5, v[156:157] op_sel_hi:[1,0,1]
	v_cvt_pk_bf16_f32 v164, v156, v157
	v_pk_mul_f32 v[198:199], v[156:157], v[156:157]
	v_lshlrev_b32_e32 v158, 16, v164
	v_and_b32_e32 v159, 0xffff0000, v164
	v_pk_add_f32 v[196:197], v[156:157], v[158:159] neg_lo:[0,1] neg_hi:[0,1]
	v_cvt_pk_bf16_f32 v168, v196, v197
	v_lshlrev_b32_e32 v156, 16, v165
	v_and_b32_e32 v157, 0xffff0000, v165
	v_lshlrev_b32_e32 v158, 16, v169
	v_and_b32_e32 v159, 0xffff0000, v169
	v_pk_add_f32 v[156:157], v[156:157], v[158:159]
	v_pk_fma_f32 v[156:157], v[16:17], 0.5, v[156:157] op_sel_hi:[1,0,1]
	v_cvt_pk_bf16_f32 v165, v156, v157
	v_pk_fma_f32 v[198:199], v[156:157], v[156:157], v[198:199]
	v_lshlrev_b32_e32 v158, 16, v165
	v_and_b32_e32 v159, 0xffff0000, v165
	v_pk_add_f32 v[196:197], v[156:157], v[158:159] neg_lo:[0,1] neg_hi:[0,1]
	v_cvt_pk_bf16_f32 v169, v196, v197
	v_lshlrev_b32_e32 v156, 16, v166
	v_and_b32_e32 v157, 0xffff0000, v166
	v_lshlrev_b32_e32 v158, 16, v170
	v_and_b32_e32 v159, 0xffff0000, v170
	v_pk_add_f32 v[156:157], v[156:157], v[158:159]
	v_pk_fma_f32 v[156:157], v[10:11], 0.5, v[156:157] op_sel_hi:[1,0,1]
	v_cvt_pk_bf16_f32 v166, v156, v157
	v_pk_fma_f32 v[198:199], v[156:157], v[156:157], v[198:199]
	v_lshlrev_b32_e32 v158, 16, v166
	v_and_b32_e32 v159, 0xffff0000, v166
	v_pk_add_f32 v[196:197], v[156:157], v[158:159] neg_lo:[0,1] neg_hi:[0,1]
	v_cvt_pk_bf16_f32 v170, v196, v197
	v_lshlrev_b32_e32 v156, 16, v167
	v_and_b32_e32 v157, 0xffff0000, v167
	v_lshlrev_b32_e32 v158, 16, v171
	v_and_b32_e32 v159, 0xffff0000, v171
	v_pk_add_f32 v[156:157], v[156:157], v[158:159]
	v_pk_fma_f32 v[156:157], v[12:13], 0.5, v[156:157] op_sel_hi:[1,0,1]
	v_cvt_pk_bf16_f32 v167, v156, v157
	v_pk_fma_f32 v[198:199], v[156:157], v[156:157], v[198:199]
	v_lshlrev_b32_e32 v158, 16, v167
	v_and_b32_e32 v159, 0xffff0000, v167
	v_pk_add_f32 v[196:197], v[156:157], v[158:159] neg_lo:[0,1] neg_hi:[0,1]
	v_cvt_pk_bf16_f32 v171, v196, v197
	global_store_dwordx4 v211, v[164:167], s[10:11]
	global_store_dwordx4 v211, v[168:171], s[6:7]
	s_waitcnt vmcnt(10)
	v_lshlrev_b32_e32 v156, 16, v172
	v_and_b32_e32 v157, 0xffff0000, v172
	v_lshlrev_b32_e32 v158, 16, v176
	v_and_b32_e32 v159, 0xffff0000, v176
	v_pk_add_f32 v[156:157], v[156:157], v[158:159]
	v_pk_fma_f32 v[156:157], v[6:7], 0.5, v[156:157] op_sel_hi:[1,0,1]
	v_cvt_pk_bf16_f32 v172, v156, v157
	v_pk_fma_f32 v[198:199], v[156:157], v[156:157], v[198:199]
	v_lshlrev_b32_e32 v158, 16, v172
	v_and_b32_e32 v159, 0xffff0000, v172
	v_pk_add_f32 v[196:197], v[156:157], v[158:159] neg_lo:[0,1] neg_hi:[0,1]
	v_cvt_pk_bf16_f32 v176, v196, v197
	v_lshlrev_b32_e32 v156, 16, v173
	v_and_b32_e32 v157, 0xffff0000, v173
	v_lshlrev_b32_e32 v158, 16, v177
	v_and_b32_e32 v159, 0xffff0000, v177
	v_pk_add_f32 v[156:157], v[156:157], v[158:159]
	v_pk_fma_f32 v[156:157], v[8:9], 0.5, v[156:157] op_sel_hi:[1,0,1]
	v_cvt_pk_bf16_f32 v173, v156, v157
	v_pk_fma_f32 v[198:199], v[156:157], v[156:157], v[198:199]
	v_lshlrev_b32_e32 v158, 16, v173
	v_and_b32_e32 v159, 0xffff0000, v173
	v_pk_add_f32 v[196:197], v[156:157], v[158:159] neg_lo:[0,1] neg_hi:[0,1]
	v_cvt_pk_bf16_f32 v177, v196, v197
	v_lshlrev_b32_e32 v156, 16, v174
	v_and_b32_e32 v157, 0xffff0000, v174
	v_lshlrev_b32_e32 v158, 16, v178
	v_and_b32_e32 v159, 0xffff0000, v178
	v_pk_add_f32 v[156:157], v[156:157], v[158:159]
	v_pk_fma_f32 v[156:157], v[2:3], 0.5, v[156:157] op_sel_hi:[1,0,1]
	v_cvt_pk_bf16_f32 v174, v156, v157
	v_pk_fma_f32 v[198:199], v[156:157], v[156:157], v[198:199]
	v_lshlrev_b32_e32 v158, 16, v174
	v_and_b32_e32 v159, 0xffff0000, v174
	v_pk_add_f32 v[196:197], v[156:157], v[158:159] neg_lo:[0,1] neg_hi:[0,1]
	v_cvt_pk_bf16_f32 v178, v196, v197
	v_lshlrev_b32_e32 v156, 16, v175
	v_and_b32_e32 v157, 0xffff0000, v175
	v_lshlrev_b32_e32 v158, 16, v179
	v_and_b32_e32 v159, 0xffff0000, v179
	v_pk_add_f32 v[156:157], v[156:157], v[158:159]
	v_pk_fma_f32 v[156:157], v[4:5], 0.5, v[156:157] op_sel_hi:[1,0,1]
	v_cvt_pk_bf16_f32 v175, v156, v157
	v_pk_fma_f32 v[198:199], v[156:157], v[156:157], v[198:199]
	v_lshlrev_b32_e32 v158, 16, v175
	v_and_b32_e32 v159, 0xffff0000, v175
	v_pk_add_f32 v[196:197], v[156:157], v[158:159] neg_lo:[0,1] neg_hi:[0,1]
	v_cvt_pk_bf16_f32 v179, v196, v197
	global_store_dwordx4 v211, v[172:175], s[10:11] offset:256
	global_store_dwordx4 v211, v[176:179], s[6:7] offset:256
	v_add_f32_e32 v209, v198, v199
	ds_bpermute_b32 v140, v214, v200
	ds_bpermute_b32 v141, v214, v201
	ds_bpermute_b32 v142, v214, v202
	ds_bpermute_b32 v143, v214, v203
	ds_bpermute_b32 v144, v214, v206
	ds_bpermute_b32 v145, v214, v207
	ds_bpermute_b32 v146, v214, v208
	ds_bpermute_b32 v147, v214, v209
	v_readlane_b32 s50, v250, 39
	v_readlane_b32 s51, v250, 40
	s_waitcnt lgkmcnt(0)
	v_add_f32_e32 v200, v200, v140
	v_add_f32_e32 v201, v201, v141
	v_add_f32_e32 v202, v202, v142
	v_add_f32_e32 v203, v203, v143
	v_add_f32_e32 v206, v206, v144
	v_add_f32_e32 v207, v207, v145
	v_add_f32_e32 v208, v208, v146
	v_add_f32_e32 v209, v209, v147
	ds_bpermute_b32 v140, v215, v200
	ds_bpermute_b32 v141, v215, v201
	ds_bpermute_b32 v142, v215, v202
	ds_bpermute_b32 v143, v215, v203
	ds_bpermute_b32 v144, v215, v206
	ds_bpermute_b32 v145, v215, v207
	ds_bpermute_b32 v146, v215, v208
	ds_bpermute_b32 v147, v215, v209
	s_waitcnt lgkmcnt(0)
	v_add_f32_e32 v200, v200, v140
	v_add_f32_e32 v201, v201, v141
	v_add_f32_e32 v202, v202, v142
	v_add_f32_e32 v203, v203, v143
	v_add_f32_e32 v206, v206, v144
	v_add_f32_e32 v207, v207, v145
	v_add_f32_e32 v208, v208, v146
	v_add_f32_e32 v209, v209, v147
	s_and_saveexec_b64 s[12:13], s[42:43]
	s_cbranch_execz .Lepir_f2d_skip
	global_store_dword v216, v200, s[50:51]
	global_store_dword v216, v201, s[50:51] offset:1024
	global_store_dword v216, v202, s[50:51] offset:2048
	global_store_dword v216, v203, s[50:51] offset:3072
	global_store_dword v217, v206, s[50:51]
	global_store_dword v217, v207, s[50:51] offset:1024
	global_store_dword v217, v208, s[50:51] offset:2048
	global_store_dword v217, v209, s[50:51] offset:3072
